# gMLP item: first activation tile loads issued before the row-statistics stage instead of after it
# baseline (speedup 1.0000x reference)
.LBB0_897:
	s_or_b64 exec, exec, s[12:13]
	v_bfe_u32 v32, v4, 2, 7
	v_lshl_add_u64 v[0:1], s[4:5], 0, v[32:33]
	v_mad_u64_u32 v[2:3], s[12:13], v0, s9, v[34:35]
	v_mov_b32_e32 v0, v3
	v_mad_u64_u32 v[0:1], s[12:13], v1, s9, v[0:1]
	v_mov_b32_e32 v3, v0
	v_lshlrev_b32_e32 v0, 3, v4
	v_and_b32_e32 v5, 24, v0
	v_lshlrev_b32_e32 v0, 1, v5
	v_mov_b32_e32 v1, v33
	v_lshl_add_u64 v[46:47], v[2:3], 0, v[0:1]
	s_waitcnt vmcnt(0)
	v_mov_b64_e32 v[8:9], v[242:243]
	v_mov_b64_e32 v[10:11], v[244:245]
	v_lshlrev_b32_e32 v157, 2, v5
	v_mov_b64_e32 v[12:13], v[246:247]
	v_mov_b64_e32 v[14:15], v[248:249]
	v_mov_b64_e32 v[16:17], v[250:251]
	v_mov_b64_e32 v[18:19], v[252:253]
	v_mov_b64_e32 v[0:1], v[238:239]
	v_mov_b64_e32 v[2:3], v[240:241]
	s_waitcnt lgkmcnt(0)
	s_barrier
	global_load_dwordx4 v[20:23], v157, s[48:49]
	global_load_dwordx4 v[24:27], v157, s[50:51]
	global_load_dwordx4 v[28:31], v157, s[48:49] offset:16
	global_load_dwordx4 v[36:39], v157, s[50:51] offset:16
	global_load_dwordx4 v[178:181], v157, s[48:49] offset:128
	global_load_dwordx4 v[182:185], v157, s[50:51] offset:128
	global_load_dwordx4 v[186:189], v157, s[48:49] offset:144
	global_load_dwordx4 v[190:193], v157, s[50:51] offset:144
	global_load_dwordx4 v[194:197], v157, s[48:49] offset:256
	global_load_dwordx4 v[198:201], v157, s[50:51] offset:256
	global_load_dwordx4 v[202:205], v157, s[48:49] offset:272
	global_load_dwordx4 v[206:209], v157, s[50:51] offset:272
	global_load_dwordx4 v[210:213], v157, s[48:49] offset:384
	global_load_dwordx4 v[214:217], v157, s[50:51] offset:384
	global_load_dwordx4 v[218:221], v157, s[48:49] offset:400
	global_load_dwordx4 v[238:241], v157, s[50:51] offset:400
	v_lshl_add_u32 v6, v32, 3, 0
	v_lshlrev_b32_e32 v7, 1, v32
	v_add_u32_e32 v160, 0x11000, v6
	v_mul_u32_u24_e32 v5, 0x110, v5
	v_add3_u32 v155, 0, v7, v5
	ds_read_b64 v[6:7], v160
	v_ashrrev_i32_e32 v44, 2, v4
	v_and_b32_e32 v50, 15, v4
	v_mov_b32_e32 v49, v33
	v_readlane_b32 s56, v254, 12
	v_readlane_b32 s58, v254, 14
	v_readlane_b32 s59, v254, 15
	v_readlane_b32 s57, v254, 13
	v_readlane_b32 s60, v254, 16
	v_readlane_b32 s61, v254, 17
	v_readlane_b32 s62, v254, 18
	v_readlane_b32 s63, v254, 19
	v_readlane_b32 s64, v254, 20
	v_readlane_b32 s65, v254, 21
	v_readlane_b32 s66, v254, 22
	v_readlane_b32 s67, v254, 23
	v_readlane_b32 s68, v254, 24
	v_readlane_b32 s69, v254, 25
	v_readlane_b32 s70, v254, 26
	v_readlane_b32 s71, v254, 27
	s_waitcnt vmcnt(7)
	v_lshlrev_b32_e32 v5, 16, v8
	s_waitcnt lgkmcnt(0)
	v_sub_f32_e32 v5, v5, v6
	v_and_b32_e32 v8, 0xffff0000, v8
	v_mul_f32_e32 v5, v7, v5
	v_lshlrev_b32_e32 v32, 16, v9
	v_sub_f32_e32 v8, v8, v6
	s_waitcnt vmcnt(2)
	v_fma_f32 v5, v20, v5, v24
	v_and_b32_e32 v9, 0xffff0000, v9
	v_sub_f32_e32 v32, v32, v6
	v_mul_f32_e32 v8, v7, v8
	v_cvt_pk_bf16_f32 v5, v5, v33
	v_lshlrev_b32_e32 v40, 16, v10
	v_sub_f32_e32 v9, v9, v6
	v_mul_f32_e32 v32, v7, v32
	v_fma_f32 v8, v21, v8, v25
	ds_write_b16 v155, v5
	v_cvt_pk_bf16_f32 v5, v8, v33
	v_and_b32_e32 v10, 0xffff0000, v10
	v_sub_f32_e32 v40, v40, v6
	v_mul_f32_e32 v9, v7, v9
	v_fma_f32 v20, v22, v32, v26
	ds_write_b16 v155, v5 offset:272
	v_cvt_pk_bf16_f32 v5, v20, v33
	v_lshlrev_b32_e32 v41, 16, v11
	v_sub_f32_e32 v10, v10, v6
	v_mul_f32_e32 v40, v7, v40
	v_fmac_f32_e32 v27, v23, v9
	ds_write_b16 v155, v5 offset:544
	v_cvt_pk_bf16_f32 v5, v27, v33
	v_and_b32_e32 v11, 0xffff0000, v11
	v_sub_f32_e32 v41, v41, v6
	v_mul_f32_e32 v10, v7, v10
	s_waitcnt vmcnt(0)
	v_fma_f32 v9, v40, v28, v36
	ds_write_b16 v155, v5 offset:816
	v_cvt_pk_bf16_f32 v5, v9, v33
	v_sub_f32_e32 v11, v11, v6
	v_mul_f32_e32 v41, v7, v41
	v_fma_f32 v10, v10, v29, v37
	ds_write_b16 v155, v5 offset:1088
	v_cvt_pk_bf16_f32 v5, v10, v33
	v_mul_f32_e32 v11, v7, v11
	v_fma_f32 v21, v41, v30, v38
	ds_write_b16 v155, v5 offset:1360
	v_cvt_pk_bf16_f32 v5, v21, v33
	v_fmac_f32_e32 v39, v11, v31
	ds_write_b16 v155, v5 offset:1632
	v_cvt_pk_bf16_f32 v5, v39, v33
	v_mov_b64_e32 v[8:9], v[178:179]
	v_mov_b64_e32 v[10:11], v[180:181]
	v_mov_b64_e32 v[20:21], v[182:183]
	v_mov_b64_e32 v[22:23], v[184:185]
	v_mov_b64_e32 v[24:25], v[186:187]
	v_mov_b64_e32 v[26:27], v[188:189]
	v_mov_b64_e32 v[28:29], v[190:191]
	v_mov_b64_e32 v[30:31], v[192:193]
	v_lshlrev_b32_e32 v32, 16, v12
	v_sub_f32_e32 v32, v32, v6
	v_and_b32_e32 v12, 0xffff0000, v12
	v_mul_f32_e32 v32, v7, v32
	v_lshlrev_b32_e32 v36, 16, v13
	v_sub_f32_e32 v12, v12, v6
	ds_write_b16 v155, v5 offset:1904
	v_and_b32_e32 v13, 0xffff0000, v13
	v_sub_f32_e32 v36, v36, v6
	v_mul_f32_e32 v12, v7, v12
	v_lshlrev_b32_e32 v37, 16, v14
	v_sub_f32_e32 v13, v13, v6
	v_mul_f32_e32 v36, v7, v36
	v_and_b32_e32 v14, 0xffff0000, v14
	v_sub_f32_e32 v37, v37, v6
	v_mul_f32_e32 v13, v7, v13
	v_lshlrev_b32_e32 v38, 16, v15
	v_sub_f32_e32 v14, v14, v6
	v_mul_f32_e32 v37, v7, v37
	v_and_b32_e32 v15, 0xffff0000, v15
	v_sub_f32_e32 v38, v38, v6
	v_mul_f32_e32 v14, v7, v14
	v_sub_f32_e32 v15, v15, v6
	v_mul_f32_e32 v38, v7, v38
	v_mul_f32_e32 v15, v7, v15
	s_waitcnt vmcnt(2)
	v_fma_f32 v5, v32, v8, v20
	v_cvt_pk_bf16_f32 v5, v5, v33
	v_fma_f32 v8, v12, v9, v21
	ds_write_b16 v155, v5 offset:8704
	v_cvt_pk_bf16_f32 v5, v8, v33
	v_fma_f32 v9, v36, v10, v22
	ds_write_b16 v155, v5 offset:8976
	v_cvt_pk_bf16_f32 v5, v9, v33
	v_fmac_f32_e32 v23, v13, v11
	ds_write_b16 v155, v5 offset:9248
	v_cvt_pk_bf16_f32 v5, v23, v33
	s_waitcnt vmcnt(0)
	v_fma_f32 v10, v37, v24, v28
	ds_write_b16 v155, v5 offset:9520
	v_cvt_pk_bf16_f32 v5, v10, v33
	v_fma_f32 v11, v14, v25, v29
	ds_write_b16 v155, v5 offset:9792
	v_cvt_pk_bf16_f32 v5, v11, v33
	v_fma_f32 v12, v38, v26, v30
	ds_write_b16 v155, v5 offset:10064
	v_cvt_pk_bf16_f32 v5, v12, v33
	v_fmac_f32_e32 v31, v15, v27
	ds_write_b16 v155, v5 offset:10336
	v_cvt_pk_bf16_f32 v5, v31, v33
	v_mov_b64_e32 v[8:9], v[194:195]
	v_mov_b64_e32 v[10:11], v[196:197]
	v_mov_b64_e32 v[12:13], v[198:199]
	v_mov_b64_e32 v[14:15], v[200:201]
	v_mov_b64_e32 v[20:21], v[202:203]
	v_mov_b64_e32 v[22:23], v[204:205]
	v_mov_b64_e32 v[24:25], v[206:207]
	v_mov_b64_e32 v[26:27], v[208:209]
	v_lshlrev_b32_e32 v28, 16, v16
	v_sub_f32_e32 v28, v28, v6
	v_and_b32_e32 v16, 0xffff0000, v16
	v_mul_f32_e32 v28, v7, v28
	v_lshlrev_b32_e32 v29, 16, v17
	v_sub_f32_e32 v16, v16, v6
	ds_write_b16 v155, v5 offset:10608
	v_and_b32_e32 v17, 0xffff0000, v17
	v_sub_f32_e32 v29, v29, v6
	v_mul_f32_e32 v16, v7, v16
	v_lshlrev_b32_e32 v30, 16, v18
	v_sub_f32_e32 v17, v17, v6
	v_mul_f32_e32 v29, v7, v29
	v_and_b32_e32 v18, 0xffff0000, v18
	v_sub_f32_e32 v30, v30, v6
	v_mul_f32_e32 v17, v7, v17
	v_lshlrev_b32_e32 v31, 16, v19
	v_sub_f32_e32 v18, v18, v6
	v_mul_f32_e32 v30, v7, v30
	v_and_b32_e32 v19, 0xffff0000, v19
	v_sub_f32_e32 v31, v31, v6
	v_mul_f32_e32 v18, v7, v18
	v_sub_f32_e32 v19, v19, v6
	v_mul_f32_e32 v31, v7, v31
	v_mul_f32_e32 v19, v7, v19
	s_waitcnt vmcnt(2)
	v_fma_f32 v5, v28, v8, v12
	v_cvt_pk_bf16_f32 v5, v5, v33
	v_fma_f32 v8, v16, v9, v13
	ds_write_b16 v155, v5 offset:17408
	v_cvt_pk_bf16_f32 v5, v8, v33
	v_fma_f32 v9, v29, v10, v14
	ds_write_b16 v155, v5 offset:17680
	v_cvt_pk_bf16_f32 v5, v9, v33
	v_fmac_f32_e32 v15, v17, v11
	ds_write_b16 v155, v5 offset:17952
	v_cvt_pk_bf16_f32 v5, v15, v33
	s_waitcnt vmcnt(0)
	v_fma_f32 v10, v30, v20, v24
	ds_write_b16 v155, v5 offset:18224
	v_cvt_pk_bf16_f32 v5, v10, v33
	v_fma_f32 v11, v18, v21, v25
	ds_write_b16 v155, v5 offset:18496
	v_cvt_pk_bf16_f32 v5, v11, v33
	v_fma_f32 v12, v31, v22, v26
	ds_write_b16 v155, v5 offset:18768
	v_cvt_pk_bf16_f32 v5, v12, v33
	v_fmac_f32_e32 v27, v19, v23
	ds_write_b16 v155, v5 offset:19040
	v_cvt_pk_bf16_f32 v5, v27, v33
	v_mov_b64_e32 v[8:9], v[210:211]
	v_mov_b64_e32 v[10:11], v[212:213]
	v_mov_b64_e32 v[12:13], v[214:215]
	v_mov_b64_e32 v[14:15], v[216:217]
	v_mov_b64_e32 v[16:17], v[218:219]
	v_mov_b64_e32 v[18:19], v[220:221]
	v_mov_b64_e32 v[20:21], v[238:239]
	v_mov_b64_e32 v[22:23], v[240:241]
	v_bfe_u32 v24, v4, 4, 2
	v_and_b32_e32 v26, -16, v44
	v_lshlrev_b32_e32 v32, 3, v24
	v_lshlrev_b32_e32 v48, 4, v24
	v_ashrrev_i32_e32 v25, 31, v26
	v_or_b32_e32 v24, v26, v50
	v_lshl_add_u64 v[26:27], s[0:1], 0, v[48:49]
	v_lshl_add_u64 v[36:37], s[4:5], 0, v[24:25]
	v_lshlrev_b64 v[24:25], 8, v[24:25]
	v_lshl_add_u64 v[42:43], v[26:27], 0, v[24:25]
	v_lshlrev_b32_e32 v24, 16, v0
	v_and_b32_e32 v0, 0xffff0000, v0
	v_lshlrev_b32_e32 v27, 16, v3
	v_and_b32_e32 v3, 0xffff0000, v3
	v_sub_f32_e32 v0, v0, v6
	v_lshlrev_b32_e32 v25, 16, v1
	v_and_b32_e32 v1, 0xffff0000, v1
	v_lshlrev_b32_e32 v26, 16, v2
	v_and_b32_e32 v2, 0xffff0000, v2
	v_sub_f32_e32 v24, v24, v6
	v_sub_f32_e32 v3, v3, v6
	v_mul_f32_e32 v0, v7, v0
	v_sub_f32_e32 v25, v25, v6
	v_sub_f32_e32 v1, v1, v6
	v_sub_f32_e32 v26, v26, v6
	v_sub_f32_e32 v2, v2, v6
	v_sub_f32_e32 v27, v27, v6
	v_mul_f32_e32 v6, v7, v24
	v_mul_f32_e32 v3, v7, v3
	v_mul_f32_e32 v24, v7, v25
	ds_write_b16 v155, v5 offset:19312
	v_mul_f32_e32 v1, v7, v1
	v_mul_f32_e32 v25, v7, v26
	v_mul_f32_e32 v2, v7, v2
	v_mul_f32_e32 v26, v7, v27
	v_mad_u64_u32 v[38:39], s[12:13], v36, s9, v[34:35]
	s_waitcnt vmcnt(2)
	v_fma_f32 v0, v0, v9, v13
	v_fma_f32 v5, v6, v8, v12
	s_waitcnt vmcnt(0)
	v_fmac_f32_e32 v23, v3, v19
	v_cvt_pk_bf16_f32 v3, v5, v33
	ds_write_b16 v155, v3 offset:26112
	v_cvt_pk_bf16_f32 v0, v0, v33
	v_fma_f32 v6, v24, v10, v14
	ds_write_b16 v155, v0 offset:26384
	v_cvt_pk_bf16_f32 v0, v6, v33
	v_fmac_f32_e32 v15, v1, v11
	ds_write_b16 v155, v0 offset:26656
	v_cvt_pk_bf16_f32 v0, v15, v33
	v_fma_f32 v1, v25, v16, v20
	ds_write_b16 v155, v0 offset:26928
	v_cvt_pk_bf16_f32 v0, v1, v33
	v_fma_f32 v2, v2, v17, v21
	ds_write_b16 v155, v0 offset:27200
	v_cvt_pk_bf16_f32 v0, v2, v33
	v_fma_f32 v7, v26, v18, v22
	ds_write_b16 v155, v0 offset:27472
	v_cvt_pk_bf16_f32 v0, v7, v33
	ds_write_b16 v155, v0 offset:27744
	v_cvt_pk_bf16_f32 v0, v23, v33
	ds_write_b16 v155, v0 offset:28016
	s_waitcnt lgkmcnt(0)
	s_barrier
	global_load_dwordx4 v[20:23], v[42:43], off
	global_load_dwordx4 v[24:27], v[42:43], off offset:64
	v_mov_b32_e32 v0, v39
	v_mad_u64_u32 v[0:1], s[12:13], v37, s9, v[0:1]
	v_mov_b32_e32 v39, v0
	v_lshl_add_u64 v[40:41], v[38:39], 0, v[32:33]
	global_load_dwordx2 v[224:225], v[40:41], off offset:1056
	global_load_dwordx2 v[226:227], v[40:41], off offset:1088
	global_load_dwordx2 v[228:229], v[40:41], off offset:1120
	global_load_dwordx2 v[230:231], v[40:41], off offset:1152
	global_load_dwordx2 v[232:233], v[40:41], off offset:1184
	global_load_dwordx2 v[234:235], v[40:41], off offset:1216
	global_load_dwordx2 v[236:237], v[40:41], off offset:1248
	global_load_dwordx2 v[52:53], v[40:41], off offset:1024
	global_load_dwordx4 v[28:31], v[42:43], off offset:128
	global_load_dwordx4 v[16:19], v[42:43], off offset:192
	v_bfi_b32 v0, -16, v44, v4
	v_ashrrev_i32_e32 v1, 31, v0
	v_lshl_add_u64 v[44:45], v[0:1], 2, s[58:59]
	global_load_dword v54, v[44:45], off
	v_mul_u32_u24_e32 v0, 0x110, v50
	v_add3_u32 v152, 0, v48, v0
	ds_read_b128 v[0:3], v152
	ds_read_b128 v[4:7], v152 offset:64
	ds_read_b128 v[48:51], v152 offset:128
	s_waitcnt vmcnt(5) lgkmcnt(2)
	v_mfma_f32_16x16x32_bf16 v[0:3], v[0:3], v[20:23], 0
	global_load_dwordx4 v[12:15], v[46:47], off offset:2304
	global_load_dwordx4 v[8:11], v[46:47], off offset:2368
	ds_read_b128 v[56:59], v152 offset:192
	s_waitcnt vmcnt(5)
	v_lshlrev_b32_e32 v64, 16, v52
	s_waitcnt lgkmcnt(2)
	v_mfma_f32_16x16x32_bf16 v[60:63], v[4:7], v[24:27], v[0:3]
	v_and_b32_e32 v65, 0xffff0000, v52
	v_lshlrev_b32_e32 v52, 16, v53
	v_and_b32_e32 v53, 0xffff0000, v53
	s_waitcnt vmcnt(4) lgkmcnt(1)
	v_mfma_f32_16x16x32_bf16 v[48:51], v[48:51], v[28:31], v[60:63]
	global_load_dwordx4 v[4:7], v[46:47], off offset:2432
	global_load_dwordx4 v[0:3], v[46:47], off offset:2496
	s_waitcnt vmcnt(0)
	v_lshlrev_b32_e32 v101, 16, v2
	s_waitcnt lgkmcnt(0)
	v_mfma_f32_16x16x32_bf16 v[48:51], v[56:59], v[16:19], v[48:51]
	v_and_b32_e32 v102, 0xffff0000, v2
	v_and_b32_e32 v100, 0xffff0000, v1
	v_lshlrev_b32_e32 v103, 16, v3
	v_and_b32_e32 v104, 0xffff0000, v3
	s_nop 3
	v_pk_add_f32 v[48:49], v[54:55], v[48:49] op_sel_hi:[0,1]
	v_pk_add_f32 v[50:51], v[54:55], v[50:51] op_sel_hi:[0,1]
	v_pk_mul_f32 v[48:49], v[48:49], v[64:65]
	v_pk_mul_f32 v[50:51], v[50:51], v[52:53]
	v_cvt_pk_bf16_f32 v150, v48, v49
	v_mul_f32_e32 v2, v49, v49
	v_cvt_pk_bf16_f32 v148, v50, v51
	ds_read_b128 v[56:59], v152 offset:4352
	ds_read_b128 v[60:63], v152 offset:4416
	s_waitcnt lgkmcnt(1)
	v_mfma_f32_16x16x32_bf16 v[56:59], v[56:59], v[20:23], 0
	v_pk_fma_f32 v[2:3], v[48:49], v[48:49], v[2:3] op_sel_hi:[1,1,0]
	s_nop 0
	v_mov_b32_e32 v84, v2
	s_waitcnt lgkmcnt(0)
	v_mfma_f32_16x16x32_bf16 v[56:59], v[60:63], v[24:27], v[56:59]
	ds_read_b128 v[60:63], v152 offset:4480
	ds_read_b128 v[64:67], v152 offset:4544
	v_mov_b64_e32 v[52:53], v[224:225]
	s_waitcnt lgkmcnt(1)
	v_mfma_f32_16x16x32_bf16 v[56:59], v[60:63], v[28:31], v[56:59]
	s_waitcnt vmcnt(0)
	v_lshlrev_b32_e32 v60, 16, v52
	s_waitcnt lgkmcnt(0)
	v_mfma_f32_16x16x32_bf16 v[56:59], v[64:67], v[16:19], v[56:59]
	v_and_b32_e32 v61, 0xffff0000, v52
	v_lshlrev_b32_e32 v62, 16, v53
	v_and_b32_e32 v63, 0xffff0000, v53
	s_nop 4
	v_pk_add_f32 v[56:57], v[54:55], v[56:57] op_sel_hi:[0,1]
	v_pk_add_f32 v[58:59], v[54:55], v[58:59] op_sel_hi:[0,1]
	v_pk_mul_f32 v[52:53], v[56:57], v[60:61]
	v_pk_mul_f32 v[60:61], v[58:59], v[62:63]
	v_cvt_pk_bf16_f32 v145, v52, v53
	s_nop 0
	v_cvt_pk_bf16_f32 v142, v60, v61
	ds_read_b128 v[56:59], v152 offset:8704
	ds_read_b128 v[62:65], v152 offset:8768
	s_waitcnt lgkmcnt(1)
	v_mfma_f32_16x16x32_bf16 v[56:59], v[56:59], v[20:23], 0
	s_waitcnt lgkmcnt(0)
	v_mfma_f32_16x16x32_bf16 v[56:59], v[62:65], v[24:27], v[56:59]
	ds_read_b128 v[62:65], v152 offset:8832
	ds_read_b128 v[66:69], v152 offset:8896
	s_waitcnt lgkmcnt(1)
	v_mfma_f32_16x16x32_bf16 v[56:59], v[62:65], v[28:31], v[56:59]
	v_mov_b64_e32 v[62:63], v[226:227]
	s_waitcnt vmcnt(0)
	v_lshlrev_b32_e32 v65, 16, v63
	s_waitcnt lgkmcnt(0)
	v_mfma_f32_16x16x32_bf16 v[56:59], v[66:69], v[16:19], v[56:59]
	v_and_b32_e32 v63, 0xffff0000, v63
	s_nop 6
	v_add_f32_e32 v55, v54, v56
	v_add_f32_e32 v56, v54, v57
	v_add_f32_e32 v57, v54, v58
	v_add_f32_e32 v58, v54, v59
	v_lshlrev_b32_e32 v59, 16, v62
	v_and_b32_e32 v62, 0xffff0000, v62
	v_mul_f32_e32 v64, v55, v59
	v_mul_f32_e32 v68, v56, v62
	v_mul_f32_e32 v66, v57, v65
	v_mul_f32_e32 v62, v58, v63
	v_cvt_pk_bf16_f32 v139, v64, v68
	v_cvt_pk_bf16_f32 v137, v66, v62
	ds_read_b128 v[56:59], v152 offset:13056
	ds_read_b128 v[70:73], v152 offset:13120
	s_waitcnt lgkmcnt(1)
	v_mfma_f32_16x16x32_bf16 v[56:59], v[56:59], v[20:23], 0
	s_waitcnt lgkmcnt(0)
	v_mfma_f32_16x16x32_bf16 v[56:59], v[70:73], v[24:27], v[56:59]
	ds_read_b128 v[70:73], v152 offset:13184
	ds_read_b128 v[74:77], v152 offset:13248
	v_mov_b64_e32 v[78:79], v[228:229]
	s_waitcnt lgkmcnt(1)
	v_mfma_f32_16x16x32_bf16 v[56:59], v[70:73], v[28:31], v[56:59]
	v_mov_b32_e32 v70, v64
	v_mov_b32_e32 v72, v66
	s_waitcnt vmcnt(0)
	v_lshlrev_b32_e32 v71, 16, v79
	s_waitcnt lgkmcnt(0)
	v_mfma_f32_16x16x32_bf16 v[56:59], v[74:77], v[16:19], v[56:59]
	v_and_b32_e32 v73, 0xffff0000, v79
	s_nop 6
	v_add_f32_e32 v55, v54, v56
	v_add_f32_e32 v56, v54, v57
	v_add_f32_e32 v65, v54, v58
	v_add_f32_e32 v67, v54, v59
	v_lshlrev_b32_e32 v57, 16, v78
	v_and_b32_e32 v58, 0xffff0000, v78
	v_mul_f32_e32 v85, v55, v57
	v_mul_f32_e32 v75, v56, v58
	v_pk_mul_f32 v[86:87], v[64:65], v[70:71]
	v_pk_mul_f32 v[88:89], v[66:67], v[72:73]
	v_cvt_pk_bf16_f32 v136, v85, v75
	v_lshlrev_b32_e32 v72, 16, v15
	v_cvt_pk_bf16_f32 v133, v87, v89
	ds_read_b128 v[56:59], v152 offset:17408
	ds_read_b128 v[76:79], v152 offset:17472
	s_waitcnt lgkmcnt(1)
	v_mfma_f32_16x16x32_bf16 v[56:59], v[56:59], v[20:23], 0
	v_and_b32_e32 v15, 0xffff0000, v15
	v_pk_mul_f32 v[48:49], v[88:89], v[88:89]
	s_waitcnt lgkmcnt(0)
	v_mfma_f32_16x16x32_bf16 v[56:59], v[76:79], v[24:27], v[56:59]
	ds_read_b128 v[76:79], v152 offset:17536
	ds_read_b128 v[80:83], v152 offset:17600
	s_waitcnt lgkmcnt(1)
	v_mfma_f32_16x16x32_bf16 v[56:59], v[76:79], v[28:31], v[56:59]
	v_mov_b64_e32 v[76:77], v[230:231]
	s_waitcnt lgkmcnt(0)
	v_mfma_f32_16x16x32_bf16 v[56:59], v[80:83], v[16:19], v[56:59]
	s_nop 7
	v_mov_b32_e32 v78, v56
	v_mov_b32_e32 v79, v58
	v_mov_b32_e32 v58, v57
	v_pk_add_f32 v[56:57], v[54:55], v[78:79] op_sel_hi:[0,1]
	v_pk_add_f32 v[58:59], v[54:55], v[58:59] op_sel_hi:[0,1]
	s_waitcnt vmcnt(0)
	v_lshlrev_b32_e32 v79, 16, v77
	v_lshlrev_b32_e32 v78, 16, v76
	v_and_b32_e32 v77, 0xffff0000, v77
	v_and_b32_e32 v76, 0xffff0000, v76
	v_pk_mul_f32 v[90:91], v[56:57], v[78:79]
	v_pk_mul_f32 v[92:93], v[58:59], v[76:77]
	s_nop 0
	v_cvt_pk_bf16_f32 v134, v90, v92
	v_cvt_pk_bf16_f32 v132, v91, v93
	ds_read_b128 v[56:59], v152 offset:21760
	ds_read_b128 v[76:79], v152 offset:21824
	s_waitcnt lgkmcnt(1)
	v_mfma_f32_16x16x32_bf16 v[56:59], v[56:59], v[20:23], 0
	s_waitcnt lgkmcnt(0)
	v_mfma_f32_16x16x32_bf16 v[56:59], v[76:79], v[24:27], v[56:59]
	ds_read_b128 v[76:79], v152 offset:21888
	ds_read_b128 v[80:83], v152 offset:21952
	s_waitcnt lgkmcnt(1)
	v_mfma_f32_16x16x32_bf16 v[56:59], v[76:79], v[28:31], v[56:59]
	v_mov_b64_e32 v[76:77], v[232:233]
	s_waitcnt lgkmcnt(0)
	v_mfma_f32_16x16x32_bf16 v[56:59], v[80:83], v[16:19], v[56:59]
	s_nop 7
	v_pk_add_f32 v[56:57], v[54:55], v[56:57] op_sel_hi:[0,1]
	v_pk_add_f32 v[78:79], v[54:55], v[58:59] op_sel_hi:[0,1]
	s_waitcnt vmcnt(0)
	v_lshlrev_b32_e32 v58, 16, v76
	v_and_b32_e32 v59, 0xffff0000, v76
	v_lshlrev_b32_e32 v76, 16, v77
	v_and_b32_e32 v77, 0xffff0000, v77
	v_pk_mul_f32 v[58:59], v[56:57], v[58:59]
	v_pk_mul_f32 v[94:95], v[78:79], v[76:77]
	v_cvt_pk_bf16_f32 v130, v58, v59
	s_nop 0
	v_cvt_pk_bf16_f32 v129, v94, v95
	ds_read_b128 v[76:79], v152 offset:26112
	ds_read_b128 v[80:83], v152 offset:26176
	s_waitcnt lgkmcnt(1)
	v_mfma_f32_16x16x32_bf16 v[76:79], v[76:79], v[20:23], 0
	s_waitcnt lgkmcnt(0)
	v_mfma_f32_16x16x32_bf16 v[76:79], v[80:83], v[24:27], v[76:79]
	ds_read_b128 v[80:83], v152 offset:26240
	ds_read_b128 v[96:99], v152 offset:26304
	v_mov_b64_e32 v[56:57], v[234:235]
	s_waitcnt vmcnt(0)
	v_lshlrev_b32_e32 v66, 16, v56
	s_waitcnt lgkmcnt(1)
	v_mfma_f32_16x16x32_bf16 v[76:79], v[80:83], v[28:31], v[76:79]
	v_and_b32_e32 v56, 0xffff0000, v56
	v_lshlrev_b32_e32 v70, 16, v57
	v_and_b32_e32 v57, 0xffff0000, v57
	s_waitcnt lgkmcnt(0)
	v_mfma_f32_16x16x32_bf16 v[76:79], v[96:99], v[16:19], v[76:79]
	s_nop 7
	v_add_f32_e32 v55, v54, v76
	v_add_f32_e32 v63, v54, v77
	v_add_f32_e32 v64, v54, v78
	v_add_f32_e32 v69, v54, v79
	v_mul_f32_e32 v96, v55, v66
	v_mul_f32_e32 v66, v63, v56
	v_mul_f32_e32 v98, v64, v70
	v_mul_f32_e32 v64, v69, v57
	v_cvt_pk_bf16_f32 v128, v96, v66
	v_cvt_pk_bf16_f32 v127, v98, v64
	ds_read_b128 v[76:79], v152 offset:30464
	ds_read_b128 v[80:83], v152 offset:30528
	s_waitcnt lgkmcnt(1)
	v_mfma_f32_16x16x32_bf16 v[20:23], v[76:79], v[20:23], 0
	v_mov_b32_e32 v76, v96
	v_mov_b32_e32 v78, v98
	v_and_b32_e32 v56, 0xffff0000, v12
	s_waitcnt lgkmcnt(0)
	v_mfma_f32_16x16x32_bf16 v[20:23], v[80:83], v[24:27], v[20:23]
	ds_read_b128 v[24:27], v152 offset:30592
	ds_read_b128 v[80:83], v152 offset:30656
	v_lshlrev_b32_e32 v63, 16, v13
	v_and_b32_e32 v69, 0xffff0000, v13
	s_waitcnt lgkmcnt(1)
	v_mfma_f32_16x16x32_bf16 v[20:23], v[24:27], v[28:31], v[20:23]
	v_mov_b64_e32 v[24:25], v[236:237]
	v_lshlrev_b32_e32 v70, 16, v14
	v_and_b32_e32 v14, 0xffff0000, v14
	s_waitcnt lgkmcnt(0)
	v_mfma_f32_16x16x32_bf16 v[16:19], v[80:83], v[16:19], v[20:23]
	s_waitcnt vmcnt(0)
	v_lshlrev_b32_e32 v77, 16, v25
	s_nop 5
	v_add_f32_e32 v16, v54, v16
	v_add_f32_e32 v17, v54, v17
	v_add_f32_e32 v97, v54, v18
	v_add_f32_e32 v99, v54, v19
	v_lshlrev_b32_e32 v18, 16, v24
	v_and_b32_e32 v19, 0xffff0000, v24
	v_and_b32_e32 v79, 0xffff0000, v25
	v_mul_f32_e32 v57, v16, v18
	v_mul_f32_e32 v55, v17, v19
	v_pk_mul_f32 v[80:81], v[96:97], v[76:77]
	v_pk_mul_f32 v[82:83], v[98:99], v[78:79]
	v_cvt_pk_bf16_f32 v126, v57, v55
	v_lshlrev_b32_e32 v54, 16, v12
	v_cvt_pk_bf16_f32 v125, v81, v83
	global_load_dwordx4 v[16:19], v157, s[48:49] offset:512
	global_load_dwordx4 v[20:23], v157, s[50:51] offset:512
	global_load_dwordx4 v[24:27], v157, s[48:49] offset:528
	global_load_dwordx4 v[28:31], v157, s[50:51] offset:528
	global_load_dwordx4 v[178:181], v157, s[48:49] offset:640
	global_load_dwordx4 v[182:185], v157, s[50:51] offset:640
	global_load_dwordx4 v[186:189], v157, s[48:49] offset:656
	global_load_dwordx4 v[190:193], v157, s[50:51] offset:656
	global_load_dwordx4 v[194:197], v157, s[48:49] offset:768
	global_load_dwordx4 v[198:201], v157, s[50:51] offset:768
	global_load_dwordx4 v[202:205], v157, s[48:49] offset:784
	global_load_dwordx4 v[206:209], v157, s[50:51] offset:784
	global_load_dwordx4 v[210:213], v157, s[48:49] offset:896
	global_load_dwordx4 v[214:217], v157, s[50:51] offset:896
	global_load_dwordx4 v[218:221], v157, s[48:49] offset:912
	global_load_dwordx4 v[238:241], v157, s[50:51] offset:912
	ds_read_b64 v[12:13], v160
	v_and_b32_e32 v96, 0xffff0000, v0
	v_lshlrev_b32_e32 v98, 16, v1
	v_mov_b32_e32 v76, v66
	v_mov_b32_e32 v78, v64
	s_waitcnt lgkmcnt(0)
	v_sub_f32_e32 v54, v54, v12
	v_sub_f32_e32 v15, v15, v12
	v_sub_f32_e32 v56, v56, v12
	v_mul_f32_e32 v54, v13, v54
	v_mul_f32_e32 v15, v13, v15
	v_sub_f32_e32 v63, v63, v12
	v_mul_f32_e32 v56, v13, v56
	v_sub_f32_e32 v69, v69, v12
	v_sub_f32_e32 v14, v14, v12
	v_mul_f32_e32 v63, v13, v63
	v_sub_f32_e32 v70, v70, v12
	v_mul_f32_e32 v69, v13, v69
	v_mul_f32_e32 v14, v13, v14
	v_sub_f32_e32 v72, v72, v12
	v_mul_f32_e32 v70, v13, v70
	v_mul_f32_e32 v72, v13, v72
	s_waitcnt vmcnt(2)
	v_fma_f32 v16, v16, v54, v20
	v_fma_f32 v17, v17, v56, v21
	s_waitcnt vmcnt(0)
	v_fmac_f32_e32 v31, v27, v15
	v_cvt_pk_bf16_f32 v15, v16, v33
	ds_write_b16 v155, v15 offset:34816
	v_cvt_pk_bf16_f32 v15, v17, v33
	v_fma_f32 v18, v18, v63, v22
	ds_write_b16 v155, v15 offset:35088
	v_cvt_pk_bf16_f32 v15, v18, v33
	v_fmac_f32_e32 v23, v19, v69
	v_fma_f32 v14, v25, v14, v29
	ds_write_b16 v155, v15 offset:35360
	v_cvt_pk_bf16_f32 v15, v23, v33
	v_fma_f32 v19, v24, v70, v28
	ds_write_b16 v155, v15 offset:35632
	v_cvt_pk_bf16_f32 v15, v19, v33
	ds_write_b16 v155, v15 offset:35904
	v_cvt_pk_bf16_f32 v14, v14, v33
	v_fma_f32 v20, v26, v72, v30
	ds_write_b16 v155, v14 offset:36176
	v_cvt_pk_bf16_f32 v14, v20, v33
	ds_write_b16 v155, v14 offset:36448
	v_cvt_pk_bf16_f32 v30, v31, v33
	v_mov_b64_e32 v[14:15], v[178:179]
	v_mov_b64_e32 v[16:17], v[180:181]
	v_mov_b64_e32 v[18:19], v[182:183]
	v_mov_b64_e32 v[20:21], v[184:185]
	v_mov_b64_e32 v[22:23], v[186:187]
	v_mov_b64_e32 v[24:25], v[188:189]
	v_mov_b64_e32 v[26:27], v[190:191]
	v_mov_b64_e32 v[28:29], v[192:193]
	v_lshlrev_b32_e32 v31, 16, v8
	v_and_b32_e32 v8, 0xffff0000, v8
	v_lshlrev_b32_e32 v63, 16, v11
	v_and_b32_e32 v11, 0xffff0000, v11
	v_sub_f32_e32 v8, v8, v12
	v_lshlrev_b32_e32 v54, 16, v9
	v_sub_f32_e32 v31, v31, v12
	v_sub_f32_e32 v11, v11, v12
	v_mul_f32_e32 v8, v13, v8
	v_and_b32_e32 v9, 0xffff0000, v9
	v_sub_f32_e32 v54, v54, v12
	v_mul_f32_e32 v31, v13, v31
	v_mul_f32_e32 v11, v13, v11
	v_lshlrev_b32_e32 v56, 16, v10
	v_sub_f32_e32 v9, v9, v12
	v_mul_f32_e32 v54, v13, v54
	ds_write_b16 v155, v30 offset:36720
	v_and_b32_e32 v10, 0xffff0000, v10
	v_sub_f32_e32 v56, v56, v12
	v_mul_f32_e32 v9, v13, v9
	v_sub_f32_e32 v10, v10, v12
	v_mul_f32_e32 v56, v13, v56
	v_sub_f32_e32 v63, v63, v12
	v_mul_f32_e32 v10, v13, v10
	v_mul_f32_e32 v63, v13, v63
	v_lshlrev_b32_e32 v30, 16, v7
	v_and_b32_e32 v7, 0xffff0000, v7
	v_sub_f32_e32 v7, v7, v12
	v_mul_f32_e32 v7, v13, v7
	v_sub_f32_e32 v30, v30, v12
	v_mul_f32_e32 v30, v13, v30
	v_mov_b32_e32 v69, v65
	v_mov_b32_e32 v70, v68
	v_mov_b32_e32 v72, v62
	v_mov_b32_e32 v65, v99
	s_waitcnt vmcnt(2)
	v_fma_f32 v8, v8, v15, v19
	v_fma_f32 v14, v31, v14, v18
	s_waitcnt vmcnt(0)
	v_fmac_f32_e32 v29, v11, v25
	v_cvt_pk_bf16_f32 v11, v14, v33
	ds_write_b16 v155, v11 offset:43520
	v_cvt_pk_bf16_f32 v8, v8, v33
	v_fma_f32 v15, v54, v16, v20
	ds_write_b16 v155, v8 offset:43792
	v_cvt_pk_bf16_f32 v8, v15, v33
	v_fmac_f32_e32 v21, v9, v17
	ds_write_b16 v155, v8 offset:44064
	v_cvt_pk_bf16_f32 v8, v21, v33
	v_fma_f32 v9, v56, v22, v26
	ds_write_b16 v155, v8 offset:44336
	v_cvt_pk_bf16_f32 v8, v9, v33
	v_fma_f32 v10, v10, v23, v27
	ds_write_b16 v155, v8 offset:44608
	v_cvt_pk_bf16_f32 v8, v10, v33
	v_fma_f32 v16, v63, v24, v28
	ds_write_b16 v155, v8 offset:44880
	v_cvt_pk_bf16_f32 v8, v16, v33
	ds_write_b16 v155, v8 offset:45152
	v_cvt_pk_bf16_f32 v26, v29, v33
	v_mov_b64_e32 v[8:9], v[194:195]
	v_mov_b64_e32 v[10:11], v[196:197]
	v_mov_b64_e32 v[14:15], v[198:199]
	v_mov_b64_e32 v[16:17], v[200:201]
	v_mov_b64_e32 v[18:19], v[202:203]
	v_mov_b64_e32 v[20:21], v[204:205]
	v_mov_b64_e32 v[22:23], v[206:207]
	v_mov_b64_e32 v[24:25], v[208:209]
	v_lshlrev_b32_e32 v27, 16, v4
	v_and_b32_e32 v4, 0xffff0000, v4
	v_sub_f32_e32 v4, v4, v12
	v_lshlrev_b32_e32 v28, 16, v5
	v_sub_f32_e32 v27, v27, v12
	v_mul_f32_e32 v4, v13, v4
	v_and_b32_e32 v5, 0xffff0000, v5
	v_sub_f32_e32 v28, v28, v12
	v_mul_f32_e32 v27, v13, v27
	v_lshlrev_b32_e32 v29, 16, v6
	v_sub_f32_e32 v5, v5, v12
	v_mul_f32_e32 v28, v13, v28
	ds_write_b16 v155, v26 offset:45424
	v_and_b32_e32 v6, 0xffff0000, v6
	v_sub_f32_e32 v29, v29, v12
	v_mul_f32_e32 v5, v13, v5
	v_sub_f32_e32 v6, v6, v12
	v_mul_f32_e32 v29, v13, v29
	v_mul_f32_e32 v6, v13, v6
	v_lshlrev_b32_e32 v56, 16, v0
	v_mul_f32_e32 v0, v51, v51
	v_pk_fma_f32 v[0:1], v[50:51], v[50:51], v[0:1] op_sel_hi:[1,1,0]
	v_mov_b32_e32 v63, v67
	v_mov_b32_e32 v67, v97
	s_waitcnt vmcnt(2)
	v_fma_f32 v4, v4, v9, v15
	v_fma_f32 v8, v27, v8, v14
	s_waitcnt vmcnt(0)
	v_fmac_f32_e32 v25, v7, v21
	v_cvt_pk_bf16_f32 v7, v8, v33
	ds_write_b16 v155, v7 offset:52224
	v_cvt_pk_bf16_f32 v4, v4, v33
	v_fma_f32 v9, v28, v10, v16
	ds_write_b16 v155, v4 offset:52496
	v_cvt_pk_bf16_f32 v4, v9, v33
	v_fmac_f32_e32 v17, v5, v11
	ds_write_b16 v155, v4 offset:52768
	v_cvt_pk_bf16_f32 v4, v17, v33
	v_fma_f32 v5, v29, v18, v22
	ds_write_b16 v155, v4 offset:53040
	v_cvt_pk_bf16_f32 v4, v5, v33
	v_fma_f32 v6, v6, v19, v23
	ds_write_b16 v155, v4 offset:53312
	v_cvt_pk_bf16_f32 v4, v6, v33
	v_fma_f32 v10, v30, v20, v24
	ds_write_b16 v155, v4 offset:53584
	v_cvt_pk_bf16_f32 v4, v10, v33
	ds_write_b16 v155, v4 offset:53856
	v_cvt_pk_bf16_f32 v54, v25, v33
	v_mov_b64_e32 v[4:5], v[210:211]
	v_mov_b64_e32 v[6:7], v[212:213]
	v_mov_b64_e32 v[8:9], v[214:215]
	v_mov_b64_e32 v[10:11], v[216:217]
	v_mov_b64_e32 v[14:15], v[218:219]
	v_mov_b64_e32 v[16:17], v[220:221]
	v_mov_b64_e32 v[18:19], v[238:239]
	v_mov_b64_e32 v[20:21], v[240:241]
	v_mov_b32_e32 v22, v0
	v_pk_add_f32 v[0:1], v[2:3], v[0:1]
	v_mul_f32_e32 v2, v61, v61
	v_mul_f32_e32 v24, v53, v53
	v_pk_fma_f32 v[2:3], v[60:61], v[60:61], v[2:3] op_sel_hi:[1,1,0]
	v_pk_fma_f32 v[24:25], v[52:53], v[52:53], v[24:25] op_sel_hi:[1,1,0]
	v_mov_b32_e32 v26, v2
	v_mov_b32_e32 v74, v24
	v_mov_b32_e32 v23, v85
	v_mov_b32_e32 v27, v75
	v_pk_add_f32 v[2:3], v[24:25], v[2:3]
	v_pk_fma_f32 v[24:25], v[68:69], v[70:71], v[86:87]
	v_pk_mul_f32 v[28:29], v[86:87], v[86:87]
	v_pk_fma_f32 v[30:31], v[62:63], v[72:73], v[88:89]
	v_pk_mul_f32 v[22:23], v[84:85], v[22:23]
	v_pk_mul_f32 v[26:27], v[74:75], v[26:27]
	v_mov_b32_e32 v25, v29
	v_mov_b32_e32 v31, v49
	v_mov_b32_e32 v1, v23
	v_mov_b32_e32 v3, v27
	v_pk_add_f32 v[22:23], v[24:25], v[30:31]
	v_pk_add_f32 v[0:1], v[0:1], v[2:3]
	v_sub_f32_e32 v2, v98, v12
	v_pk_add_f32 v[88:89], v[0:1], v[22:23]
	v_pk_mul_f32 v[0:1], v[92:93], v[92:93]
	ds_write_b16 v155, v54 offset:54128
	v_pk_fma_f32 v[0:1], v[90:91], v[90:91], v[0:1]
	v_sub_f32_e32 v3, v100, v12
	v_pk_add_f32 v[86:87], v[0:1], v[0:1] op_sel:[0,1] op_sel_hi:[1,0]
	v_mul_f32_e32 v0, v95, v95
	v_pk_fma_f32 v[84:85], v[94:95], v[94:95], v[0:1] op_sel_hi:[1,1,0]
	v_sub_f32_e32 v0, v56, v12
	v_mul_f32_e32 v0, v13, v0
	v_sub_f32_e32 v1, v96, v12
	v_mul_f32_e32 v1, v13, v1
	v_mul_f32_e32 v2, v13, v2
	v_sub_f32_e32 v22, v101, v12
	v_mul_f32_e32 v3, v13, v3
	v_sub_f32_e32 v23, v102, v12
	v_mul_f32_e32 v22, v13, v22
	v_sub_f32_e32 v24, v103, v12
	v_mul_f32_e32 v23, v13, v23
	v_sub_f32_e32 v12, v104, v12
	v_mul_f32_e32 v24, v13, v24
	v_mul_f32_e32 v12, v13, v12
	s_waitcnt vmcnt(2)
	v_fma_f32 v0, v0, v4, v8
	v_cvt_pk_bf16_f32 v0, v0, v33
	v_fma_f32 v1, v1, v5, v9
	ds_write_b16 v155, v0 offset:60928
	v_cvt_pk_bf16_f32 v0, v1, v33
	v_fma_f32 v2, v2, v6, v10
	ds_write_b16 v155, v0 offset:61200
	v_cvt_pk_bf16_f32 v0, v2, v33
	v_fmac_f32_e32 v11, v3, v7
	ds_write_b16 v155, v0 offset:61472
	v_cvt_pk_bf16_f32 v0, v11, v33
	s_waitcnt vmcnt(0)
	v_fma_f32 v3, v22, v14, v18
	ds_write_b16 v155, v0 offset:61744
	v_cvt_pk_bf16_f32 v0, v3, v33
	v_fma_f32 v4, v23, v15, v19
	ds_write_b16 v155, v0 offset:62016
	v_cvt_pk_bf16_f32 v0, v4, v33
	v_fma_f32 v5, v24, v16, v20
	ds_write_b16 v155, v0 offset:62288
	v_cvt_pk_bf16_f32 v0, v5, v33
	v_fmac_f32_e32 v21, v12, v17
	ds_write_b16 v155, v0 offset:62560
	v_cvt_pk_bf16_f32 v0, v21, v33
	ds_write_b16 v155, v0 offset:62832
	s_waitcnt lgkmcnt(0)
	s_barrier
	v_add_co_u32_e32 v0, vcc, s26, v42
	v_pk_fma_f32 v[66:67], v[66:67], v[76:77], v[80:81]
	s_nop 0
	v_addc_co_u32_e32 v1, vcc, 0, v43, vcc
	global_load_dwordx2 v[224:225], v[40:41], off offset:1312
	global_load_dwordx2 v[226:227], v[40:41], off offset:1344
	global_load_dwordx2 v[228:229], v[40:41], off offset:1376
	global_load_dwordx2 v[230:231], v[40:41], off offset:1408
	global_load_dwordx2 v[232:233], v[40:41], off offset:1440
	global_load_dwordx2 v[234:235], v[40:41], off offset:1472
	global_load_dwordx2 v[236:237], v[40:41], off offset:1504
	global_load_dwordx4 v[20:23], v[0:1], off
	global_load_dwordx4 v[24:27], v[0:1], off offset:64
	global_load_dwordx2 v[72:73], v[40:41], off offset:1280
	global_load_dwordx4 v[28:31], v[0:1], off offset:128
	global_load_dwordx4 v[16:19], v[0:1], off offset:192
	global_load_dword v48, v[44:45], off offset:512
	ds_read_b128 v[0:3], v152 offset:34816
	ds_read_b128 v[4:7], v152 offset:34880
	ds_read_b128 v[50:53], v152 offset:34944
	global_load_dwordx4 v[12:15], v[46:47], off offset:2560
	global_load_dwordx4 v[8:11], v[46:47], off offset:2624
	ds_read_b128 v[60:63], v152 offset:35008
	v_pk_mul_f32 v[76:77], v[80:81], v[80:81]
	v_pk_fma_f32 v[64:65], v[64:65], v[78:79], v[82:83]
	v_pk_mul_f32 v[78:79], v[82:83], v[82:83]
	v_mov_b32_e32 v67, v77
	v_mov_b32_e32 v65, v79
	s_waitcnt vmcnt(7) lgkmcnt(3)
	v_mfma_f32_16x16x32_bf16 v[0:3], v[0:3], v[20:23], 0
	s_waitcnt vmcnt(5)
	v_lshlrev_b32_e32 v75, 16, v73
	v_lshlrev_b32_e32 v74, 16, v72
	s_waitcnt lgkmcnt(2)
	v_mfma_f32_16x16x32_bf16 v[68:71], v[4:7], v[24:27], v[0:3]
	global_load_dwordx4 v[4:7], v[46:47], off offset:2688
	s_nop 1
	global_load_dwordx4 v[0:3], v[46:47], off offset:2752
	s_waitcnt vmcnt(0)
	v_and_b32_e32 v76, 0xffff0000, v1
	s_waitcnt lgkmcnt(1)
	v_mfma_f32_16x16x32_bf16 v[50:53], v[50:53], v[28:31], v[68:71]
	v_lshlrev_b32_e32 v77, 16, v2
	v_and_b32_e32 v78, 0xffff0000, v2
	v_lshlrev_b32_e32 v79, 16, v3
	s_waitcnt lgkmcnt(0)
	v_mfma_f32_16x16x32_bf16 v[50:53], v[60:63], v[16:19], v[50:53]
	v_and_b32_e32 v69, 0xffff0000, v73
	v_and_b32_e32 v68, 0xffff0000, v72
	v_and_b32_e32 v80, 0xffff0000, v3
	s_nop 4
	v_mov_b32_e32 v60, v50
	v_mov_b32_e32 v61, v52
	v_mov_b32_e32 v52, v51
	v_pk_add_f32 v[50:51], v[48:49], v[60:61] op_sel_hi:[0,1]
	v_pk_add_f32 v[52:53], v[48:49], v[52:53] op_sel_hi:[0,1]
	v_pk_mul_f32 v[90:91], v[50:51], v[74:75]
	v_pk_mul_f32 v[92:93], v[52:53], v[68:69]
	s_nop 0
	v_cvt_pk_bf16_f32 v156, v90, v92
	v_cvt_pk_bf16_f32 v154, v91, v93
	ds_read_b128 v[50:53], v152 offset:39168
	ds_read_b128 v[60:63], v152 offset:39232
	s_waitcnt lgkmcnt(1)
	v_mfma_f32_16x16x32_bf16 v[50:53], v[50:53], v[20:23], 0
	s_waitcnt lgkmcnt(0)
	v_mfma_f32_16x16x32_bf16 v[50:53], v[60:63], v[24:27], v[50:53]
	ds_read_b128 v[60:63], v152 offset:39296
	ds_read_b128 v[68:71], v152 offset:39360
	s_waitcnt lgkmcnt(1)
	v_mfma_f32_16x16x32_bf16 v[50:53], v[60:63], v[28:31], v[50:53]
	v_mov_b64_e32 v[60:61], v[224:225]
	s_waitcnt vmcnt(0)
	v_lshlrev_b32_e32 v62, 16, v60
	s_waitcnt lgkmcnt(0)
	v_mfma_f32_16x16x32_bf16 v[50:53], v[68:71], v[16:19], v[50:53]
	v_and_b32_e32 v63, 0xffff0000, v60
	v_lshlrev_b32_e32 v60, 16, v61
	v_and_b32_e32 v61, 0xffff0000, v61
	s_nop 4
	v_pk_add_f32 v[50:51], v[48:49], v[50:51] op_sel_hi:[0,1]
	v_pk_add_f32 v[52:53], v[48:49], v[52:53] op_sel_hi:[0,1]
	v_pk_mul_f32 v[94:95], v[50:51], v[62:63]
	v_pk_mul_f32 v[96:97], v[52:53], v[60:61]
	v_cvt_pk_bf16_f32 v153, v94, v95
	s_nop 0
	v_cvt_pk_bf16_f32 v151, v96, v97
	ds_read_b128 v[50:53], v152 offset:43520
	ds_read_b128 v[60:63], v152 offset:43584
	s_waitcnt lgkmcnt(1)
	v_mfma_f32_16x16x32_bf16 v[50:53], v[50:53], v[20:23], 0
	s_waitcnt lgkmcnt(0)
	v_mfma_f32_16x16x32_bf16 v[50:53], v[60:63], v[24:27], v[50:53]
	ds_read_b128 v[60:63], v152 offset:43648
	ds_read_b128 v[68:71], v152 offset:43712
	s_waitcnt lgkmcnt(1)
	v_mfma_f32_16x16x32_bf16 v[50:53], v[60:63], v[28:31], v[50:53]
	v_mov_b64_e32 v[60:61], v[226:227]
	s_waitcnt vmcnt(0)
	v_and_b32_e32 v54, 0xffff0000, v60
	s_waitcnt lgkmcnt(0)
	v_mfma_f32_16x16x32_bf16 v[50:53], v[68:71], v[16:19], v[50:53]
	v_lshlrev_b32_e32 v56, 16, v61
	v_and_b32_e32 v61, 0xffff0000, v61
	s_nop 5
	v_add_f32_e32 v49, v48, v50
	v_add_f32_e32 v50, v48, v51
	v_add_f32_e32 v51, v48, v52
	v_add_f32_e32 v52, v48, v53
	v_lshlrev_b32_e32 v53, 16, v60
	v_mul_f32_e32 v60, v49, v53
	v_mul_f32_e32 v100, v50, v54
	v_mul_f32_e32 v62, v51, v56
	v_mul_f32_e32 v98, v52, v61
	v_cvt_pk_bf16_f32 v149, v60, v100
	v_cvt_pk_bf16_f32 v147, v62, v98
	ds_read_b128 v[50:53], v152 offset:47872
	ds_read_b128 v[68:71], v152 offset:47936
	s_waitcnt lgkmcnt(1)
	v_mfma_f32_16x16x32_bf16 v[50:53], v[50:53], v[20:23], 0
	v_mov_b32_e32 v102, v60
	v_mov_b32_e32 v104, v62
	s_waitcnt lgkmcnt(0)
	v_mfma_f32_16x16x32_bf16 v[50:53], v[68:71], v[24:27], v[50:53]
	ds_read_b128 v[68:71], v152 offset:48000
	ds_read_b128 v[72:75], v152 offset:48064
	s_waitcnt lgkmcnt(1)
	v_mfma_f32_16x16x32_bf16 v[50:53], v[68:71], v[28:31], v[50:53]
	v_mov_b64_e32 v[68:69], v[228:229]
	s_waitcnt vmcnt(0)
	v_lshlrev_b32_e32 v103, 16, v69
	s_waitcnt lgkmcnt(0)
	v_mfma_f32_16x16x32_bf16 v[50:53], v[72:75], v[16:19], v[50:53]
	v_and_b32_e32 v105, 0xffff0000, v69
	s_nop 6
	v_add_f32_e32 v49, v48, v50
	v_add_f32_e32 v50, v48, v51
	v_add_f32_e32 v61, v48, v52
	v_add_f32_e32 v63, v48, v53
	v_lshlrev_b32_e32 v51, 16, v68
	v_and_b32_e32 v52, 0xffff0000, v68
	v_mul_f32_e32 v109, v49, v51
	v_mul_f32_e32 v107, v50, v52
	v_pk_mul_f32 v[110:111], v[60:61], v[102:103]
	v_pk_mul_f32 v[112:113], v[62:63], v[104:105]
	v_cvt_pk_bf16_f32 v146, v109, v107
	v_mov_b32_e32 v101, v61
	v_cvt_pk_bf16_f32 v143, v111, v113
	ds_read_b128 v[50:53], v152 offset:52224
	ds_read_b128 v[68:71], v152 offset:52288
	s_waitcnt lgkmcnt(1)
	v_mfma_f32_16x16x32_bf16 v[50:53], v[50:53], v[20:23], 0
	v_mov_b32_e32 v99, v63
	v_mov_b32_e32 v102, v100
	v_mov_b32_e32 v104, v98
	s_waitcnt lgkmcnt(0)
	v_mfma_f32_16x16x32_bf16 v[50:53], v[68:71], v[24:27], v[50:53]
	ds_read_b128 v[68:71], v152 offset:52352
	ds_read_b128 v[72:75], v152 offset:52416
	v_mov_b32_e32 v3, v109
	s_waitcnt lgkmcnt(1)
	v_mfma_f32_16x16x32_bf16 v[50:53], v[68:71], v[28:31], v[50:53]
	v_mov_b64_e32 v[68:69], v[230:231]
	s_waitcnt lgkmcnt(0)
	v_mfma_f32_16x16x32_bf16 v[50:53], v[72:75], v[16:19], v[50:53]
	s_nop 7
	v_mov_b32_e32 v70, v50
	v_mov_b32_e32 v71, v52
	v_mov_b32_e32 v52, v51
	v_pk_add_f32 v[50:51], v[48:49], v[70:71] op_sel_hi:[0,1]
	v_pk_add_f32 v[52:53], v[48:49], v[52:53] op_sel_hi:[0,1]
	s_waitcnt vmcnt(0)
	v_lshlrev_b32_e32 v71, 16, v69
	v_lshlrev_b32_e32 v70, 16, v68
	v_and_b32_e32 v69, 0xffff0000, v69
	v_and_b32_e32 v68, 0xffff0000, v68
	v_pk_mul_f32 v[114:115], v[50:51], v[70:71]
	v_pk_mul_f32 v[116:117], v[52:53], v[68:69]
	s_nop 0
	v_cvt_pk_bf16_f32 v144, v114, v116
	v_cvt_pk_bf16_f32 v141, v115, v117
	ds_read_b128 v[50:53], v152 offset:56576
	ds_read_b128 v[68:71], v152 offset:56640
	s_waitcnt lgkmcnt(1)
	v_mfma_f32_16x16x32_bf16 v[50:53], v[50:53], v[20:23], 0
	s_waitcnt lgkmcnt(0)
	v_mfma_f32_16x16x32_bf16 v[50:53], v[68:71], v[24:27], v[50:53]
	ds_read_b128 v[68:71], v152 offset:56704
	ds_read_b128 v[72:75], v152 offset:56768
	s_waitcnt lgkmcnt(1)
	v_mfma_f32_16x16x32_bf16 v[50:53], v[68:71], v[28:31], v[50:53]
	v_mov_b64_e32 v[68:69], v[232:233]
	s_waitcnt lgkmcnt(0)
	v_mfma_f32_16x16x32_bf16 v[50:53], v[72:75], v[16:19], v[50:53]
	s_nop 7
	v_pk_add_f32 v[50:51], v[48:49], v[50:51] op_sel_hi:[0,1]
	v_pk_add_f32 v[70:71], v[48:49], v[52:53] op_sel_hi:[0,1]
	s_waitcnt vmcnt(0)
	v_lshlrev_b32_e32 v52, 16, v68
	v_and_b32_e32 v53, 0xffff0000, v68
	v_lshlrev_b32_e32 v68, 16, v69
	v_and_b32_e32 v69, 0xffff0000, v69
	v_pk_mul_f32 v[52:53], v[50:51], v[52:53]
	v_pk_mul_f32 v[118:119], v[70:71], v[68:69]
	v_cvt_pk_bf16_f32 v140, v52, v53
	s_nop 0
	v_cvt_pk_bf16_f32 v138, v118, v119
	ds_read_b128 v[68:71], v152 offset:60928
	ds_read_b128 v[72:75], v152 offset:60992
	s_waitcnt lgkmcnt(1)
	v_mfma_f32_16x16x32_bf16 v[68:71], v[68:71], v[20:23], 0
	s_waitcnt lgkmcnt(0)
	v_mfma_f32_16x16x32_bf16 v[68:71], v[72:75], v[24:27], v[68:71]
	ds_read_b128 v[72:75], v152 offset:61056
	ds_read_b128 v[120:123], v152 offset:61120
	v_mov_b64_e32 v[50:51], v[234:235]
	s_waitcnt vmcnt(0)
	v_lshlrev_b32_e32 v62, 16, v50
	s_waitcnt lgkmcnt(1)
	v_mfma_f32_16x16x32_bf16 v[68:71], v[72:75], v[28:31], v[68:71]
	v_and_b32_e32 v50, 0xffff0000, v50
	s_waitcnt lgkmcnt(0)
	v_mfma_f32_16x16x32_bf16 v[68:71], v[120:123], v[16:19], v[68:71]
	s_nop 7
	v_add_f32_e32 v49, v48, v68
	v_add_f32_e32 v54, v48, v69
	v_add_f32_e32 v56, v48, v70
	v_add_f32_e32 v60, v48, v71
	v_lshlrev_b32_e32 v68, 16, v51
	v_and_b32_e32 v51, 0xffff0000, v51
	v_mul_f32_e32 v120, v49, v62
	v_mul_f32_e32 v62, v54, v50
	v_mul_f32_e32 v122, v56, v68
	v_mul_f32_e32 v60, v60, v51
	v_cvt_pk_bf16_f32 v135, v120, v62
	v_cvt_pk_bf16_f32 v131, v122, v60
	ds_read_b128 v[68:71], v152 offset:65280
	ds_read_b128 v[72:75], v152 offset:65344
	s_waitcnt lgkmcnt(1)
	v_mfma_f32_16x16x32_bf16 v[20:23], v[68:71], v[20:23], 0
	v_mov_b32_e32 v68, v120
	v_mov_b32_e32 v70, v122
	v_and_b32_e32 v50, 0xffff0000, v12
	s_waitcnt lgkmcnt(0)
	v_mfma_f32_16x16x32_bf16 v[20:23], v[72:75], v[24:27], v[20:23]
	ds_read_b128 v[24:27], v152 offset:65408
	ds_read_b128 v[72:75], v152 offset:65472
	v_lshlrev_b32_e32 v54, 16, v13
	v_and_b32_e32 v56, 0xffff0000, v13
	s_waitcnt lgkmcnt(1)
	v_mfma_f32_16x16x32_bf16 v[20:23], v[24:27], v[28:31], v[20:23]
	v_mov_b64_e32 v[24:25], v[236:237]
	s_waitcnt vmcnt(0)
	v_lshlrev_b32_e32 v69, 16, v25
	s_waitcnt lgkmcnt(0)
	v_mfma_f32_16x16x32_bf16 v[16:19], v[72:75], v[16:19], v[20:23]
	v_and_b32_e32 v71, 0xffff0000, v25
	s_nop 6
	v_add_f32_e32 v16, v48, v16
	v_add_f32_e32 v17, v48, v17
	v_add_f32_e32 v121, v48, v18
	v_add_f32_e32 v123, v48, v19
	v_lshlrev_b32_e32 v18, 16, v24
	v_and_b32_e32 v19, 0xffff0000, v24
	v_mul_f32_e32 v51, v16, v18
	v_mul_f32_e32 v49, v17, v19
	v_pk_mul_f32 v[72:73], v[120:121], v[68:69]
	v_pk_mul_f32 v[74:75], v[122:123], v[70:71]
	v_cvt_pk_bf16_f32 v122, v51, v49
	v_lshlrev_b32_e32 v48, 16, v12
	v_cvt_pk_bf16_f32 v120, v73, v75
	global_load_dwordx4 v[16:19], v157, s[48:49] offset:1024
	global_load_dwordx4 v[20:23], v157, s[50:51] offset:1024
	global_load_dwordx4 v[24:27], v157, s[48:49] offset:1040
	global_load_dwordx4 v[28:31], v157, s[50:51] offset:1040
	global_load_dwordx4 v[178:181], v157, s[48:49] offset:1152
	global_load_dwordx4 v[182:185], v157, s[50:51] offset:1152
	global_load_dwordx4 v[186:189], v157, s[48:49] offset:1168
	global_load_dwordx4 v[190:193], v157, s[50:51] offset:1168
	global_load_dwordx4 v[194:197], v157, s[48:49] offset:1280
	global_load_dwordx4 v[198:201], v157, s[50:51] offset:1280
	global_load_dwordx4 v[202:205], v157, s[48:49] offset:1296
	global_load_dwordx4 v[206:209], v157, s[50:51] offset:1296
	global_load_dwordx4 v[210:213], v157, s[48:49] offset:1408
	global_load_dwordx4 v[214:217], v157, s[50:51] offset:1408
	global_load_dwordx4 v[218:221], v157, s[48:49] offset:1424
	global_load_dwordx4 v[238:241], v157, s[50:51] offset:1424
	ds_read_b64 v[12:13], v160
	v_lshlrev_b32_e32 v70, 16, v15
	v_and_b32_e32 v15, 0xffff0000, v15
	v_lshlrev_b32_e32 v68, 16, v14
	v_and_b32_e32 v14, 0xffff0000, v14
	s_waitcnt lgkmcnt(0)
	v_sub_f32_e32 v48, v48, v12
	v_sub_f32_e32 v15, v15, v12
	v_sub_f32_e32 v50, v50, v12
	v_mul_f32_e32 v48, v13, v48
	v_mul_f32_e32 v15, v13, v15
	v_sub_f32_e32 v54, v54, v12
	v_mul_f32_e32 v50, v13, v50
	v_sub_f32_e32 v56, v56, v12
	v_sub_f32_e32 v14, v14, v12
	v_mul_f32_e32 v54, v13, v54
	v_sub_f32_e32 v68, v68, v12
	v_mul_f32_e32 v56, v13, v56
	v_mul_f32_e32 v14, v13, v14
	v_sub_f32_e32 v70, v70, v12
	v_mul_f32_e32 v68, v13, v68
	v_mul_f32_e32 v70, v13, v70
	v_mov_b32_e32 v63, v121
	v_mov_b32_e32 v61, v123
	s_waitcnt vmcnt(2)
	v_fma_f32 v16, v16, v48, v20
	v_fma_f32 v17, v17, v50, v21
	s_waitcnt vmcnt(0)
	v_fmac_f32_e32 v31, v27, v15
	v_cvt_pk_bf16_f32 v15, v16, v33
	ds_write_b16 v155, v15
	v_cvt_pk_bf16_f32 v15, v17, v33
	v_fma_f32 v18, v18, v54, v22
	ds_write_b16 v155, v15 offset:272
	v_cvt_pk_bf16_f32 v15, v18, v33
	v_fmac_f32_e32 v23, v19, v56
	v_fma_f32 v14, v25, v14, v29
	ds_write_b16 v155, v15 offset:544
	v_cvt_pk_bf16_f32 v15, v23, v33
	v_fma_f32 v19, v24, v68, v28
	ds_write_b16 v155, v15 offset:816
	v_cvt_pk_bf16_f32 v15, v19, v33
	ds_write_b16 v155, v15 offset:1088
	v_cvt_pk_bf16_f32 v14, v14, v33
	v_fma_f32 v20, v26, v70, v30
	ds_write_b16 v155, v14 offset:1360
	v_cvt_pk_bf16_f32 v14, v20, v33
	ds_write_b16 v155, v14 offset:1632
	v_cvt_pk_bf16_f32 v30, v31, v33
	v_mov_b64_e32 v[14:15], v[178:179]
	v_mov_b64_e32 v[16:17], v[180:181]
	v_mov_b64_e32 v[18:19], v[182:183]
	v_mov_b64_e32 v[20:21], v[184:185]
	v_mov_b64_e32 v[22:23], v[186:187]
	v_mov_b64_e32 v[24:25], v[188:189]
	v_mov_b64_e32 v[26:27], v[190:191]
	v_mov_b64_e32 v[28:29], v[192:193]
	v_lshlrev_b32_e32 v31, 16, v8
	v_and_b32_e32 v8, 0xffff0000, v8
	v_lshlrev_b32_e32 v54, 16, v11
	v_and_b32_e32 v11, 0xffff0000, v11
	v_sub_f32_e32 v8, v8, v12
	v_lshlrev_b32_e32 v48, 16, v9
	v_sub_f32_e32 v31, v31, v12
	v_sub_f32_e32 v11, v11, v12
	v_mul_f32_e32 v8, v13, v8
	v_and_b32_e32 v9, 0xffff0000, v9
	v_sub_f32_e32 v48, v48, v12
	v_mul_f32_e32 v31, v13, v31
	v_mul_f32_e32 v11, v13, v11
	v_lshlrev_b32_e32 v50, 16, v10
	v_sub_f32_e32 v9, v9, v12
	v_mul_f32_e32 v48, v13, v48
	ds_write_b16 v155, v30 offset:1904
	v_and_b32_e32 v10, 0xffff0000, v10
	v_sub_f32_e32 v50, v50, v12
	v_mul_f32_e32 v9, v13, v9
	v_sub_f32_e32 v10, v10, v12
	v_mul_f32_e32 v50, v13, v50
	v_sub_f32_e32 v54, v54, v12
	v_mul_f32_e32 v10, v13, v10
	v_mul_f32_e32 v54, v13, v54
	v_mul_f32_e32 v30, v59, v59
	v_mov_b32_e32 v68, v62
	v_mov_b32_e32 v70, v60
	s_waitcnt vmcnt(2)
	v_fma_f32 v8, v8, v15, v19
	v_fma_f32 v14, v31, v14, v18
	s_waitcnt vmcnt(0)
	v_fmac_f32_e32 v29, v11, v25
	v_cvt_pk_bf16_f32 v11, v14, v33
	ds_write_b16 v155, v11 offset:8704
	v_cvt_pk_bf16_f32 v8, v8, v33
	v_fma_f32 v15, v48, v16, v20
	ds_write_b16 v155, v8 offset:8976
	v_cvt_pk_bf16_f32 v8, v15, v33
	v_fmac_f32_e32 v21, v9, v17
	ds_write_b16 v155, v8 offset:9248
	v_cvt_pk_bf16_f32 v8, v21, v33
	v_fma_f32 v9, v50, v22, v26
	ds_write_b16 v155, v8 offset:9520
	v_cvt_pk_bf16_f32 v8, v9, v33
	v_fma_f32 v10, v10, v23, v27
	ds_write_b16 v155, v8 offset:9792
	v_cvt_pk_bf16_f32 v8, v10, v33
	v_fma_f32 v16, v54, v24, v28
	ds_write_b16 v155, v8 offset:10064
	v_cvt_pk_bf16_f32 v8, v16, v33
	ds_write_b16 v155, v8 offset:10336
	v_cvt_pk_bf16_f32 v48, v29, v33
	v_mov_b64_e32 v[8:9], v[194:195]
	v_mov_b64_e32 v[10:11], v[196:197]
	v_mov_b64_e32 v[14:15], v[198:199]
	v_mov_b64_e32 v[16:17], v[200:201]
	v_mov_b64_e32 v[18:19], v[202:203]
	v_mov_b64_e32 v[20:21], v[204:205]
	v_mov_b64_e32 v[22:23], v[206:207]
	v_mov_b64_e32 v[24:25], v[208:209]
	v_pk_add_f32 v[26:27], v[88:89], v[88:89] op_sel:[0,1] op_sel_hi:[1,0]
	v_pk_fma_f32 v[30:31], v[58:59], v[58:59], v[30:31] op_sel_hi:[1,1,0]
	v_mov_b32_e32 v56, v26
	v_pk_add_f32 v[26:27], v[26:27], v[86:87]
	v_lshlrev_b32_e32 v58, 16, v7
	v_lshlrev_b32_e32 v27, 16, v4
	v_and_b32_e32 v4, 0xffff0000, v4
	v_and_b32_e32 v7, 0xffff0000, v7
	v_sub_f32_e32 v4, v4, v12
	v_lshlrev_b32_e32 v50, 16, v5
	v_sub_f32_e32 v27, v27, v12
	v_sub_f32_e32 v7, v7, v12
	v_mul_f32_e32 v4, v13, v4
	v_and_b32_e32 v5, 0xffff0000, v5
	v_sub_f32_e32 v50, v50, v12
	v_mul_f32_e32 v27, v13, v27
	v_mul_f32_e32 v7, v13, v7
	v_lshlrev_b32_e32 v54, 16, v6
	v_sub_f32_e32 v5, v5, v12
	v_mul_f32_e32 v50, v13, v50
	ds_write_b16 v155, v48 offset:10608
	v_and_b32_e32 v6, 0xffff0000, v6
	v_sub_f32_e32 v54, v54, v12
	v_mul_f32_e32 v5, v13, v5
	v_sub_f32_e32 v6, v6, v12
	v_mul_f32_e32 v54, v13, v54
	v_sub_f32_e32 v58, v58, v12
	v_mul_f32_e32 v6, v13, v6
	v_mul_f32_e32 v58, v13, v58
	v_mov_b32_e32 v28, v86
	v_mov_b32_e32 v29, v57
	v_mov_b32_e32 v88, v84
	v_mov_b32_e32 v89, v55
	s_waitcnt vmcnt(2)
	v_fma_f32 v4, v4, v9, v15
	v_fma_f32 v8, v27, v8, v14
	s_waitcnt vmcnt(0)
	v_fmac_f32_e32 v25, v7, v21
	v_cvt_pk_bf16_f32 v7, v8, v33
	ds_write_b16 v155, v7 offset:17408
	v_cvt_pk_bf16_f32 v4, v4, v33
	v_fma_f32 v9, v50, v10, v16
	ds_write_b16 v155, v4 offset:17680
	v_cvt_pk_bf16_f32 v4, v9, v33
	v_fmac_f32_e32 v17, v5, v11
	ds_write_b16 v155, v4 offset:17952
	v_cvt_pk_bf16_f32 v4, v17, v33
	v_fma_f32 v5, v54, v18, v22
	ds_write_b16 v155, v4 offset:18224
	v_cvt_pk_bf16_f32 v4, v5, v33
	v_fma_f32 v6, v6, v19, v23
	ds_write_b16 v155, v4 offset:18496
	v_cvt_pk_bf16_f32 v4, v6, v33
	v_fma_f32 v10, v58, v20, v24
	ds_write_b16 v155, v4 offset:18768
	v_cvt_pk_bf16_f32 v4, v10, v33
	ds_write_b16 v155, v4 offset:19040
	v_cvt_pk_bf16_f32 v48, v25, v33
	v_mov_b64_e32 v[4:5], v[210:211]
	v_mov_b64_e32 v[6:7], v[212:213]
	v_mov_b64_e32 v[8:9], v[214:215]
	v_mov_b64_e32 v[10:11], v[216:217]
	v_mov_b64_e32 v[14:15], v[218:219]
	v_mov_b64_e32 v[16:17], v[220:221]
	v_mov_b64_e32 v[18:19], v[238:239]
	v_mov_b64_e32 v[20:21], v[240:241]
	v_pk_mul_f32 v[22:23], v[56:57], v[28:29]
	v_mov_b32_e32 v54, v30
	v_pk_add_f32 v[24:25], v[30:31], v[84:85]
	v_mov_b32_e32 v27, v23
	v_pk_mul_f32 v[22:23], v[54:55], v[88:89]
	v_pk_add_f32 v[28:29], v[66:67], v[64:65]
	v_mov_b32_e32 v25, v23
	v_pk_add_f32 v[22:23], v[26:27], v[24:25]
	v_lshlrev_b32_e32 v50, 16, v0
	v_and_b32_e32 v56, 0xffff0000, v0
	v_lshlrev_b32_e32 v57, 16, v1
	v_pk_mul_f32 v[0:1], v[92:93], v[92:93]
	v_pk_add_f32 v[22:23], v[22:23], v[28:29]
	v_pk_fma_f32 v[0:1], v[90:91], v[90:91], v[0:1]
	v_pk_add_f32 v[22:23], v[22:23], v[22:23] op_sel:[0,1] op_sel_hi:[1,0]
	v_pk_add_f32 v[0:1], v[0:1], v[0:1] op_sel:[0,1] op_sel_hi:[1,0]
	v_mov_b32_e32 v108, v22
	v_mov_b32_e32 v2, v0
	v_pk_add_f32 v[0:1], v[22:23], v[0:1]
	v_mul_f32_e32 v22, v97, v97
	v_mul_f32_e32 v24, v95, v95
	v_pk_fma_f32 v[22:23], v[96:97], v[96:97], v[22:23] op_sel_hi:[1,1,0]
	v_pk_fma_f32 v[24:25], v[94:95], v[94:95], v[24:25] op_sel_hi:[1,1,0]
	v_mov_b32_e32 v26, v22
	v_mov_b32_e32 v106, v24
	v_mov_b32_e32 v27, v107
	v_pk_add_f32 v[22:23], v[24:25], v[22:23]
	v_pk_fma_f32 v[24:25], v[100:101], v[102:103], v[110:111]
	v_pk_mul_f32 v[28:29], v[110:111], v[110:111]
	v_pk_fma_f32 v[30:31], v[98:99], v[104:105], v[112:113]
	v_pk_mul_f32 v[54:55], v[112:113], v[112:113]
	v_pk_mul_f32 v[2:3], v[108:109], v[2:3]
	v_pk_mul_f32 v[26:27], v[106:107], v[26:27]
	v_mov_b32_e32 v25, v29
	v_mov_b32_e32 v31, v55
	v_mov_b32_e32 v1, v3
	v_mov_b32_e32 v23, v27
	v_pk_add_f32 v[2:3], v[24:25], v[30:31]
	v_pk_add_f32 v[0:1], v[0:1], v[22:23]
	ds_write_b16 v155, v48 offset:19312
	v_pk_add_f32 v[66:67], v[0:1], v[2:3]
	v_pk_mul_f32 v[0:1], v[116:117], v[116:117]
	v_sub_f32_e32 v2, v57, v12
	v_pk_fma_f32 v[0:1], v[114:115], v[114:115], v[0:1]
	v_sub_f32_e32 v3, v76, v12
	v_pk_add_f32 v[64:65], v[0:1], v[0:1] op_sel:[0,1] op_sel_hi:[1,0]
	v_mul_f32_e32 v0, v119, v119
	v_pk_fma_f32 v[58:59], v[118:119], v[118:119], v[0:1] op_sel_hi:[1,1,0]
	v_sub_f32_e32 v0, v50, v12
	v_mul_f32_e32 v0, v13, v0
	v_sub_f32_e32 v1, v56, v12
	v_mul_f32_e32 v1, v13, v1
	v_mul_f32_e32 v2, v13, v2
	v_sub_f32_e32 v22, v77, v12
	v_mul_f32_e32 v3, v13, v3
	v_sub_f32_e32 v23, v78, v12
	v_mul_f32_e32 v22, v13, v22
	v_sub_f32_e32 v24, v79, v12
	v_mul_f32_e32 v23, v13, v23
	v_sub_f32_e32 v12, v80, v12
	v_mul_f32_e32 v24, v13, v24
	v_mul_f32_e32 v12, v13, v12
	s_waitcnt vmcnt(2)
	v_fma_f32 v0, v0, v4, v8
	v_cvt_pk_bf16_f32 v0, v0, v33
	v_fma_f32 v1, v1, v5, v9
	ds_write_b16 v155, v0 offset:26112
	v_cvt_pk_bf16_f32 v0, v1, v33
	v_fma_f32 v2, v2, v6, v10
	ds_write_b16 v155, v0 offset:26384
	v_cvt_pk_bf16_f32 v0, v2, v33
	v_fmac_f32_e32 v11, v3, v7
	ds_write_b16 v155, v0 offset:26656
	v_cvt_pk_bf16_f32 v0, v11, v33
	s_waitcnt vmcnt(0)
	v_fma_f32 v3, v22, v14, v18
	ds_write_b16 v155, v0 offset:26928
	v_cvt_pk_bf16_f32 v0, v3, v33
	v_fma_f32 v4, v23, v15, v19
	ds_write_b16 v155, v0 offset:27200
	v_cvt_pk_bf16_f32 v0, v4, v33
	v_fma_f32 v5, v24, v16, v20
	ds_write_b16 v155, v0 offset:27472
	v_cvt_pk_bf16_f32 v0, v5, v33
	v_fmac_f32_e32 v21, v12, v17
	ds_write_b16 v155, v0 offset:27744
	v_cvt_pk_bf16_f32 v0, v21, v33
	ds_write_b16 v155, v0 offset:28016
	s_waitcnt lgkmcnt(0)
	s_barrier
	v_add_co_u32_e32 v0, vcc, s27, v42
	v_pk_fma_f32 v[68:69], v[62:63], v[68:69], v[72:73]
	s_nop 0
	v_addc_co_u32_e32 v1, vcc, 0, v43, vcc
	global_load_dwordx2 v[224:225], v[40:41], off offset:1568
	global_load_dwordx2 v[226:227], v[40:41], off offset:1600
	global_load_dwordx2 v[228:229], v[40:41], off offset:1632
	global_load_dwordx2 v[230:231], v[40:41], off offset:1664
	global_load_dwordx2 v[232:233], v[40:41], off offset:1696
	global_load_dwordx2 v[234:235], v[40:41], off offset:1728
	global_load_dwordx2 v[236:237], v[40:41], off offset:1760
	global_load_dwordx4 v[20:23], v[0:1], off
	global_load_dwordx4 v[24:27], v[0:1], off offset:64
	global_load_dwordx2 v[84:85], v[40:41], off offset:1536
	global_load_dwordx4 v[28:31], v[0:1], off offset:128
	global_load_dwordx4 v[16:19], v[0:1], off offset:192
	global_load_dword v48, v[44:45], off offset:1024
	ds_read_b128 v[0:3], v152
	ds_read_b128 v[4:7], v152 offset:64
	ds_read_b128 v[54:57], v152 offset:128
	global_load_dwordx4 v[12:15], v[46:47], off offset:2816
	global_load_dwordx4 v[8:11], v[46:47], off offset:2880
	ds_read_b128 v[76:79], v152 offset:192
	v_pk_mul_f32 v[62:63], v[72:73], v[72:73]
	v_pk_fma_f32 v[70:71], v[60:61], v[70:71], v[74:75]
	v_pk_mul_f32 v[60:61], v[74:75], v[74:75]
	v_mov_b32_e32 v69, v63
	v_mov_b32_e32 v71, v61
	s_waitcnt vmcnt(7) lgkmcnt(3)
	v_mfma_f32_16x16x32_bf16 v[0:3], v[0:3], v[20:23], 0
	s_waitcnt vmcnt(6) lgkmcnt(2)
	v_mfma_f32_16x16x32_bf16 v[80:83], v[4:7], v[24:27], v[0:3]
	global_load_dwordx4 v[4:7], v[46:47], off offset:2944
	s_nop 4
	global_load_dwordx4 v[0:3], v[46:47], off offset:3008
	s_waitcnt vmcnt(7)
	v_lshlrev_b32_e32 v47, 16, v85
	v_lshlrev_b32_e32 v46, 16, v84
	s_waitcnt vmcnt(6) lgkmcnt(1)
	v_mfma_f32_16x16x32_bf16 v[54:57], v[54:57], v[28:31], v[80:83]
	s_waitcnt vmcnt(0)
	v_and_b32_e32 v72, 0xffff0000, v2
	s_waitcnt lgkmcnt(0)
	v_mfma_f32_16x16x32_bf16 v[54:57], v[76:79], v[16:19], v[54:57]
	v_and_b32_e32 v81, 0xffff0000, v85
	v_and_b32_e32 v80, 0xffff0000, v84
	v_lshlrev_b32_e32 v73, 16, v3
	v_and_b32_e32 v74, 0xffff0000, v3
	s_nop 3
	v_mov_b32_e32 v76, v54
	v_mov_b32_e32 v77, v56
	v_mov_b32_e32 v56, v55
	v_pk_add_f32 v[54:55], v[48:49], v[76:77] op_sel_hi:[0,1]
	v_pk_add_f32 v[56:57], v[48:49], v[56:57] op_sel_hi:[0,1]
	v_pk_mul_f32 v[76:77], v[54:55], v[46:47]
	v_pk_mul_f32 v[78:79], v[56:57], v[80:81]
	s_nop 0
	v_cvt_pk_bf16_f32 v159, v76, v78
	v_cvt_pk_bf16_f32 v158, v77, v79
	ds_read_b128 v[54:57], v152 offset:4352
	ds_read_b128 v[80:83], v152 offset:4416
	s_waitcnt lgkmcnt(1)
	v_mfma_f32_16x16x32_bf16 v[54:57], v[54:57], v[20:23], 0
	s_waitcnt lgkmcnt(0)
	v_mfma_f32_16x16x32_bf16 v[54:57], v[80:83], v[24:27], v[54:57]
	ds_read_b128 v[80:83], v152 offset:4480
	ds_read_b128 v[84:87], v152 offset:4544
	v_mov_b64_e32 v[46:47], v[224:225]
	s_waitcnt lgkmcnt(1)
	v_mfma_f32_16x16x32_bf16 v[54:57], v[80:83], v[28:31], v[54:57]
	s_waitcnt vmcnt(0)
	v_lshlrev_b32_e32 v80, 16, v46
	s_waitcnt lgkmcnt(0)
	v_mfma_f32_16x16x32_bf16 v[54:57], v[84:87], v[16:19], v[54:57]
	v_and_b32_e32 v81, 0xffff0000, v46
	v_lshlrev_b32_e32 v46, 16, v47
	v_and_b32_e32 v47, 0xffff0000, v47
	s_nop 4
	v_pk_add_f32 v[54:55], v[48:49], v[54:55] op_sel_hi:[0,1]
	v_pk_add_f32 v[56:57], v[48:49], v[56:57] op_sel_hi:[0,1]
	v_pk_mul_f32 v[80:81], v[54:55], v[80:81]
	v_pk_mul_f32 v[82:83], v[56:57], v[46:47]
	v_cvt_pk_bf16_f32 v123, v80, v81
	s_nop 0
	v_cvt_pk_bf16_f32 v121, v82, v83
	ds_read_b128 v[54:57], v152 offset:8704
	ds_read_b128 v[84:87], v152 offset:8768
	s_waitcnt lgkmcnt(1)
	v_mfma_f32_16x16x32_bf16 v[54:57], v[54:57], v[20:23], 0
	s_waitcnt lgkmcnt(0)
	v_mfma_f32_16x16x32_bf16 v[54:57], v[84:87], v[24:27], v[54:57]
	ds_read_b128 v[84:87], v152 offset:8832
	ds_read_b128 v[88:91], v152 offset:8896
	v_mov_b64_e32 v[46:47], v[226:227]
	s_waitcnt lgkmcnt(1)
	v_mfma_f32_16x16x32_bf16 v[54:57], v[84:87], v[28:31], v[54:57]
	s_waitcnt vmcnt(0)
	v_lshlrev_b32_e32 v84, 16, v47
	s_waitcnt lgkmcnt(0)
	v_mfma_f32_16x16x32_bf16 v[54:57], v[88:91], v[16:19], v[54:57]
	v_and_b32_e32 v47, 0xffff0000, v47
	s_nop 6
	v_add_f32_e32 v50, v48, v54
	v_add_f32_e32 v55, v48, v55
	v_add_f32_e32 v56, v48, v56
	v_add_f32_e32 v57, v48, v57
	v_lshlrev_b32_e32 v54, 16, v46
	v_and_b32_e32 v46, 0xffff0000, v46
	v_mul_f32_e32 v54, v50, v54
	v_mul_f32_e32 v86, v55, v46
	v_mul_f32_e32 v56, v56, v84
	v_mul_f32_e32 v84, v57, v47
	v_cvt_pk_bf16_f32 v119, v54, v86
	v_cvt_pk_bf16_f32 v118, v56, v84
	ds_read_b128 v[88:91], v152 offset:13056
	ds_read_b128 v[92:95], v152 offset:13120
	s_waitcnt lgkmcnt(1)
	v_mfma_f32_16x16x32_bf16 v[88:91], v[88:91], v[20:23], 0
	s_waitcnt lgkmcnt(0)
	v_mfma_f32_16x16x32_bf16 v[88:91], v[92:95], v[24:27], v[88:91]
	ds_read_b128 v[92:95], v152 offset:13184
	ds_read_b128 v[96:99], v152 offset:13248
	v_mov_b64_e32 v[46:47], v[228:229]
	s_waitcnt vmcnt(0)
	v_lshlrev_b32_e32 v87, 16, v46
	s_waitcnt lgkmcnt(1)
	v_mfma_f32_16x16x32_bf16 v[92:95], v[92:95], v[28:31], v[88:91]
	v_and_b32_e32 v46, 0xffff0000, v46
	s_waitcnt lgkmcnt(0)
	v_mfma_f32_16x16x32_bf16 v[92:95], v[96:99], v[16:19], v[92:95]
	v_mov_b32_e32 v88, v54
	v_mov_b32_e32 v90, v56
	v_lshlrev_b32_e32 v89, 16, v47
	v_and_b32_e32 v91, 0xffff0000, v47
	s_nop 3
	v_add_f32_e32 v50, v48, v92
	v_add_f32_e32 v85, v48, v93
	v_add_f32_e32 v55, v48, v94
	v_add_f32_e32 v57, v48, v95
	v_mul_f32_e32 v95, v50, v87
	v_mul_f32_e32 v93, v85, v46
	v_pk_mul_f32 v[96:97], v[54:55], v[88:89]
	v_pk_mul_f32 v[98:99], v[56:57], v[90:91]
	v_cvt_pk_bf16_f32 v117, v95, v93
	v_mov_b32_e32 v3, v95
	v_cvt_pk_bf16_f32 v115, v97, v99
	ds_read_b128 v[100:103], v152 offset:17408
	ds_read_b128 v[104:107], v152 offset:17472
	s_waitcnt lgkmcnt(1)
	v_mfma_f32_16x16x32_bf16 v[100:103], v[100:103], v[20:23], 0
	s_waitcnt lgkmcnt(0)
	v_mfma_f32_16x16x32_bf16 v[100:103], v[104:107], v[24:27], v[100:103]
	ds_read_b128 v[104:107], v152 offset:17536
	ds_read_b128 v[108:111], v152 offset:17600
	v_mov_b64_e32 v[46:47], v[230:231]
	s_waitcnt lgkmcnt(1)
	v_mfma_f32_16x16x32_bf16 v[100:103], v[104:107], v[28:31], v[100:103]
	s_waitcnt lgkmcnt(0)
	v_mfma_f32_16x16x32_bf16 v[100:103], v[108:111], v[16:19], v[100:103]
	s_nop 7
	v_mov_b32_e32 v104, v100
	v_mov_b32_e32 v105, v102
	v_mov_b32_e32 v102, v101
	v_pk_add_f32 v[100:101], v[48:49], v[104:105] op_sel_hi:[0,1]
	v_pk_add_f32 v[102:103], v[48:49], v[102:103] op_sel_hi:[0,1]
	s_waitcnt vmcnt(0)
	v_lshlrev_b32_e32 v105, 16, v47
	v_lshlrev_b32_e32 v104, 16, v46
	v_and_b32_e32 v47, 0xffff0000, v47
	v_and_b32_e32 v46, 0xffff0000, v46
	v_pk_mul_f32 v[100:101], v[100:101], v[104:105]
	v_pk_mul_f32 v[102:103], v[102:103], v[46:47]
	s_nop 0
	v_cvt_pk_bf16_f32 v116, v100, v102
	v_cvt_pk_bf16_f32 v114, v101, v103
	ds_read_b128 v[104:107], v152 offset:21760
	ds_read_b128 v[108:111], v152 offset:21824
	s_waitcnt lgkmcnt(1)
	v_mfma_f32_16x16x32_bf16 v[104:107], v[104:107], v[20:23], 0
	s_waitcnt lgkmcnt(0)
	v_mfma_f32_16x16x32_bf16 v[104:107], v[108:111], v[24:27], v[104:107]
	ds_read_b128 v[108:111], v152 offset:21888
	ds_read_b128 v[162:165], v152 offset:21952
	v_mov_b64_e32 v[46:47], v[232:233]
	s_waitcnt lgkmcnt(1)
	v_mfma_f32_16x16x32_bf16 v[104:107], v[108:111], v[28:31], v[104:107]
	s_waitcnt vmcnt(0)
	v_lshlrev_b32_e32 v108, 16, v46
	s_waitcnt lgkmcnt(0)
	v_mfma_f32_16x16x32_bf16 v[104:107], v[162:165], v[16:19], v[104:107]
	v_and_b32_e32 v109, 0xffff0000, v46
	v_lshlrev_b32_e32 v110, 16, v47
	v_and_b32_e32 v111, 0xffff0000, v47
	s_nop 4
	v_pk_add_f32 v[104:105], v[48:49], v[104:105] op_sel_hi:[0,1]
	v_pk_add_f32 v[106:107], v[48:49], v[106:107] op_sel_hi:[0,1]
	v_pk_mul_f32 v[46:47], v[104:105], v[108:109]
	v_pk_mul_f32 v[104:105], v[106:107], v[110:111]
	v_cvt_pk_bf16_f32 v113, v46, v47
	s_nop 0
	v_cvt_pk_bf16_f32 v112, v104, v105
	ds_read_b128 v[106:109], v152 offset:26112
	ds_read_b128 v[162:165], v152 offset:26176
	s_waitcnt lgkmcnt(1)
	v_mfma_f32_16x16x32_bf16 v[106:109], v[106:109], v[20:23], 0
	s_waitcnt lgkmcnt(0)
	v_mfma_f32_16x16x32_bf16 v[106:109], v[162:165], v[24:27], v[106:109]
	ds_read_b128 v[162:165], v152 offset:26240
	ds_read_b128 v[166:169], v152 offset:26304
	v_mov_b64_e32 v[110:111], v[234:235]
	s_waitcnt vmcnt(0)
	v_lshlrev_b32_e32 v56, 16, v110
	s_waitcnt lgkmcnt(1)
	v_mfma_f32_16x16x32_bf16 v[106:109], v[162:165], v[28:31], v[106:109]
	v_and_b32_e32 v88, 0xffff0000, v110
	v_lshlrev_b32_e32 v90, 16, v111
	v_and_b32_e32 v92, 0xffff0000, v111
	s_waitcnt lgkmcnt(0)
	v_mfma_f32_16x16x32_bf16 v[106:109], v[166:169], v[16:19], v[106:109]
	s_nop 7
	v_add_f32_e32 v50, v48, v106
	v_add_f32_e32 v54, v48, v107
	v_add_f32_e32 v85, v48, v108
	v_add_f32_e32 v87, v48, v109
	v_mul_f32_e32 v106, v50, v56
	v_mul_f32_e32 v56, v54, v88
	v_mul_f32_e32 v108, v85, v90
	v_mul_f32_e32 v54, v87, v92
	v_cvt_pk_bf16_f32 v111, v106, v56
	v_cvt_pk_bf16_f32 v110, v108, v54
	ds_read_b128 v[162:165], v152 offset:30464
	ds_read_b128 v[166:169], v152 offset:30528
	s_waitcnt lgkmcnt(1)
	v_mfma_f32_16x16x32_bf16 v[20:23], v[162:165], v[20:23], 0
	v_mov_b32_e32 v87, v55
	v_mov_b32_e32 v85, v57
	v_mov_b32_e32 v88, v86
	s_waitcnt lgkmcnt(0)
	v_mfma_f32_16x16x32_bf16 v[20:23], v[166:169], v[24:27], v[20:23]
	ds_read_b128 v[24:27], v152 offset:30592
	ds_read_b128 v[162:165], v152 offset:30656
	v_mov_b32_e32 v90, v84
	s_waitcnt lgkmcnt(1)
	v_mfma_f32_16x16x32_bf16 v[24:27], v[24:27], v[28:31], v[20:23]
	v_mov_b64_e32 v[28:29], v[236:237]
	v_lshlrev_b32_e32 v30, 16, v15
	s_nop 0
	v_mov_b32_e32 v20, v106
	s_waitcnt lgkmcnt(0)
	v_mfma_f32_16x16x32_bf16 v[16:19], v[162:165], v[16:19], v[24:27]
	v_mov_b32_e32 v22, v108
	v_and_b32_e32 v15, 0xffff0000, v15
	v_mov_b32_e32 v31, v51
	s_waitcnt vmcnt(0)
	v_and_b32_e32 v24, 0xffff0000, v28
	s_nop 2
	v_add_f32_e32 v16, v48, v16
	v_add_f32_e32 v17, v48, v17
	v_add_f32_e32 v107, v48, v18
	v_add_f32_e32 v109, v48, v19
	v_lshlrev_b32_e32 v18, 16, v28
	v_lshlrev_b32_e32 v21, 16, v29
	v_and_b32_e32 v23, 0xffff0000, v29
	v_mul_f32_e32 v19, v16, v18
	v_mul_f32_e32 v17, v17, v24
	v_pk_mul_f32 v[26:27], v[106:107], v[20:21]
	v_pk_mul_f32 v[24:25], v[108:109], v[22:23]
	v_cvt_pk_bf16_f32 v106, v19, v17
	v_lshlrev_b32_e32 v16, 16, v12
	v_cvt_pk_bf16_f32 v29, v27, v25
	global_load_dwordx4 v[162:165], v157, s[48:49] offset:1536
	global_load_dwordx4 v[166:169], v157, s[50:51] offset:1536
	global_load_dwordx4 v[170:173], v157, s[48:49] offset:1552
	global_load_dwordx4 v[174:177], v157, s[50:51] offset:1552
	global_load_dwordx4 v[178:181], v157, s[48:49] offset:1664
	global_load_dwordx4 v[182:185], v157, s[50:51] offset:1664
	global_load_dwordx4 v[186:189], v157, s[48:49] offset:1680
	global_load_dwordx4 v[190:193], v157, s[50:51] offset:1680
	global_load_dwordx4 v[194:197], v157, s[48:49] offset:1792
	global_load_dwordx4 v[198:201], v157, s[50:51] offset:1792
	global_load_dwordx4 v[202:205], v157, s[48:49] offset:1808
	global_load_dwordx4 v[206:209], v157, s[50:51] offset:1808
	global_load_dwordx4 v[210:213], v157, s[48:49] offset:1920
	global_load_dwordx4 v[214:217], v157, s[50:51] offset:1920
	global_load_dwordx4 v[218:221], v157, s[48:49] offset:1936
	global_load_dwordx4 v[238:241], v157, s[50:51] offset:1936
	v_and_b32_e32 v18, 0xffff0000, v12
	v_lshlrev_b32_e32 v20, 16, v13
	v_and_b32_e32 v22, 0xffff0000, v13
	ds_read_b64 v[12:13], v160
	v_lshlrev_b32_e32 v28, 16, v14
	v_and_b32_e32 v14, 0xffff0000, v14
	v_mov_b32_e32 v57, v107
	v_mov_b32_e32 v55, v109
	s_waitcnt lgkmcnt(0)
	v_sub_f32_e32 v16, v16, v12
	v_sub_f32_e32 v15, v15, v12
	v_sub_f32_e32 v18, v18, v12
	v_mul_f32_e32 v16, v13, v16
	v_mul_f32_e32 v15, v13, v15
	v_sub_f32_e32 v20, v20, v12
	v_mul_f32_e32 v18, v13, v18
	v_sub_f32_e32 v22, v22, v12
	v_sub_f32_e32 v14, v14, v12
	v_mul_f32_e32 v20, v13, v20
	v_sub_f32_e32 v28, v28, v12
	v_mul_f32_e32 v22, v13, v22
	v_mul_f32_e32 v14, v13, v14
	v_sub_f32_e32 v30, v30, v12
	v_mul_f32_e32 v28, v13, v28
	v_mul_f32_e32 v30, v13, v30
	s_waitcnt vmcnt(2)
	v_fma_f32 v16, v162, v16, v166
	v_fma_f32 v18, v163, v18, v167
	s_waitcnt vmcnt(0)
	v_fmac_f32_e32 v177, v173, v15
	v_cvt_pk_bf16_f32 v15, v16, v33
	ds_write_b16 v155, v15 offset:34816
	v_cvt_pk_bf16_f32 v15, v18, v33
	v_fma_f32 v20, v164, v20, v168
	ds_write_b16 v155, v15 offset:35088
	v_cvt_pk_bf16_f32 v15, v20, v33
	v_fmac_f32_e32 v169, v165, v22
	v_fma_f32 v14, v171, v14, v175
	ds_write_b16 v155, v15 offset:35360
	v_cvt_pk_bf16_f32 v15, v169, v33
	v_fma_f32 v22, v170, v28, v174
	ds_write_b16 v155, v15 offset:35632
	v_cvt_pk_bf16_f32 v15, v22, v33
	ds_write_b16 v155, v15 offset:35904
	v_cvt_pk_bf16_f32 v14, v14, v33
	v_fma_f32 v28, v172, v30, v176
	ds_write_b16 v155, v14 offset:36176
	v_cvt_pk_bf16_f32 v14, v28, v33
	ds_write_b16 v155, v14 offset:36448
	v_cvt_pk_bf16_f32 v14, v177, v33
	v_mov_b64_e32 v[160:161], v[178:179]
	v_mov_b64_e32 v[162:163], v[180:181]
	v_mov_b64_e32 v[164:165], v[182:183]
	v_mov_b64_e32 v[166:167], v[184:185]
	v_mov_b64_e32 v[168:169], v[186:187]
	v_mov_b64_e32 v[170:171], v[188:189]
	v_mov_b64_e32 v[172:173], v[190:191]
	v_mov_b64_e32 v[174:175], v[192:193]
	v_lshlrev_b32_e32 v15, 16, v8
	v_and_b32_e32 v8, 0xffff0000, v8
	v_lshlrev_b32_e32 v20, 16, v11
	v_and_b32_e32 v11, 0xffff0000, v11
	v_sub_f32_e32 v8, v8, v12
	v_lshlrev_b32_e32 v16, 16, v9
	v_sub_f32_e32 v15, v15, v12
	v_sub_f32_e32 v11, v11, v12
	v_mul_f32_e32 v8, v13, v8
	v_and_b32_e32 v9, 0xffff0000, v9
	v_sub_f32_e32 v16, v16, v12
	v_mul_f32_e32 v15, v13, v15
	v_mul_f32_e32 v11, v13, v11
	v_lshlrev_b32_e32 v18, 16, v10
	v_sub_f32_e32 v9, v9, v12
	v_mul_f32_e32 v16, v13, v16
	ds_write_b16 v155, v14 offset:36720
	v_and_b32_e32 v10, 0xffff0000, v10
	v_sub_f32_e32 v18, v18, v12
	v_mul_f32_e32 v9, v13, v9
	v_sub_f32_e32 v10, v10, v12
	v_mul_f32_e32 v18, v13, v18
	v_sub_f32_e32 v20, v20, v12
	v_mul_f32_e32 v10, v13, v10
	v_mul_f32_e32 v20, v13, v20
	v_lshlrev_b32_e32 v22, 16, v7
	v_and_b32_e32 v7, 0xffff0000, v7
	v_sub_f32_e32 v7, v7, v12
	v_mul_f32_e32 v7, v13, v7
	v_sub_f32_e32 v22, v22, v12
	v_mul_f32_e32 v22, v13, v22
	v_mov_b32_e32 v30, v64
	v_lshlrev_b32_e32 v28, 16, v0
	s_waitcnt vmcnt(2)
	v_fma_f32 v8, v8, v161, v165
	v_fma_f32 v14, v15, v160, v164
	s_waitcnt vmcnt(0)
	v_fmac_f32_e32 v175, v11, v171
	v_cvt_pk_bf16_f32 v11, v14, v33
	ds_write_b16 v155, v11 offset:43520
	v_cvt_pk_bf16_f32 v8, v8, v33
	v_fma_f32 v15, v16, v162, v166
	ds_write_b16 v155, v8 offset:43792
	v_cvt_pk_bf16_f32 v8, v15, v33
	v_fmac_f32_e32 v167, v9, v163
	ds_write_b16 v155, v8 offset:44064
	v_cvt_pk_bf16_f32 v8, v167, v33
	v_fma_f32 v9, v18, v168, v172
	ds_write_b16 v155, v8 offset:44336
	v_cvt_pk_bf16_f32 v8, v9, v33
	v_fma_f32 v10, v10, v169, v173
	ds_write_b16 v155, v8 offset:44608
	v_cvt_pk_bf16_f32 v8, v10, v33
	v_fma_f32 v16, v20, v170, v174
	ds_write_b16 v155, v8 offset:44880
	v_cvt_pk_bf16_f32 v8, v16, v33
	ds_write_b16 v155, v8 offset:45152
	v_cvt_pk_bf16_f32 v18, v175, v33
	v_mov_b64_e32 v[8:9], v[194:195]
	v_mov_b64_e32 v[10:11], v[196:197]
	v_mov_b64_e32 v[160:161], v[198:199]
	v_mov_b64_e32 v[162:163], v[200:201]
	v_mov_b64_e32 v[164:165], v[202:203]
	v_mov_b64_e32 v[166:167], v[204:205]
	v_mov_b64_e32 v[168:169], v[206:207]
	v_mov_b64_e32 v[170:171], v[208:209]
	v_pk_add_f32 v[14:15], v[66:67], v[66:67] op_sel:[0,1] op_sel_hi:[1,0]
	v_mul_f32_e32 v16, v53, v53
	v_mov_b32_e32 v50, v14
	v_pk_add_f32 v[14:15], v[14:15], v[64:65]
	v_pk_fma_f32 v[52:53], v[52:53], v[52:53], v[16:17] op_sel_hi:[1,1,0]
	v_lshlrev_b32_e32 v15, 16, v4
	v_and_b32_e32 v4, 0xffff0000, v4
	v_sub_f32_e32 v4, v4, v12
	v_lshlrev_b32_e32 v16, 16, v5
	v_sub_f32_e32 v15, v15, v12
	v_mul_f32_e32 v4, v13, v4
	v_and_b32_e32 v5, 0xffff0000, v5
	v_sub_f32_e32 v16, v16, v12
	v_mul_f32_e32 v15, v13, v15
	v_lshlrev_b32_e32 v20, 16, v6
	v_sub_f32_e32 v5, v5, v12
	v_mul_f32_e32 v16, v13, v16
	ds_write_b16 v155, v18 offset:45424
	v_and_b32_e32 v6, 0xffff0000, v6
	v_sub_f32_e32 v20, v20, v12
	v_mul_f32_e32 v5, v13, v5
	v_sub_f32_e32 v6, v6, v12
	v_mul_f32_e32 v20, v13, v20
	v_mul_f32_e32 v6, v13, v6
	v_mov_b32_e32 v172, v58
	v_mov_b32_e32 v173, v49
	v_pk_mul_f32 v[30:31], v[50:51], v[30:31]
	v_mov_b32_e32 v48, v52
	v_pk_add_f32 v[50:51], v[52:53], v[58:59]
	v_pk_add_f32 v[52:53], v[68:69], v[70:71]
	v_and_b32_e32 v68, 0xffff0000, v0
	v_lshlrev_b32_e32 v69, 16, v1
	v_and_b32_e32 v70, 0xffff0000, v1
	v_pk_mul_f32 v[0:1], v[78:79], v[78:79]
	v_lshlrev_b32_e32 v71, 16, v2
	v_pk_fma_f32 v[0:1], v[76:77], v[76:77], v[0:1]
	v_pk_mul_f32 v[58:59], v[98:99], v[98:99]
	v_pk_add_f32 v[0:1], v[0:1], v[0:1] op_sel:[0,1] op_sel_hi:[1,0]
	s_waitcnt vmcnt(2)
	v_fma_f32 v4, v4, v9, v161
	v_fma_f32 v8, v15, v8, v160
	s_waitcnt vmcnt(0)
	v_fmac_f32_e32 v171, v7, v167
	v_cvt_pk_bf16_f32 v7, v8, v33
	ds_write_b16 v155, v7 offset:52224
	v_cvt_pk_bf16_f32 v4, v4, v33
	v_fma_f32 v9, v16, v10, v162
	ds_write_b16 v155, v4 offset:52496
	v_cvt_pk_bf16_f32 v4, v9, v33
	v_fmac_f32_e32 v163, v5, v11
	ds_write_b16 v155, v4 offset:52768
	v_cvt_pk_bf16_f32 v4, v163, v33
	v_fma_f32 v5, v20, v164, v168
	ds_write_b16 v155, v4 offset:53040
	v_cvt_pk_bf16_f32 v4, v5, v33
	v_fma_f32 v6, v6, v165, v169
	ds_write_b16 v155, v4 offset:53312
	v_cvt_pk_bf16_f32 v4, v6, v33
	v_fma_f32 v10, v22, v166, v170
	ds_write_b16 v155, v4 offset:53584
	v_cvt_pk_bf16_f32 v4, v10, v33
	ds_write_b16 v155, v4 offset:53856
	v_cvt_pk_bf16_f32 v18, v171, v33
	v_mov_b64_e32 v[4:5], v[210:211]
	v_mov_b64_e32 v[6:7], v[212:213]
	v_mov_b64_e32 v[8:9], v[214:215]
	v_mov_b64_e32 v[10:11], v[216:217]
	v_mov_b64_e32 v[60:61], v[218:219]
	v_mov_b64_e32 v[62:63], v[220:221]
	v_mov_b64_e32 v[64:65], v[238:239]
	v_mov_b64_e32 v[66:67], v[240:241]
	v_mov_b32_e32 v15, v31
	v_pk_mul_f32 v[30:31], v[48:49], v[172:173]
	v_mov_b32_e32 v2, v0
	v_mov_b32_e32 v51, v31
	v_pk_add_f32 v[14:15], v[14:15], v[50:51]
	v_mul_f32_e32 v16, v81, v81
	v_pk_add_f32 v[14:15], v[14:15], v[52:53]
	v_pk_fma_f32 v[30:31], v[80:81], v[80:81], v[16:17] op_sel_hi:[1,1,0]
	v_pk_add_f32 v[14:15], v[14:15], v[14:15] op_sel:[0,1] op_sel_hi:[1,0]
	v_mov_b32_e32 v92, v30
	v_mov_b32_e32 v94, v14
	v_pk_add_f32 v[0:1], v[14:15], v[0:1]
	v_mul_f32_e32 v14, v83, v83
	v_pk_fma_f32 v[14:15], v[82:83], v[82:83], v[14:15] op_sel_hi:[1,1,0]
	v_mov_b32_e32 v49, v93
	v_mov_b32_e32 v48, v14
	v_pk_add_f32 v[14:15], v[30:31], v[14:15]
	v_pk_fma_f32 v[30:31], v[86:87], v[88:89], v[96:97]
	v_pk_mul_f32 v[50:51], v[96:97], v[96:97]
	v_pk_fma_f32 v[52:53], v[84:85], v[90:91], v[98:99]
	v_pk_mul_f32 v[2:3], v[94:95], v[2:3]
	v_pk_mul_f32 v[48:49], v[92:93], v[48:49]
	v_mov_b32_e32 v31, v51
	v_mov_b32_e32 v53, v59
	v_mov_b32_e32 v1, v3
	v_mov_b32_e32 v15, v49
	v_pk_add_f32 v[2:3], v[30:31], v[52:53]
	v_pk_add_f32 v[0:1], v[0:1], v[14:15]
	ds_write_b16 v155, v18 offset:54128
	v_pk_add_f32 v[50:51], v[0:1], v[2:3]
	v_pk_mul_f32 v[0:1], v[102:103], v[102:103]
	v_sub_f32_e32 v2, v69, v12
	v_pk_fma_f32 v[0:1], v[100:101], v[100:101], v[0:1]
	v_sub_f32_e32 v3, v70, v12
	v_pk_add_f32 v[48:49], v[0:1], v[0:1] op_sel:[0,1] op_sel_hi:[1,0]
	v_mul_f32_e32 v0, v105, v105
	v_pk_fma_f32 v[30:31], v[104:105], v[104:105], v[0:1] op_sel_hi:[1,1,0]
	v_sub_f32_e32 v0, v28, v12
	v_mul_f32_e32 v0, v13, v0
	v_sub_f32_e32 v1, v68, v12
	v_mul_f32_e32 v1, v13, v1
	v_mul_f32_e32 v2, v13, v2
	v_sub_f32_e32 v14, v71, v12
	v_mul_f32_e32 v3, v13, v3
	v_sub_f32_e32 v15, v72, v12
	v_mul_f32_e32 v14, v13, v14
	v_sub_f32_e32 v16, v73, v12
	v_mul_f32_e32 v15, v13, v15
	v_sub_f32_e32 v12, v74, v12
	v_mul_f32_e32 v16, v13, v16
	v_mul_f32_e32 v12, v13, v12
	v_mov_b32_e32 v20, v56
	v_mov_b32_e32 v22, v54
	s_waitcnt vmcnt(2)
	v_fma_f32 v0, v0, v4, v8
	v_cvt_pk_bf16_f32 v0, v0, v33
	v_fma_f32 v1, v1, v5, v9
	ds_write_b16 v155, v0 offset:60928
	v_cvt_pk_bf16_f32 v0, v1, v33
	v_fma_f32 v2, v2, v6, v10
	ds_write_b16 v155, v0 offset:61200
	v_cvt_pk_bf16_f32 v0, v2, v33
	v_fmac_f32_e32 v11, v3, v7
	ds_write_b16 v155, v0 offset:61472
	v_cvt_pk_bf16_f32 v0, v11, v33
	s_waitcnt vmcnt(0)
	v_fma_f32 v3, v14, v60, v64
	ds_write_b16 v155, v0 offset:61744
	v_cvt_pk_bf16_f32 v0, v3, v33
	v_fma_f32 v4, v15, v61, v65
	ds_write_b16 v155, v0 offset:62016
	v_cvt_pk_bf16_f32 v0, v4, v33
	v_fma_f32 v5, v16, v62, v66
	ds_write_b16 v155, v0 offset:62288
	v_cvt_pk_bf16_f32 v0, v5, v33
	v_fmac_f32_e32 v67, v12, v63
	ds_write_b16 v155, v0 offset:62560
	v_cvt_pk_bf16_f32 v0, v67, v33
	ds_write_b16 v155, v0 offset:62832
	s_waitcnt lgkmcnt(0)
	s_barrier
	v_add_co_u32_e32 v4, vcc, s28, v42
	v_pk_fma_f32 v[56:57], v[56:57], v[20:21], v[26:27]
	s_nop 0
	v_addc_co_u32_e32 v5, vcc, 0, v43, vcc
	global_load_dwordx2 v[224:225], v[40:41], off offset:1824
	global_load_dwordx2 v[226:227], v[40:41], off offset:1856
	global_load_dwordx2 v[228:229], v[40:41], off offset:1888
	global_load_dwordx2 v[230:231], v[40:41], off offset:1920
	global_load_dwordx2 v[232:233], v[40:41], off offset:1952
	global_load_dwordx2 v[234:235], v[40:41], off offset:1984
	global_load_dwordx2 v[236:237], v[40:41], off offset:2016
	global_load_dwordx4 v[8:11], v[4:5], off
	global_load_dwordx4 v[0:3], v[4:5], off offset:64
	global_load_dwordx2 v[52:53], v[40:41], off offset:1792
	global_load_dwordx4 v[12:15], v[4:5], off offset:128
	s_nop 0
	global_load_dwordx4 v[4:7], v[4:5], off offset:192
	s_nop 0
	global_load_dword v28, v[44:45], off offset:1536
	ds_read_b128 v[42:45], v152 offset:34816
	ds_read_b128 v[58:61], v152 offset:34880
	ds_read_b128 v[62:65], v152 offset:34944
	v_pk_fma_f32 v[54:55], v[54:55], v[22:23], v[24:25]
	v_pk_mul_f32 v[24:25], v[24:25], v[24:25]
	v_pk_mul_f32 v[26:27], v[26:27], v[26:27]
	v_pk_add_f32 v[50:51], v[50:51], v[50:51] op_sel:[0,1] op_sel_hi:[1,0]
	v_mov_b32_e32 v168, v48
	v_mov_b32_e32 v169, v19
	v_mov_b32_e32 v170, v30
	v_mov_b32_e32 v171, v17
	s_waitcnt vmcnt(5) lgkmcnt(2)
	v_mfma_f32_16x16x32_bf16 v[42:45], v[42:45], v[8:11], 0
	s_waitcnt vmcnt(3)
	v_lshlrev_b32_e32 v67, 16, v53
	v_lshlrev_b32_e32 v66, 16, v52
	s_waitcnt lgkmcnt(1)
	v_mfma_f32_16x16x32_bf16 v[42:45], v[58:61], v[0:3], v[42:45]
	ds_read_b128 v[58:61], v152 offset:35008
	v_and_b32_e32 v53, 0xffff0000, v53
	v_and_b32_e32 v52, 0xffff0000, v52
	s_waitcnt vmcnt(2) lgkmcnt(1)
	v_mfma_f32_16x16x32_bf16 v[42:45], v[62:65], v[12:15], v[42:45]
	s_waitcnt vmcnt(1) lgkmcnt(0)
	v_mfma_f32_16x16x32_bf16 v[42:45], v[58:61], v[4:7], v[42:45]
	s_nop 7
	v_mov_b32_e32 v58, v42
	v_mov_b32_e32 v59, v44
	v_mov_b32_e32 v44, v43
	s_waitcnt vmcnt(0)
	v_pk_add_f32 v[42:43], v[28:29], v[58:59] op_sel_hi:[0,1]
	v_pk_add_f32 v[44:45], v[28:29], v[44:45] op_sel_hi:[0,1]
	v_pk_mul_f32 v[42:43], v[42:43], v[66:67]
	v_pk_mul_f32 v[44:45], v[44:45], v[52:53]
	s_nop 0
	v_cvt_pk_bf16_f32 v77, v42, v44
	v_cvt_pk_bf16_f32 v76, v43, v45
	ds_read_b128 v[58:61], v152 offset:39168
	ds_read_b128 v[62:65], v152 offset:39232
	s_waitcnt lgkmcnt(1)
	v_mfma_f32_16x16x32_bf16 v[58:61], v[58:61], v[8:11], 0
	s_waitcnt lgkmcnt(0)
	v_mfma_f32_16x16x32_bf16 v[58:61], v[62:65], v[0:3], v[58:61]
	ds_read_b128 v[62:65], v152 offset:39296
	ds_read_b128 v[66:69], v152 offset:39360
	v_mov_b64_e32 v[52:53], v[224:225]
	s_waitcnt lgkmcnt(1)
	v_mfma_f32_16x16x32_bf16 v[58:61], v[62:65], v[12:15], v[58:61]
	s_waitcnt vmcnt(0)
	v_lshlrev_b32_e32 v62, 16, v52
	s_waitcnt lgkmcnt(0)
	v_mfma_f32_16x16x32_bf16 v[58:61], v[66:69], v[4:7], v[58:61]
	v_and_b32_e32 v63, 0xffff0000, v52
	v_lshlrev_b32_e32 v64, 16, v53
	v_and_b32_e32 v65, 0xffff0000, v53
	s_nop 4
	v_pk_add_f32 v[58:59], v[28:29], v[58:59] op_sel_hi:[0,1]
	v_pk_add_f32 v[60:61], v[28:29], v[60:61] op_sel_hi:[0,1]
	v_pk_mul_f32 v[52:53], v[58:59], v[62:63]
	v_pk_mul_f32 v[58:59], v[60:61], v[64:65]
	v_cvt_pk_bf16_f32 v75, v52, v53
	s_nop 0
	v_cvt_pk_bf16_f32 v74, v58, v59
	ds_read_b128 v[60:63], v152 offset:43520
	ds_read_b128 v[64:67], v152 offset:43584
	s_waitcnt lgkmcnt(1)
	v_mfma_f32_16x16x32_bf16 v[60:63], v[60:63], v[8:11], 0
	s_waitcnt lgkmcnt(0)
	v_mfma_f32_16x16x32_bf16 v[60:63], v[64:67], v[0:3], v[60:63]
	ds_read_b128 v[64:67], v152 offset:43648
	ds_read_b128 v[68:71], v152 offset:43712
	s_waitcnt lgkmcnt(1)
	v_mfma_f32_16x16x32_bf16 v[60:63], v[64:67], v[12:15], v[60:63]
	v_mov_b64_e32 v[64:65], v[226:227]
	s_waitcnt vmcnt(0)
	v_lshlrev_b32_e32 v66, 16, v65
	s_waitcnt lgkmcnt(0)
	v_mfma_f32_16x16x32_bf16 v[60:63], v[68:71], v[4:7], v[60:63]
	v_and_b32_e32 v65, 0xffff0000, v65
	s_nop 6
	v_add_f32_e32 v16, v28, v60
	v_add_f32_e32 v18, v28, v61
	v_add_f32_e32 v60, v28, v62
	v_add_f32_e32 v61, v28, v63
	v_lshlrev_b32_e32 v62, 16, v64
	v_and_b32_e32 v63, 0xffff0000, v64
	v_mul_f32_e32 v64, v16, v62
	v_mul_f32_e32 v62, v18, v63
	v_mul_f32_e32 v66, v60, v66
	v_mul_f32_e32 v60, v61, v65
	v_cvt_pk_bf16_f32 v73, v64, v62
	v_cvt_pk_bf16_f32 v72, v66, v60
	ds_read_b128 v[68:71], v152 offset:47872
	ds_read_b128 v[78:81], v152 offset:47936
	s_waitcnt lgkmcnt(1)
	v_mfma_f32_16x16x32_bf16 v[68:71], v[68:71], v[8:11], 0
	v_mov_b32_e32 v94, v64
	v_mov_b32_e32 v96, v66
	s_waitcnt lgkmcnt(0)
	v_mfma_f32_16x16x32_bf16 v[68:71], v[78:81], v[0:3], v[68:71]
	ds_read_b128 v[78:81], v152 offset:48000
	ds_read_b128 v[82:85], v152 offset:48064
	s_waitcnt lgkmcnt(1)
	v_mfma_f32_16x16x32_bf16 v[68:71], v[78:81], v[12:15], v[68:71]
	v_mov_b64_e32 v[78:79], v[228:229]
	s_waitcnt vmcnt(0)
	v_lshlrev_b32_e32 v61, 16, v78
	s_waitcnt lgkmcnt(0)
	v_mfma_f32_16x16x32_bf16 v[68:71], v[82:85], v[4:7], v[68:71]
	v_and_b32_e32 v63, 0xffff0000, v78
	v_lshlrev_b32_e32 v95, 16, v79
	v_and_b32_e32 v97, 0xffff0000, v79
	s_nop 4
	v_add_f32_e32 v16, v28, v68
	v_add_f32_e32 v18, v28, v69
	v_add_f32_e32 v65, v28, v70
	v_add_f32_e32 v67, v28, v71
	v_mul_f32_e32 v99, v16, v61
	v_mul_f32_e32 v101, v18, v63
	v_pk_mul_f32 v[102:103], v[64:65], v[94:95]
	v_pk_mul_f32 v[104:105], v[66:67], v[96:97]
	v_cvt_pk_bf16_f32 v71, v99, v101
	v_mul_f32_e32 v16, v47, v47
	v_cvt_pk_bf16_f32 v69, v103, v105
	ds_read_b128 v[78:81], v152 offset:52224
	ds_read_b128 v[82:85], v152 offset:52288
	s_waitcnt lgkmcnt(1)
	v_mfma_f32_16x16x32_bf16 v[78:81], v[78:81], v[8:11], 0
	v_mov_b32_e32 v18, v50
	v_pk_mul_f32 v[18:19], v[18:19], v[168:169]
	v_mov_b32_e32 v63, v65
	s_waitcnt lgkmcnt(0)
	v_mfma_f32_16x16x32_bf16 v[78:81], v[82:85], v[0:3], v[78:81]
	ds_read_b128 v[82:85], v152 offset:52352
	ds_read_b128 v[86:89], v152 offset:52416
	v_mov_b32_e32 v94, v62
	v_mov_b32_e32 v96, v60
	s_waitcnt lgkmcnt(1)
	v_mfma_f32_16x16x32_bf16 v[78:81], v[82:85], v[12:15], v[78:81]
	v_mov_b64_e32 v[82:83], v[230:231]
	s_waitcnt lgkmcnt(0)
	v_mfma_f32_16x16x32_bf16 v[78:81], v[86:89], v[4:7], v[78:81]
	s_nop 7
	v_mov_b32_e32 v84, v78
	v_mov_b32_e32 v85, v80
	v_mov_b32_e32 v80, v79
	v_pk_add_f32 v[78:79], v[28:29], v[84:85] op_sel_hi:[0,1]
	v_pk_add_f32 v[80:81], v[28:29], v[80:81] op_sel_hi:[0,1]
	s_waitcnt vmcnt(0)
	v_lshlrev_b32_e32 v85, 16, v83
	v_lshlrev_b32_e32 v84, 16, v82
	v_and_b32_e32 v83, 0xffff0000, v83
	v_and_b32_e32 v82, 0xffff0000, v82
	v_pk_mul_f32 v[108:109], v[78:79], v[84:85]
	v_pk_mul_f32 v[160:161], v[80:81], v[82:83]
	s_nop 0
	v_cvt_pk_bf16_f32 v70, v108, v160
	v_cvt_pk_bf16_f32 v68, v109, v161
	ds_read_b128 v[78:81], v152 offset:56576
	ds_read_b128 v[82:85], v152 offset:56640
	s_waitcnt lgkmcnt(1)
	v_mfma_f32_16x16x32_bf16 v[78:81], v[78:81], v[8:11], 0
	s_waitcnt lgkmcnt(0)
	v_mfma_f32_16x16x32_bf16 v[78:81], v[82:85], v[0:3], v[78:81]
	ds_read_b128 v[82:85], v152 offset:56704
	ds_read_b128 v[86:89], v152 offset:56768
	s_waitcnt lgkmcnt(1)
	v_mfma_f32_16x16x32_bf16 v[78:81], v[82:85], v[12:15], v[78:81]
	v_mov_b64_e32 v[82:83], v[232:233]
	s_waitcnt vmcnt(0)
	v_lshlrev_b32_e32 v84, 16, v82
	s_waitcnt lgkmcnt(0)
	v_mfma_f32_16x16x32_bf16 v[78:81], v[86:89], v[4:7], v[78:81]
	v_and_b32_e32 v85, 0xffff0000, v82
	v_lshlrev_b32_e32 v82, 16, v83
	v_and_b32_e32 v83, 0xffff0000, v83
	s_nop 4
	v_pk_add_f32 v[78:79], v[28:29], v[78:79] op_sel_hi:[0,1]
	v_pk_add_f32 v[80:81], v[28:29], v[80:81] op_sel_hi:[0,1]
	v_pk_mul_f32 v[162:163], v[78:79], v[84:85]
	v_pk_mul_f32 v[164:165], v[80:81], v[82:83]
	v_cvt_pk_bf16_f32 v66, v162, v163
	s_nop 0
	v_cvt_pk_bf16_f32 v64, v164, v165
	v_mov_b64_e32 v[166:167], v[234:235]
	ds_read_b128 v[78:81], v152 offset:60928
	ds_read_b128 v[82:85], v152 offset:60992
	ds_read_b128 v[86:89], v152 offset:61056
	ds_read_b128 v[90:93], v152 offset:61120
	s_waitcnt lgkmcnt(3)
	v_mfma_f32_16x16x32_bf16 v[78:81], v[78:81], v[8:11], 0
	s_waitcnt vmcnt(0)
	v_lshlrev_b32_e32 v24, 16, v166
	s_waitcnt lgkmcnt(2)
	v_mfma_f32_16x16x32_bf16 v[78:81], v[82:85], v[0:3], v[78:81]
	v_and_b32_e32 v55, 0xffff0000, v166
	v_lshlrev_b32_e32 v57, 16, v167
	v_and_b32_e32 v61, 0xffff0000, v167
	s_waitcnt lgkmcnt(1)
	v_mfma_f32_16x16x32_bf16 v[78:81], v[86:89], v[12:15], v[78:81]
	s_waitcnt lgkmcnt(0)
	v_mfma_f32_16x16x32_bf16 v[20:23], v[90:93], v[4:7], v[78:81]
	s_nop 7
	v_add_f32_e32 v20, v28, v20
	v_add_f32_e32 v21, v28, v21
	v_add_f32_e32 v22, v28, v22
	v_add_f32_e32 v23, v28, v23
	v_mul_f32_e32 v26, v20, v24
	v_mul_f32_e32 v78, v21, v55
	v_mul_f32_e32 v80, v22, v57
	v_mul_f32_e32 v82, v23, v61
	v_cvt_pk_bf16_f32 v21, v26, v78
	v_cvt_pk_bf16_f32 v20, v80, v82
	v_mov_b64_e32 v[84:85], v[236:237]
	v_pk_fma_f32 v[40:41], v[46:47], v[46:47], v[16:17] op_sel_hi:[1,1,0]
	v_pk_add_f32 v[22:23], v[50:51], v[48:49]
	v_mov_b32_e32 v16, v40
	v_mov_b32_e32 v55, v25
	v_pk_add_f32 v[24:25], v[40:41], v[30:31]
	v_pk_mul_f32 v[16:17], v[16:17], v[170:171]
	v_mov_b32_e32 v57, v27
	v_mov_b32_e32 v23, v19
	v_mov_b32_e32 v25, v17
	v_pk_add_f32 v[30:31], v[56:57], v[54:55]
	v_pk_add_f32 v[16:17], v[22:23], v[24:25]
	v_pk_mul_f32 v[18:19], v[44:45], v[44:45]
	v_pk_add_f32 v[16:17], v[16:17], v[30:31]
	v_pk_fma_f32 v[18:19], v[42:43], v[42:43], v[18:19]
	v_pk_add_f32 v[16:17], v[16:17], v[16:17] op_sel:[0,1] op_sel_hi:[1,0]
	v_pk_add_f32 v[18:19], v[18:19], v[18:19] op_sel:[0,1] op_sel_hi:[1,0]
	v_mov_b32_e32 v98, v16
	v_mov_b32_e32 v22, v18
	v_pk_add_f32 v[16:17], v[16:17], v[18:19]
	v_mul_f32_e32 v18, v59, v59
	v_mul_f32_e32 v24, v53, v53
	v_pk_fma_f32 v[18:19], v[58:59], v[58:59], v[18:19] op_sel_hi:[1,1,0]
	v_pk_fma_f32 v[24:25], v[52:53], v[52:53], v[24:25] op_sel_hi:[1,1,0]
	v_mov_b32_e32 v30, v18
	v_mov_b32_e32 v100, v24
	v_mov_b32_e32 v61, v67
	v_mov_b32_e32 v23, v99
	v_mov_b32_e32 v31, v101
	v_pk_add_f32 v[18:19], v[24:25], v[18:19]
	v_pk_fma_f32 v[24:25], v[62:63], v[94:95], v[102:103]
	v_pk_mul_f32 v[40:41], v[102:103], v[102:103]
	v_pk_fma_f32 v[42:43], v[60:61], v[96:97], v[104:105]
	v_pk_mul_f32 v[44:45], v[104:105], v[104:105]
	v_pk_mul_f32 v[22:23], v[98:99], v[22:23]
	v_pk_mul_f32 v[30:31], v[100:101], v[30:31]
	v_mov_b32_e32 v25, v41
	v_mov_b32_e32 v43, v45
	v_mov_b32_e32 v17, v23
	v_mov_b32_e32 v19, v31
	v_pk_add_f32 v[22:23], v[24:25], v[42:43]
	v_pk_add_f32 v[16:17], v[16:17], v[18:19]
	v_mul_f32_e32 v48, v165, v165
	v_pk_add_f32 v[16:17], v[16:17], v[22:23]
	v_pk_mul_f32 v[22:23], v[160:161], v[160:161]
	v_pk_add_f32 v[30:31], v[16:17], v[16:17] op_sel:[0,1] op_sel_hi:[1,0]
	ds_read_b128 v[16:19], v152 offset:65280
	v_pk_fma_f32 v[22:23], v[108:109], v[108:109], v[22:23]
	v_mov_b32_e32 v44, v30
	v_pk_add_f32 v[40:41], v[22:23], v[22:23] op_sel:[0,1] op_sel_hi:[1,0]
	ds_read_b128 v[22:25], v152 offset:65344
	v_mov_b32_e32 v46, v40
	v_pk_add_f32 v[30:31], v[30:31], v[40:41]
	ds_read_b128 v[40:43], v152 offset:65408
	s_waitcnt lgkmcnt(2)
	v_mfma_f32_16x16x32_bf16 v[8:11], v[16:19], v[8:11], 0
	ds_read_b128 v[16:19], v152 offset:65472
	v_mul_f32_e32 v50, v163, v163
	v_pk_fma_f32 v[48:49], v[164:165], v[164:165], v[48:49] op_sel_hi:[1,1,0]
	s_waitcnt lgkmcnt(2)
	v_mfma_f32_16x16x32_bf16 v[0:3], v[22:25], v[0:3], v[8:11]
	v_mov_b32_e32 v22, v48
	s_waitcnt lgkmcnt(1)
	v_mfma_f32_16x16x32_bf16 v[0:3], v[40:43], v[12:15], v[0:3]
	v_fma_f32 v8, v162, v162, v50
	v_fma_f32 v9, v163, v163, v50
	v_mov_b32_e32 v12, v26
	v_mov_b32_e32 v14, v80
	s_waitcnt lgkmcnt(0)
	v_mfma_f32_16x16x32_bf16 v[0:3], v[16:19], v[4:7], v[0:3]
	v_mov_b32_e32 v10, v8
	v_pk_add_f32 v[8:9], v[8:9], v[48:49]
	s_waitcnt vmcnt(0)
	v_lshlrev_b32_e32 v13, 16, v85
	s_nop 3
	v_add_f32_e32 v0, v28, v0
	v_add_f32_e32 v1, v28, v1
	v_add_f32_e32 v27, v28, v2
	v_add_f32_e32 v81, v28, v3
	v_lshlrev_b32_e32 v2, 16, v84
	v_and_b32_e32 v3, 0xffff0000, v84
	v_and_b32_e32 v15, 0xffff0000, v85
	v_mul_f32_e32 v45, v0, v2
	v_mul_f32_e32 v11, v1, v3
	v_mov_b32_e32 v79, v27
	v_mov_b32_e32 v83, v81
	v_pk_mul_f32 v[0:1], v[26:27], v[12:13]
	v_mov_b32_e32 v12, v78
	v_pk_mul_f32 v[2:3], v[80:81], v[14:15]
	v_mov_b32_e32 v14, v82
	v_mov_b32_e32 v47, v45
	v_mov_b32_e32 v23, v11
	v_cvt_pk_bf16_f32 v7, v45, v11
	v_cvt_pk_bf16_f32 v6, v1, v3
	v_pk_fma_f32 v[4:5], v[78:79], v[12:13], v[0:1]
	v_pk_mul_f32 v[0:1], v[0:1], v[0:1]
	v_pk_fma_f32 v[12:13], v[82:83], v[14:15], v[2:3]
	v_pk_mul_f32 v[2:3], v[2:3], v[2:3]
	v_pk_mul_f32 v[14:15], v[44:45], v[46:47]
	v_pk_mul_f32 v[10:11], v[10:11], v[22:23]
	v_mov_b32_e32 v5, v1
	v_mov_b32_e32 v13, v3
	v_mov_b32_e32 v31, v15
	v_mov_b32_e32 v9, v11
	v_pk_add_f32 v[0:1], v[4:5], v[12:13]
	v_pk_add_f32 v[2:3], v[30:31], v[8:9]
	s_nop 0
	v_pk_add_f32 v[0:1], v[2:3], v[0:1]
	s_barrier
	v_add_f32_e32 v8, v0, v1
	v_lshl_add_u64 v[4:5], v[38:39], 0, s[10:11]
	v_lshl_add_u64 v[0:1], v[4:5], 0, v[32:33]
	global_load_dwordx2 v[0:1], v[0:1], off
	v_or_b32_e32 v160, 0x20, v32
	v_mov_b32_e32 v161, v33
	v_lshl_add_u64 v[160:161], v[4:5], 0, v[160:161]
	global_load_dwordx2 v[160:161], v[160:161], off
	v_or_b32_e32 v162, 0x40, v32
	v_mov_b32_e32 v163, v33
	v_lshl_add_u64 v[162:163], v[4:5], 0, v[162:163]
	global_load_dwordx2 v[162:163], v[162:163], off
	v_or_b32_e32 v164, 0x60, v32
	v_mov_b32_e32 v165, v33
	v_lshl_add_u64 v[164:165], v[4:5], 0, v[164:165]
	global_load_dwordx2 v[164:165], v[164:165], off
	v_or_b32_e32 v166, 0x80, v32
	v_mov_b32_e32 v167, v33
	v_lshl_add_u64 v[166:167], v[4:5], 0, v[166:167]
	global_load_dwordx2 v[166:167], v[166:167], off
	v_or_b32_e32 v168, 0xa0, v32
	v_mov_b32_e32 v169, v33
	v_lshl_add_u64 v[168:169], v[4:5], 0, v[168:169]
	global_load_dwordx2 v[168:169], v[168:169], off
	v_or_b32_e32 v170, 0xc0, v32
	v_mov_b32_e32 v171, v33
	v_lshl_add_u64 v[170:171], v[4:5], 0, v[170:171]
	global_load_dwordx2 v[170:171], v[170:171], off
	v_or_b32_e32 v172, 0xe0, v32
	v_mov_b32_e32 v173, v33
	v_lshl_add_u64 v[172:173], v[4:5], 0, v[172:173]
	global_load_dwordx2 v[172:173], v[172:173], off
	v_or_b32_e32 v174, 0x100, v32
	v_mov_b32_e32 v175, v33
	v_lshl_add_u64 v[174:175], v[4:5], 0, v[174:175]
	global_load_dwordx2 v[174:175], v[174:175], off
	v_or_b32_e32 v176, 0x120, v32
	v_mov_b32_e32 v177, v33
	v_lshl_add_u64 v[176:177], v[4:5], 0, v[176:177]
	global_load_dwordx2 v[176:177], v[176:177], off
	v_or_b32_e32 v178, 0x140, v32
	v_mov_b32_e32 v179, v33
	v_lshl_add_u64 v[178:179], v[4:5], 0, v[178:179]
	global_load_dwordx2 v[178:179], v[178:179], off
	v_or_b32_e32 v180, 0x160, v32
	v_mov_b32_e32 v181, v33
	v_lshl_add_u64 v[180:181], v[4:5], 0, v[180:181]
	global_load_dwordx2 v[180:181], v[180:181], off
	v_or_b32_e32 v182, 0x180, v32
	v_mov_b32_e32 v183, v33
	v_lshl_add_u64 v[182:183], v[4:5], 0, v[182:183]
	global_load_dwordx2 v[182:183], v[182:183], off
	v_or_b32_e32 v184, 0x1a0, v32
	v_mov_b32_e32 v185, v33
	v_lshl_add_u64 v[184:185], v[4:5], 0, v[184:185]
	global_load_dwordx2 v[184:185], v[184:185], off
	v_or_b32_e32 v186, 0x1c0, v32
	v_mov_b32_e32 v187, v33
	v_lshl_add_u64 v[186:187], v[4:5], 0, v[186:187]
	global_load_dwordx2 v[186:187], v[186:187], off
	v_or_b32_e32 v188, 0x1e0, v32
	v_mov_b32_e32 v189, v33
	v_lshl_add_u64 v[188:189], v[4:5], 0, v[188:189]
	global_load_dwordx2 v[188:189], v[188:189], off
	v_or_b32_e32 v190, 0x200, v32
	v_mov_b32_e32 v191, v33
	v_lshl_add_u64 v[190:191], v[4:5], 0, v[190:191]
	global_load_dwordx2 v[190:191], v[190:191], off
	v_or_b32_e32 v192, 0x220, v32
	v_mov_b32_e32 v193, v33
	v_lshl_add_u64 v[192:193], v[4:5], 0, v[192:193]
	global_load_dwordx2 v[192:193], v[192:193], off
	v_or_b32_e32 v194, 0x240, v32
	v_mov_b32_e32 v195, v33
	v_lshl_add_u64 v[194:195], v[4:5], 0, v[194:195]
	global_load_dwordx2 v[194:195], v[194:195], off
	v_or_b32_e32 v196, 0x260, v32
	v_mov_b32_e32 v197, v33
	v_lshl_add_u64 v[196:197], v[4:5], 0, v[196:197]
	global_load_dwordx2 v[196:197], v[196:197], off
	v_or_b32_e32 v198, 0x280, v32
	v_mov_b32_e32 v199, v33
	v_lshl_add_u64 v[198:199], v[4:5], 0, v[198:199]
	global_load_dwordx2 v[198:199], v[198:199], off
	v_or_b32_e32 v200, 0x2a0, v32
	v_mov_b32_e32 v201, v33
	v_lshl_add_u64 v[200:201], v[4:5], 0, v[200:201]
	global_load_dwordx2 v[200:201], v[200:201], off
	v_or_b32_e32 v202, 0x2c0, v32
	v_mov_b32_e32 v203, v33
	v_lshl_add_u64 v[202:203], v[4:5], 0, v[202:203]
	global_load_dwordx2 v[202:203], v[202:203], off
	v_or_b32_e32 v204, 0x2e0, v32
	v_mov_b32_e32 v205, v33
	v_lshl_add_u64 v[204:205], v[4:5], 0, v[204:205]
	global_load_dwordx2 v[204:205], v[204:205], off
	v_or_b32_e32 v206, 0x300, v32
	v_mov_b32_e32 v207, v33
	v_lshl_add_u64 v[206:207], v[4:5], 0, v[206:207]
	global_load_dwordx2 v[206:207], v[206:207], off
	v_or_b32_e32 v208, 0x320, v32
	v_mov_b32_e32 v209, v33
	v_lshl_add_u64 v[208:209], v[4:5], 0, v[208:209]
	global_load_dwordx2 v[208:209], v[208:209], off
	v_or_b32_e32 v210, 0x340, v32
	v_mov_b32_e32 v211, v33
	v_lshl_add_u64 v[210:211], v[4:5], 0, v[210:211]
	global_load_dwordx2 v[210:211], v[210:211], off
	v_or_b32_e32 v212, 0x360, v32
	v_mov_b32_e32 v213, v33
	v_lshl_add_u64 v[212:213], v[4:5], 0, v[212:213]
	global_load_dwordx2 v[212:213], v[212:213], off
	v_or_b32_e32 v214, 0x380, v32
	v_mov_b32_e32 v215, v33
	v_lshl_add_u64 v[214:215], v[4:5], 0, v[214:215]
	global_load_dwordx2 v[214:215], v[214:215], off
	v_or_b32_e32 v216, 0x3a0, v32
	v_mov_b32_e32 v217, v33
	v_lshl_add_u64 v[216:217], v[4:5], 0, v[216:217]
	global_load_dwordx2 v[216:217], v[216:217], off
	v_or_b32_e32 v218, 0x3c0, v32
	v_mov_b32_e32 v219, v33
	v_lshl_add_u64 v[218:219], v[4:5], 0, v[218:219]
	global_load_dwordx2 v[218:219], v[218:219], off
	v_or_b32_e32 v220, 0x3e0, v32
	v_mov_b32_e32 v221, v33
	v_lshl_add_u64 v[220:221], v[4:5], 0, v[220:221]
	global_load_dwordx2 v[220:221], v[220:221], off
	v_lshlrev_b64 v[2:3], 11, v[36:37]
	v_lshl_add_u64 v[18:19], s[86:87], 0, v[2:3]
	v_lshlrev_b32_e32 v9, 16, v150
	v_and_b32_e32 v11, 0xffff0000, v150
	s_waitcnt lgkmcnt(0)
	v_mov_b32_e32 v10, v8
	s_nop 1
	v_permlane16_swap_b32_e32 v8, v10
	v_add_f32_e32 v8, v8, v10
	v_mov_b32_e32 v10, v8
	s_nop 1
	v_permlane32_swap_b32_e32 v8, v10
	v_add_f32_e32 v8, v8, v10
	v_fmamk_f32 v8, v8, 0x3b000000, v124
	v_mul_f32_e32 v10, 0x4b800000, v8
	v_cmp_gt_f32_e32 vcc, s3, v8
	v_lshlrev_b32_e32 v13, 16, v148
	v_and_b32_e32 v15, 0xffff0000, v148
	v_cndmask_b32_e32 v8, v8, v10, vcc
	v_rsq_f32_e32 v8, v8
	v_or_b32_e32 v16, 32, v32
	v_mov_b32_e32 v17, v33
	v_lshl_add_u64 v[16:17], v[4:5], 0, v[16:17]
	v_mul_f32_e32 v2, 0x45800000, v8
	v_cndmask_b32_e32 v3, v8, v2, vcc
	v_mov_b32_e32 v24, v3
	v_mov_b32_e32 v26, v3
	v_mov_b32_e32 v30, v3
	s_add_i32 s54, s54, s52
	s_add_u32 s4, s4, s6
	s_addc_u32 s5, s5, s7
	s_cmpk_gt_i32 s54, 0xff
	s_waitcnt vmcnt(0)
	v_lshlrev_b32_e32 v8, 16, v0
	v_and_b32_e32 v10, 0xffff0000, v0
	v_mul_f32_e32 v0, 0xbfb8aa3b, v8
	v_exp_f32_e32 v0, v0
	v_lshlrev_b32_e32 v12, 16, v1
	v_and_b32_e32 v14, 0xffff0000, v1
	v_mul_f32_e32 v1, 0xbfb8aa3b, v10
	v_exp_f32_e32 v1, v1
	v_add_f32_e32 v0, 1.0, v0
	v_rcp_f32_e32 v2, v0
	v_mul_f32_e32 v0, 0xbfb8aa3b, v12
	v_exp_f32_e32 v0, v0
	v_add_f32_e32 v1, 1.0, v1
	v_pk_mul_f32 v[8:9], v[2:3], v[8:9]
	v_rcp_f32_e32 v2, v1
	v_mul_f32_e32 v1, 0xbfb8aa3b, v14
	v_exp_f32_e32 v22, v1
	v_add_f32_e32 v0, 1.0, v0
	v_pk_mul_f32 v[10:11], v[2:3], v[10:11]
	v_rcp_f32_e32 v2, v0
	v_lshl_add_u64 v[0:1], v[18:19], 0, v[32:33]
	v_add_f32_e32 v18, 1.0, v22
	v_mul_f32_e32 v19, v8, v9
	v_pk_mul_f32 v[8:9], v[2:3], v[12:13]
	v_rcp_f32_e32 v2, v18
	v_mul_f32_e32 v10, v10, v11
	v_mul_f32_e32 v11, v8, v9
	v_cvt_pk_bf16_f32 v10, v19, v10
	v_pk_mul_f32 v[8:9], v[2:3], v[14:15]
	v_and_b32_e32 v12, 0xffff0000, v145
	v_mul_f32_e32 v2, v8, v9
	v_cvt_pk_bf16_f32 v11, v11, v2
	global_store_dwordx2 v[0:1], v[10:11], off offset:1024
	v_mov_b64_e32 v[8:9], v[160:161]
	v_lshlrev_b32_e32 v10, 16, v145
	v_lshlrev_b32_e32 v14, 16, v142
	v_mov_b32_e32 v22, v3
	v_and_b32_e32 v16, 0xffff0000, v142
	v_or_b32_e32 v18, 64, v32
	v_mov_b32_e32 v19, v33
	v_lshl_add_u64 v[18:19], v[4:5], 0, v[18:19]
	v_lshlrev_b32_e32 v11, 16, v8
	v_and_b32_e32 v13, 0xffff0000, v8
	v_lshlrev_b32_e32 v15, 16, v9
	v_and_b32_e32 v17, 0xffff0000, v9
	v_mul_f32_e32 v2, 0xbfb8aa3b, v11
	v_mul_f32_e32 v8, 0xbfb8aa3b, v13
	v_mul_f32_e32 v9, 0xbfb8aa3b, v15
	v_mul_f32_e32 v23, 0xbfb8aa3b, v17
	v_exp_f32_e32 v2, v2
	v_exp_f32_e32 v8, v8
	v_exp_f32_e32 v9, v9
	v_exp_f32_e32 v23, v23
	v_add_f32_e32 v2, 1.0, v2
	v_add_f32_e32 v8, 1.0, v8
	v_add_f32_e32 v9, 1.0, v9
	v_add_f32_e32 v28, 1.0, v23
	v_rcp_f32_e32 v23, v2
	v_rcp_f32_e32 v25, v8
	v_rcp_f32_e32 v27, v9
	v_rcp_f32_e32 v31, v28
	v_pk_mul_f32 v[8:9], v[22:23], v[10:11]
	v_pk_mul_f32 v[10:11], v[24:25], v[12:13]
	v_pk_mul_f32 v[12:13], v[26:27], v[14:15]
	v_pk_mul_f32 v[14:15], v[30:31], v[16:17]
	v_mul_f32_e32 v2, v8, v9
	v_mul_f32_e32 v8, v10, v11
	v_mul_f32_e32 v9, v12, v13
	v_mul_f32_e32 v10, v14, v15
	v_cvt_pk_bf16_f32 v8, v2, v8
	v_cvt_pk_bf16_f32 v9, v9, v10
	global_store_dwordx2 v[0:1], v[8:9], off offset:1056
	v_mov_b64_e32 v[8:9], v[162:163]
	v_lshlrev_b32_e32 v10, 16, v139
	v_and_b32_e32 v12, 0xffff0000, v139
	v_lshlrev_b32_e32 v14, 16, v137
	v_and_b32_e32 v16, 0xffff0000, v137
	v_or_b32_e32 v18, 0x60, v32
	v_mov_b32_e32 v19, v33
	v_lshl_add_u64 v[18:19], v[4:5], 0, v[18:19]
	v_lshlrev_b32_e32 v11, 16, v8
	v_and_b32_e32 v13, 0xffff0000, v8
	v_lshlrev_b32_e32 v15, 16, v9
	v_and_b32_e32 v17, 0xffff0000, v9
	v_mul_f32_e32 v2, 0xbfb8aa3b, v11
	v_mul_f32_e32 v8, 0xbfb8aa3b, v13
	v_mul_f32_e32 v9, 0xbfb8aa3b, v15
	v_mul_f32_e32 v23, 0xbfb8aa3b, v17
	v_exp_f32_e32 v2, v2
	v_exp_f32_e32 v8, v8
	v_exp_f32_e32 v9, v9
	v_exp_f32_e32 v23, v23
	v_add_f32_e32 v2, 1.0, v2
	v_add_f32_e32 v8, 1.0, v8
	v_add_f32_e32 v9, 1.0, v9
	v_add_f32_e32 v28, 1.0, v23
	v_rcp_f32_e32 v23, v2
	v_rcp_f32_e32 v25, v8
	v_rcp_f32_e32 v27, v9
	v_rcp_f32_e32 v31, v28
	v_pk_mul_f32 v[8:9], v[22:23], v[10:11]
	v_pk_mul_f32 v[10:11], v[24:25], v[12:13]
	v_pk_mul_f32 v[12:13], v[26:27], v[14:15]
	v_pk_mul_f32 v[14:15], v[30:31], v[16:17]
	v_mul_f32_e32 v2, v8, v9
	v_mul_f32_e32 v8, v10, v11
	v_mul_f32_e32 v9, v12, v13
	v_mul_f32_e32 v10, v14, v15
	v_cvt_pk_bf16_f32 v8, v2, v8
	v_cvt_pk_bf16_f32 v9, v9, v10
	global_store_dwordx2 v[0:1], v[8:9], off offset:1088
	v_mov_b64_e32 v[8:9], v[164:165]
	v_lshlrev_b32_e32 v10, 16, v136
	v_and_b32_e32 v12, 0xffff0000, v136
	v_lshlrev_b32_e32 v14, 16, v133
	v_and_b32_e32 v16, 0xffff0000, v133
	v_or_b32_e32 v18, 0x80, v32
	v_mov_b32_e32 v19, v33
	v_lshl_add_u64 v[18:19], v[4:5], 0, v[18:19]
	v_lshlrev_b32_e32 v11, 16, v8
	v_and_b32_e32 v13, 0xffff0000, v8
	v_lshlrev_b32_e32 v15, 16, v9
	v_and_b32_e32 v17, 0xffff0000, v9
	v_mul_f32_e32 v2, 0xbfb8aa3b, v11
	v_mul_f32_e32 v8, 0xbfb8aa3b, v13
	v_mul_f32_e32 v9, 0xbfb8aa3b, v15
	v_mul_f32_e32 v23, 0xbfb8aa3b, v17
	v_exp_f32_e32 v2, v2
	v_exp_f32_e32 v8, v8
	v_exp_f32_e32 v9, v9
	v_exp_f32_e32 v23, v23
	v_add_f32_e32 v2, 1.0, v2
	v_add_f32_e32 v8, 1.0, v8
	v_add_f32_e32 v9, 1.0, v9
	v_add_f32_e32 v28, 1.0, v23
	v_rcp_f32_e32 v23, v2
	v_rcp_f32_e32 v25, v8
	v_rcp_f32_e32 v27, v9
	v_rcp_f32_e32 v31, v28
	v_pk_mul_f32 v[8:9], v[22:23], v[10:11]
	v_pk_mul_f32 v[10:11], v[24:25], v[12:13]
	v_pk_mul_f32 v[12:13], v[26:27], v[14:15]
	v_pk_mul_f32 v[14:15], v[30:31], v[16:17]
	v_mul_f32_e32 v2, v8, v9
	v_mul_f32_e32 v8, v10, v11
	v_mul_f32_e32 v9, v12, v13
	v_mul_f32_e32 v10, v14, v15
	v_cvt_pk_bf16_f32 v8, v2, v8
	v_cvt_pk_bf16_f32 v9, v9, v10
	global_store_dwordx2 v[0:1], v[8:9], off offset:1120
	v_mov_b64_e32 v[8:9], v[166:167]
	v_lshlrev_b32_e32 v10, 16, v134
	v_and_b32_e32 v12, 0xffff0000, v134
	v_lshlrev_b32_e32 v14, 16, v132
	v_and_b32_e32 v16, 0xffff0000, v132
	v_or_b32_e32 v18, 0xa0, v32
	v_mov_b32_e32 v19, v33
	v_lshl_add_u64 v[18:19], v[4:5], 0, v[18:19]
	v_lshlrev_b32_e32 v11, 16, v8
	v_and_b32_e32 v13, 0xffff0000, v8
	v_lshlrev_b32_e32 v15, 16, v9
	v_and_b32_e32 v17, 0xffff0000, v9
	v_mul_f32_e32 v2, 0xbfb8aa3b, v11
	v_mul_f32_e32 v8, 0xbfb8aa3b, v13
	v_mul_f32_e32 v9, 0xbfb8aa3b, v15
	v_mul_f32_e32 v23, 0xbfb8aa3b, v17
	v_exp_f32_e32 v2, v2
	v_exp_f32_e32 v8, v8
	v_exp_f32_e32 v9, v9
	v_exp_f32_e32 v23, v23
	v_add_f32_e32 v2, 1.0, v2
	v_add_f32_e32 v8, 1.0, v8
	v_add_f32_e32 v9, 1.0, v9
	v_add_f32_e32 v28, 1.0, v23
	v_rcp_f32_e32 v23, v2
	v_rcp_f32_e32 v25, v8
	v_rcp_f32_e32 v27, v9
	v_rcp_f32_e32 v31, v28
	v_pk_mul_f32 v[8:9], v[22:23], v[10:11]
	v_pk_mul_f32 v[10:11], v[24:25], v[12:13]
	v_pk_mul_f32 v[12:13], v[26:27], v[14:15]
	v_pk_mul_f32 v[14:15], v[30:31], v[16:17]
	v_mul_f32_e32 v2, v8, v9
	v_mul_f32_e32 v8, v10, v11
	v_mul_f32_e32 v9, v12, v13
	v_mul_f32_e32 v10, v14, v15
	v_cvt_pk_bf16_f32 v8, v2, v8
	v_cvt_pk_bf16_f32 v9, v9, v10
	global_store_dwordx2 v[0:1], v[8:9], off offset:1152
	v_mov_b64_e32 v[8:9], v[168:169]
	v_lshlrev_b32_e32 v10, 16, v130
	v_and_b32_e32 v12, 0xffff0000, v130
	v_lshlrev_b32_e32 v14, 16, v129
	v_and_b32_e32 v16, 0xffff0000, v129
	v_or_b32_e32 v18, 0xc0, v32
	v_mov_b32_e32 v19, v33
	v_lshl_add_u64 v[18:19], v[4:5], 0, v[18:19]
	v_lshlrev_b32_e32 v11, 16, v8
	v_and_b32_e32 v13, 0xffff0000, v8
	v_lshlrev_b32_e32 v15, 16, v9
	v_and_b32_e32 v17, 0xffff0000, v9
	v_mul_f32_e32 v2, 0xbfb8aa3b, v11
	v_mul_f32_e32 v8, 0xbfb8aa3b, v13
	v_mul_f32_e32 v9, 0xbfb8aa3b, v15
	v_mul_f32_e32 v23, 0xbfb8aa3b, v17
	v_exp_f32_e32 v2, v2
	v_exp_f32_e32 v8, v8
	v_exp_f32_e32 v9, v9
	v_exp_f32_e32 v23, v23
	v_add_f32_e32 v2, 1.0, v2
	v_add_f32_e32 v8, 1.0, v8
	v_add_f32_e32 v9, 1.0, v9
	v_add_f32_e32 v28, 1.0, v23
	v_rcp_f32_e32 v23, v2
	v_rcp_f32_e32 v25, v8
	v_rcp_f32_e32 v27, v9
	v_rcp_f32_e32 v31, v28
	v_pk_mul_f32 v[8:9], v[22:23], v[10:11]
	v_pk_mul_f32 v[10:11], v[24:25], v[12:13]
	v_pk_mul_f32 v[12:13], v[26:27], v[14:15]
	v_pk_mul_f32 v[14:15], v[30:31], v[16:17]
	v_mul_f32_e32 v2, v8, v9
	v_mul_f32_e32 v8, v10, v11
	v_mul_f32_e32 v9, v12, v13
	v_mul_f32_e32 v10, v14, v15
	v_cvt_pk_bf16_f32 v8, v2, v8
	v_cvt_pk_bf16_f32 v9, v9, v10
	global_store_dwordx2 v[0:1], v[8:9], off offset:1184
	v_mov_b64_e32 v[8:9], v[170:171]
	v_lshlrev_b32_e32 v10, 16, v128
	v_and_b32_e32 v12, 0xffff0000, v128
	v_lshlrev_b32_e32 v14, 16, v127
	v_and_b32_e32 v16, 0xffff0000, v127
	v_or_b32_e32 v18, 0xe0, v32
	v_mov_b32_e32 v19, v33
	v_lshl_add_u64 v[18:19], v[4:5], 0, v[18:19]
	v_lshlrev_b32_e32 v11, 16, v8
	v_and_b32_e32 v13, 0xffff0000, v8
	v_lshlrev_b32_e32 v15, 16, v9
	v_and_b32_e32 v17, 0xffff0000, v9
	v_mul_f32_e32 v2, 0xbfb8aa3b, v11
	v_mul_f32_e32 v8, 0xbfb8aa3b, v13
	v_mul_f32_e32 v9, 0xbfb8aa3b, v15
	v_mul_f32_e32 v23, 0xbfb8aa3b, v17
	v_exp_f32_e32 v2, v2
	v_exp_f32_e32 v8, v8
	v_exp_f32_e32 v9, v9
	v_exp_f32_e32 v23, v23
	v_add_f32_e32 v2, 1.0, v2
	v_add_f32_e32 v8, 1.0, v8
	v_add_f32_e32 v9, 1.0, v9
	v_add_f32_e32 v28, 1.0, v23
	v_rcp_f32_e32 v23, v2
	v_rcp_f32_e32 v25, v8
	v_rcp_f32_e32 v27, v9
	v_rcp_f32_e32 v31, v28
	v_pk_mul_f32 v[8:9], v[22:23], v[10:11]
	v_pk_mul_f32 v[10:11], v[24:25], v[12:13]
	v_pk_mul_f32 v[12:13], v[26:27], v[14:15]
	v_pk_mul_f32 v[14:15], v[30:31], v[16:17]
	v_mul_f32_e32 v2, v8, v9
	v_mul_f32_e32 v8, v10, v11
	v_mul_f32_e32 v9, v12, v13
	v_mul_f32_e32 v10, v14, v15
	v_cvt_pk_bf16_f32 v8, v2, v8
	v_cvt_pk_bf16_f32 v9, v9, v10
	global_store_dwordx2 v[0:1], v[8:9], off offset:1216
	v_mov_b64_e32 v[8:9], v[172:173]
	v_lshlrev_b32_e32 v10, 16, v126
	v_and_b32_e32 v12, 0xffff0000, v126
	v_lshlrev_b32_e32 v14, 16, v125
	v_and_b32_e32 v16, 0xffff0000, v125
	v_or_b32_e32 v18, 0x100, v32
	v_mov_b32_e32 v19, v33
	v_lshl_add_u64 v[18:19], v[4:5], 0, v[18:19]
	v_lshlrev_b32_e32 v11, 16, v8
	v_and_b32_e32 v13, 0xffff0000, v8
	v_lshlrev_b32_e32 v15, 16, v9
	v_and_b32_e32 v17, 0xffff0000, v9
	v_mul_f32_e32 v2, 0xbfb8aa3b, v11
	v_mul_f32_e32 v8, 0xbfb8aa3b, v13
	v_mul_f32_e32 v9, 0xbfb8aa3b, v15
	v_mul_f32_e32 v23, 0xbfb8aa3b, v17
	v_exp_f32_e32 v2, v2
	v_exp_f32_e32 v8, v8
	v_exp_f32_e32 v9, v9
	v_exp_f32_e32 v23, v23
	v_add_f32_e32 v2, 1.0, v2
	v_add_f32_e32 v8, 1.0, v8
	v_add_f32_e32 v9, 1.0, v9
	v_add_f32_e32 v28, 1.0, v23
	v_rcp_f32_e32 v23, v2
	v_rcp_f32_e32 v25, v8
	v_rcp_f32_e32 v27, v9
	v_rcp_f32_e32 v31, v28
	v_pk_mul_f32 v[8:9], v[22:23], v[10:11]
	v_pk_mul_f32 v[10:11], v[24:25], v[12:13]
	v_pk_mul_f32 v[12:13], v[26:27], v[14:15]
	v_pk_mul_f32 v[14:15], v[30:31], v[16:17]
	v_mul_f32_e32 v2, v8, v9
	v_mul_f32_e32 v8, v10, v11
	v_mul_f32_e32 v9, v12, v13
	v_mul_f32_e32 v10, v14, v15
	v_cvt_pk_bf16_f32 v8, v2, v8
	v_cvt_pk_bf16_f32 v9, v9, v10
	global_store_dwordx2 v[0:1], v[8:9], off offset:1248
	v_mov_b64_e32 v[8:9], v[174:175]
	v_lshlrev_b32_e32 v10, 16, v156
	v_and_b32_e32 v12, 0xffff0000, v156
	v_lshlrev_b32_e32 v14, 16, v154
	v_and_b32_e32 v16, 0xffff0000, v154
	v_or_b32_e32 v18, 0x120, v32
	v_mov_b32_e32 v19, v33
	v_lshl_add_u64 v[18:19], v[4:5], 0, v[18:19]
	v_lshlrev_b32_e32 v11, 16, v8
	v_and_b32_e32 v13, 0xffff0000, v8
	v_lshlrev_b32_e32 v15, 16, v9
	v_and_b32_e32 v17, 0xffff0000, v9
	v_mul_f32_e32 v2, 0xbfb8aa3b, v11
	v_mul_f32_e32 v8, 0xbfb8aa3b, v13
	v_mul_f32_e32 v9, 0xbfb8aa3b, v15
	v_mul_f32_e32 v23, 0xbfb8aa3b, v17
	v_exp_f32_e32 v2, v2
	v_exp_f32_e32 v8, v8
	v_exp_f32_e32 v9, v9
	v_exp_f32_e32 v23, v23
	v_add_f32_e32 v2, 1.0, v2
	v_add_f32_e32 v8, 1.0, v8
	v_add_f32_e32 v9, 1.0, v9
	v_add_f32_e32 v28, 1.0, v23
	v_rcp_f32_e32 v23, v2
	v_rcp_f32_e32 v25, v8
	v_rcp_f32_e32 v27, v9
	v_rcp_f32_e32 v31, v28
	v_pk_mul_f32 v[8:9], v[22:23], v[10:11]
	v_pk_mul_f32 v[10:11], v[24:25], v[12:13]
	v_pk_mul_f32 v[12:13], v[26:27], v[14:15]
	v_pk_mul_f32 v[14:15], v[30:31], v[16:17]
	v_mul_f32_e32 v2, v8, v9
	v_mul_f32_e32 v8, v10, v11
	v_mul_f32_e32 v9, v12, v13
	v_mul_f32_e32 v10, v14, v15
	v_cvt_pk_bf16_f32 v8, v2, v8
	v_cvt_pk_bf16_f32 v9, v9, v10
	global_store_dwordx2 v[0:1], v[8:9], off offset:1280
	v_mov_b64_e32 v[8:9], v[176:177]
	v_lshlrev_b32_e32 v10, 16, v153
	v_and_b32_e32 v12, 0xffff0000, v153
	v_lshlrev_b32_e32 v14, 16, v151
	v_and_b32_e32 v16, 0xffff0000, v151
	v_or_b32_e32 v18, 0x140, v32
	v_mov_b32_e32 v19, v33
	v_lshl_add_u64 v[18:19], v[4:5], 0, v[18:19]
	v_lshlrev_b32_e32 v11, 16, v8
	v_and_b32_e32 v13, 0xffff0000, v8
	v_lshlrev_b32_e32 v15, 16, v9
	v_and_b32_e32 v17, 0xffff0000, v9
	v_mul_f32_e32 v2, 0xbfb8aa3b, v11
	v_mul_f32_e32 v8, 0xbfb8aa3b, v13
	v_mul_f32_e32 v9, 0xbfb8aa3b, v15
	v_mul_f32_e32 v23, 0xbfb8aa3b, v17
	v_exp_f32_e32 v2, v2
	v_exp_f32_e32 v8, v8
	v_exp_f32_e32 v9, v9
	v_exp_f32_e32 v23, v23
	v_add_f32_e32 v2, 1.0, v2
	v_add_f32_e32 v8, 1.0, v8
	v_add_f32_e32 v9, 1.0, v9
	v_add_f32_e32 v28, 1.0, v23
	v_rcp_f32_e32 v23, v2
	v_rcp_f32_e32 v25, v8
	v_rcp_f32_e32 v27, v9
	v_rcp_f32_e32 v31, v28
	v_pk_mul_f32 v[8:9], v[22:23], v[10:11]
	v_pk_mul_f32 v[10:11], v[24:25], v[12:13]
	v_pk_mul_f32 v[12:13], v[26:27], v[14:15]
	v_pk_mul_f32 v[14:15], v[30:31], v[16:17]
	v_mul_f32_e32 v2, v8, v9
	v_mul_f32_e32 v8, v10, v11
	v_mul_f32_e32 v9, v12, v13
	v_mul_f32_e32 v10, v14, v15
	v_cvt_pk_bf16_f32 v8, v2, v8
	v_cvt_pk_bf16_f32 v9, v9, v10
	global_store_dwordx2 v[0:1], v[8:9], off offset:1312
	v_mov_b64_e32 v[8:9], v[178:179]
	v_lshlrev_b32_e32 v10, 16, v149
	v_and_b32_e32 v12, 0xffff0000, v149
	v_lshlrev_b32_e32 v14, 16, v147
	v_and_b32_e32 v16, 0xffff0000, v147
	v_or_b32_e32 v18, 0x160, v32
	v_mov_b32_e32 v19, v33
	v_lshl_add_u64 v[18:19], v[4:5], 0, v[18:19]
	v_lshlrev_b32_e32 v11, 16, v8
	v_and_b32_e32 v13, 0xffff0000, v8
	v_lshlrev_b32_e32 v15, 16, v9
	v_and_b32_e32 v17, 0xffff0000, v9
	v_mul_f32_e32 v2, 0xbfb8aa3b, v11
	v_mul_f32_e32 v8, 0xbfb8aa3b, v13
	v_mul_f32_e32 v9, 0xbfb8aa3b, v15
	v_mul_f32_e32 v23, 0xbfb8aa3b, v17
	v_exp_f32_e32 v2, v2
	v_exp_f32_e32 v8, v8
	v_exp_f32_e32 v9, v9
	v_exp_f32_e32 v23, v23
	v_add_f32_e32 v2, 1.0, v2
	v_add_f32_e32 v8, 1.0, v8
	v_add_f32_e32 v9, 1.0, v9
	v_add_f32_e32 v28, 1.0, v23
	v_rcp_f32_e32 v23, v2
	v_rcp_f32_e32 v25, v8
	v_rcp_f32_e32 v27, v9
	v_rcp_f32_e32 v31, v28
	v_pk_mul_f32 v[8:9], v[22:23], v[10:11]
	v_pk_mul_f32 v[10:11], v[24:25], v[12:13]
	v_pk_mul_f32 v[12:13], v[26:27], v[14:15]
	v_pk_mul_f32 v[14:15], v[30:31], v[16:17]
	v_mul_f32_e32 v2, v8, v9
	v_mul_f32_e32 v8, v10, v11
	v_mul_f32_e32 v9, v12, v13
	v_mul_f32_e32 v10, v14, v15
	v_cvt_pk_bf16_f32 v8, v2, v8
	v_cvt_pk_bf16_f32 v9, v9, v10
	global_store_dwordx2 v[0:1], v[8:9], off offset:1344
	v_mov_b64_e32 v[8:9], v[180:181]
	v_lshlrev_b32_e32 v10, 16, v146
	v_and_b32_e32 v12, 0xffff0000, v146
	v_lshlrev_b32_e32 v14, 16, v143
	v_and_b32_e32 v16, 0xffff0000, v143
	v_or_b32_e32 v18, 0x180, v32
	v_mov_b32_e32 v19, v33
	v_lshl_add_u64 v[18:19], v[4:5], 0, v[18:19]
	v_lshlrev_b32_e32 v11, 16, v8
	v_and_b32_e32 v13, 0xffff0000, v8
	v_lshlrev_b32_e32 v15, 16, v9
	v_and_b32_e32 v17, 0xffff0000, v9
	v_mul_f32_e32 v2, 0xbfb8aa3b, v11
	v_mul_f32_e32 v8, 0xbfb8aa3b, v13
	v_mul_f32_e32 v9, 0xbfb8aa3b, v15
	v_mul_f32_e32 v23, 0xbfb8aa3b, v17
	v_exp_f32_e32 v2, v2
	v_exp_f32_e32 v8, v8
	v_exp_f32_e32 v9, v9
	v_exp_f32_e32 v23, v23
	v_add_f32_e32 v2, 1.0, v2
	v_add_f32_e32 v8, 1.0, v8
	v_add_f32_e32 v9, 1.0, v9
	v_add_f32_e32 v28, 1.0, v23
	v_rcp_f32_e32 v23, v2
	v_rcp_f32_e32 v25, v8
	v_rcp_f32_e32 v27, v9
	v_rcp_f32_e32 v31, v28
	v_pk_mul_f32 v[8:9], v[22:23], v[10:11]
	v_pk_mul_f32 v[10:11], v[24:25], v[12:13]
	v_pk_mul_f32 v[12:13], v[26:27], v[14:15]
	v_pk_mul_f32 v[14:15], v[30:31], v[16:17]
	v_mul_f32_e32 v2, v8, v9
	v_mul_f32_e32 v8, v10, v11
	v_mul_f32_e32 v9, v12, v13
	v_mul_f32_e32 v10, v14, v15
	v_cvt_pk_bf16_f32 v8, v2, v8
	v_cvt_pk_bf16_f32 v9, v9, v10
	global_store_dwordx2 v[0:1], v[8:9], off offset:1376
	v_mov_b64_e32 v[8:9], v[182:183]
	v_lshlrev_b32_e32 v10, 16, v144
	v_and_b32_e32 v12, 0xffff0000, v144
	v_lshlrev_b32_e32 v14, 16, v141
	v_and_b32_e32 v16, 0xffff0000, v141
	v_or_b32_e32 v18, 0x1a0, v32
	v_mov_b32_e32 v19, v33
	v_lshl_add_u64 v[18:19], v[4:5], 0, v[18:19]
	v_lshlrev_b32_e32 v11, 16, v8
	v_and_b32_e32 v13, 0xffff0000, v8
	v_lshlrev_b32_e32 v15, 16, v9
	v_and_b32_e32 v17, 0xffff0000, v9
	v_mul_f32_e32 v2, 0xbfb8aa3b, v11
	v_mul_f32_e32 v8, 0xbfb8aa3b, v13
	v_mul_f32_e32 v9, 0xbfb8aa3b, v15
	v_mul_f32_e32 v23, 0xbfb8aa3b, v17
	v_exp_f32_e32 v2, v2
	v_exp_f32_e32 v8, v8
	v_exp_f32_e32 v9, v9
	v_exp_f32_e32 v23, v23
	v_add_f32_e32 v2, 1.0, v2
	v_add_f32_e32 v8, 1.0, v8
	v_add_f32_e32 v9, 1.0, v9
	v_add_f32_e32 v28, 1.0, v23
	v_rcp_f32_e32 v23, v2
	v_rcp_f32_e32 v25, v8
	v_rcp_f32_e32 v27, v9
	v_rcp_f32_e32 v31, v28
	v_pk_mul_f32 v[8:9], v[22:23], v[10:11]
	v_pk_mul_f32 v[10:11], v[24:25], v[12:13]
	v_pk_mul_f32 v[12:13], v[26:27], v[14:15]
	v_pk_mul_f32 v[14:15], v[30:31], v[16:17]
	v_mul_f32_e32 v2, v8, v9
	v_mul_f32_e32 v8, v10, v11
	v_mul_f32_e32 v9, v12, v13
	v_mul_f32_e32 v10, v14, v15
	v_cvt_pk_bf16_f32 v8, v2, v8
	v_cvt_pk_bf16_f32 v9, v9, v10
	global_store_dwordx2 v[0:1], v[8:9], off offset:1408
	v_mov_b64_e32 v[8:9], v[184:185]
	v_lshlrev_b32_e32 v10, 16, v140
	v_and_b32_e32 v12, 0xffff0000, v140
	v_lshlrev_b32_e32 v14, 16, v138
	v_and_b32_e32 v16, 0xffff0000, v138
	v_or_b32_e32 v18, 0x1c0, v32
	v_mov_b32_e32 v19, v33
	v_lshl_add_u64 v[18:19], v[4:5], 0, v[18:19]
	v_lshlrev_b32_e32 v11, 16, v8
	v_and_b32_e32 v13, 0xffff0000, v8
	v_lshlrev_b32_e32 v15, 16, v9
	v_and_b32_e32 v17, 0xffff0000, v9
	v_mul_f32_e32 v2, 0xbfb8aa3b, v11
	v_mul_f32_e32 v8, 0xbfb8aa3b, v13
	v_mul_f32_e32 v9, 0xbfb8aa3b, v15
	v_mul_f32_e32 v23, 0xbfb8aa3b, v17
	v_exp_f32_e32 v2, v2
	v_exp_f32_e32 v8, v8
	v_exp_f32_e32 v9, v9
	v_exp_f32_e32 v23, v23
	v_add_f32_e32 v2, 1.0, v2
	v_add_f32_e32 v8, 1.0, v8
	v_add_f32_e32 v9, 1.0, v9
	v_add_f32_e32 v28, 1.0, v23
	v_rcp_f32_e32 v23, v2
	v_rcp_f32_e32 v25, v8
	v_rcp_f32_e32 v27, v9
	v_rcp_f32_e32 v31, v28
	v_pk_mul_f32 v[8:9], v[22:23], v[10:11]
	v_pk_mul_f32 v[10:11], v[24:25], v[12:13]
	v_pk_mul_f32 v[12:13], v[26:27], v[14:15]
	v_pk_mul_f32 v[14:15], v[30:31], v[16:17]
	v_mul_f32_e32 v2, v8, v9
	v_mul_f32_e32 v8, v10, v11
	v_mul_f32_e32 v9, v12, v13
	v_mul_f32_e32 v10, v14, v15
	v_cvt_pk_bf16_f32 v8, v2, v8
	v_cvt_pk_bf16_f32 v9, v9, v10
	global_store_dwordx2 v[0:1], v[8:9], off offset:1440
	v_mov_b64_e32 v[8:9], v[186:187]
	v_lshlrev_b32_e32 v10, 16, v135
	v_and_b32_e32 v12, 0xffff0000, v135
	v_lshlrev_b32_e32 v14, 16, v131
	v_and_b32_e32 v16, 0xffff0000, v131
	v_or_b32_e32 v18, 0x1e0, v32
	v_mov_b32_e32 v19, v33
	v_lshl_add_u64 v[18:19], v[4:5], 0, v[18:19]
	v_lshlrev_b32_e32 v11, 16, v8
	v_and_b32_e32 v13, 0xffff0000, v8
	v_lshlrev_b32_e32 v15, 16, v9
	v_and_b32_e32 v17, 0xffff0000, v9
	v_mul_f32_e32 v2, 0xbfb8aa3b, v11
	v_mul_f32_e32 v8, 0xbfb8aa3b, v13
	v_mul_f32_e32 v9, 0xbfb8aa3b, v15
	v_mul_f32_e32 v23, 0xbfb8aa3b, v17
	v_exp_f32_e32 v2, v2
	v_exp_f32_e32 v8, v8
	v_exp_f32_e32 v9, v9
	v_exp_f32_e32 v23, v23
	v_add_f32_e32 v2, 1.0, v2
	v_add_f32_e32 v8, 1.0, v8
	v_add_f32_e32 v9, 1.0, v9
	v_add_f32_e32 v28, 1.0, v23
	v_rcp_f32_e32 v23, v2
	v_rcp_f32_e32 v25, v8
	v_rcp_f32_e32 v27, v9
	v_rcp_f32_e32 v31, v28
	v_pk_mul_f32 v[8:9], v[22:23], v[10:11]
	v_pk_mul_f32 v[10:11], v[24:25], v[12:13]
	v_pk_mul_f32 v[12:13], v[26:27], v[14:15]
	v_pk_mul_f32 v[14:15], v[30:31], v[16:17]
	v_mul_f32_e32 v2, v8, v9
	v_mul_f32_e32 v8, v10, v11
	v_mul_f32_e32 v9, v12, v13
	v_mul_f32_e32 v10, v14, v15
	v_cvt_pk_bf16_f32 v8, v2, v8
	v_cvt_pk_bf16_f32 v9, v9, v10
	global_store_dwordx2 v[0:1], v[8:9], off offset:1472
	v_mov_b64_e32 v[8:9], v[188:189]
	v_lshlrev_b32_e32 v10, 16, v122
	v_and_b32_e32 v12, 0xffff0000, v122
	v_lshlrev_b32_e32 v14, 16, v120
	v_and_b32_e32 v16, 0xffff0000, v120
	v_or_b32_e32 v18, 0x200, v32
	v_mov_b32_e32 v19, v33
	v_lshl_add_u64 v[18:19], v[4:5], 0, v[18:19]
	v_lshlrev_b32_e32 v11, 16, v8
	v_and_b32_e32 v13, 0xffff0000, v8
	v_lshlrev_b32_e32 v15, 16, v9
	v_and_b32_e32 v17, 0xffff0000, v9
	v_mul_f32_e32 v2, 0xbfb8aa3b, v11
	v_mul_f32_e32 v8, 0xbfb8aa3b, v13
	v_mul_f32_e32 v9, 0xbfb8aa3b, v15
	v_mul_f32_e32 v23, 0xbfb8aa3b, v17
	v_exp_f32_e32 v2, v2
	v_exp_f32_e32 v8, v8
	v_exp_f32_e32 v9, v9
	v_exp_f32_e32 v23, v23
	v_add_f32_e32 v2, 1.0, v2
	v_add_f32_e32 v8, 1.0, v8
	v_add_f32_e32 v9, 1.0, v9
	v_add_f32_e32 v28, 1.0, v23
	v_rcp_f32_e32 v23, v2
	v_rcp_f32_e32 v25, v8
	v_rcp_f32_e32 v27, v9
	v_rcp_f32_e32 v31, v28
	v_pk_mul_f32 v[8:9], v[22:23], v[10:11]
	v_pk_mul_f32 v[10:11], v[24:25], v[12:13]
	v_pk_mul_f32 v[12:13], v[26:27], v[14:15]
	v_pk_mul_f32 v[14:15], v[30:31], v[16:17]
	v_mul_f32_e32 v2, v8, v9
	v_mul_f32_e32 v8, v10, v11
	v_mul_f32_e32 v9, v12, v13
	v_mul_f32_e32 v10, v14, v15
	v_cvt_pk_bf16_f32 v8, v2, v8
	v_cvt_pk_bf16_f32 v9, v9, v10
	global_store_dwordx2 v[0:1], v[8:9], off offset:1504
	v_mov_b64_e32 v[8:9], v[190:191]
	v_lshlrev_b32_e32 v10, 16, v159
	v_and_b32_e32 v12, 0xffff0000, v159
	v_lshlrev_b32_e32 v14, 16, v158
	v_and_b32_e32 v16, 0xffff0000, v158
	v_or_b32_e32 v18, 0x220, v32
	v_mov_b32_e32 v19, v33
	v_lshl_add_u64 v[18:19], v[4:5], 0, v[18:19]
	v_lshlrev_b32_e32 v11, 16, v8
	v_and_b32_e32 v13, 0xffff0000, v8
	v_lshlrev_b32_e32 v15, 16, v9
	v_and_b32_e32 v17, 0xffff0000, v9
	v_mul_f32_e32 v2, 0xbfb8aa3b, v11
	v_mul_f32_e32 v8, 0xbfb8aa3b, v13
	v_mul_f32_e32 v9, 0xbfb8aa3b, v15
	v_mul_f32_e32 v23, 0xbfb8aa3b, v17
	v_exp_f32_e32 v2, v2
	v_exp_f32_e32 v8, v8
	v_exp_f32_e32 v9, v9
	v_exp_f32_e32 v23, v23
	v_add_f32_e32 v2, 1.0, v2
	v_add_f32_e32 v8, 1.0, v8
	v_add_f32_e32 v9, 1.0, v9
	v_add_f32_e32 v28, 1.0, v23
	v_rcp_f32_e32 v23, v2
	v_rcp_f32_e32 v25, v8
	v_rcp_f32_e32 v27, v9
	v_rcp_f32_e32 v31, v28
	v_pk_mul_f32 v[8:9], v[22:23], v[10:11]
	v_pk_mul_f32 v[10:11], v[24:25], v[12:13]
	v_pk_mul_f32 v[12:13], v[26:27], v[14:15]
	v_pk_mul_f32 v[14:15], v[30:31], v[16:17]
	v_mul_f32_e32 v2, v8, v9
	v_mul_f32_e32 v8, v10, v11
	v_mul_f32_e32 v9, v12, v13
	v_mul_f32_e32 v10, v14, v15
	v_cvt_pk_bf16_f32 v8, v2, v8
	v_cvt_pk_bf16_f32 v9, v9, v10
	global_store_dwordx2 v[0:1], v[8:9], off offset:1536
	v_mov_b64_e32 v[8:9], v[192:193]
	v_lshlrev_b32_e32 v10, 16, v123
	v_and_b32_e32 v12, 0xffff0000, v123
	v_lshlrev_b32_e32 v14, 16, v121
	v_and_b32_e32 v16, 0xffff0000, v121
	v_or_b32_e32 v18, 0x240, v32
	v_mov_b32_e32 v19, v33
	v_lshl_add_u64 v[18:19], v[4:5], 0, v[18:19]
	v_lshlrev_b32_e32 v11, 16, v8
	v_and_b32_e32 v13, 0xffff0000, v8
	v_lshlrev_b32_e32 v15, 16, v9
	v_and_b32_e32 v17, 0xffff0000, v9
	v_mul_f32_e32 v2, 0xbfb8aa3b, v11
	v_mul_f32_e32 v8, 0xbfb8aa3b, v13
	v_mul_f32_e32 v9, 0xbfb8aa3b, v15
	v_mul_f32_e32 v23, 0xbfb8aa3b, v17
	v_exp_f32_e32 v2, v2
	v_exp_f32_e32 v8, v8
	v_exp_f32_e32 v9, v9
	v_exp_f32_e32 v23, v23
	v_add_f32_e32 v2, 1.0, v2
	v_add_f32_e32 v8, 1.0, v8
	v_add_f32_e32 v9, 1.0, v9
	v_add_f32_e32 v28, 1.0, v23
	v_rcp_f32_e32 v23, v2
	v_rcp_f32_e32 v25, v8
	v_rcp_f32_e32 v27, v9
	v_rcp_f32_e32 v31, v28
	v_pk_mul_f32 v[8:9], v[22:23], v[10:11]
	v_pk_mul_f32 v[10:11], v[24:25], v[12:13]
	v_pk_mul_f32 v[12:13], v[26:27], v[14:15]
	v_pk_mul_f32 v[14:15], v[30:31], v[16:17]
	v_mul_f32_e32 v2, v8, v9
	v_mul_f32_e32 v8, v10, v11
	v_mul_f32_e32 v9, v12, v13
	v_mul_f32_e32 v10, v14, v15
	v_cvt_pk_bf16_f32 v8, v2, v8
	v_cvt_pk_bf16_f32 v9, v9, v10
	global_store_dwordx2 v[0:1], v[8:9], off offset:1568
	v_mov_b64_e32 v[8:9], v[194:195]
	v_lshlrev_b32_e32 v10, 16, v119
	v_and_b32_e32 v12, 0xffff0000, v119
	v_lshlrev_b32_e32 v14, 16, v118
	v_and_b32_e32 v16, 0xffff0000, v118
	v_or_b32_e32 v18, 0x260, v32
	v_mov_b32_e32 v19, v33
	v_lshl_add_u64 v[18:19], v[4:5], 0, v[18:19]
	v_lshlrev_b32_e32 v11, 16, v8
	v_and_b32_e32 v13, 0xffff0000, v8
	v_lshlrev_b32_e32 v15, 16, v9
	v_and_b32_e32 v17, 0xffff0000, v9
	v_mul_f32_e32 v2, 0xbfb8aa3b, v11
	v_mul_f32_e32 v8, 0xbfb8aa3b, v13
	v_mul_f32_e32 v9, 0xbfb8aa3b, v15
	v_mul_f32_e32 v23, 0xbfb8aa3b, v17
	v_exp_f32_e32 v2, v2
	v_exp_f32_e32 v8, v8
	v_exp_f32_e32 v9, v9
	v_exp_f32_e32 v23, v23
	v_add_f32_e32 v2, 1.0, v2
	v_add_f32_e32 v8, 1.0, v8
	v_add_f32_e32 v9, 1.0, v9
	v_add_f32_e32 v28, 1.0, v23
	v_rcp_f32_e32 v23, v2
	v_rcp_f32_e32 v25, v8
	v_rcp_f32_e32 v27, v9
	v_rcp_f32_e32 v31, v28
	v_pk_mul_f32 v[8:9], v[22:23], v[10:11]
	v_pk_mul_f32 v[10:11], v[24:25], v[12:13]
	v_pk_mul_f32 v[12:13], v[26:27], v[14:15]
	v_pk_mul_f32 v[14:15], v[30:31], v[16:17]
	v_mul_f32_e32 v2, v8, v9
	v_mul_f32_e32 v8, v10, v11
	v_mul_f32_e32 v9, v12, v13
	v_mul_f32_e32 v10, v14, v15
	v_cvt_pk_bf16_f32 v8, v2, v8
	v_cvt_pk_bf16_f32 v9, v9, v10
	global_store_dwordx2 v[0:1], v[8:9], off offset:1600
	v_mov_b64_e32 v[8:9], v[196:197]
	v_lshlrev_b32_e32 v10, 16, v117
	v_and_b32_e32 v12, 0xffff0000, v117
	v_lshlrev_b32_e32 v14, 16, v115
	v_and_b32_e32 v16, 0xffff0000, v115
	v_or_b32_e32 v18, 0x280, v32
	v_mov_b32_e32 v19, v33
	v_lshl_add_u64 v[18:19], v[4:5], 0, v[18:19]
	v_lshlrev_b32_e32 v11, 16, v8
	v_and_b32_e32 v13, 0xffff0000, v8
	v_lshlrev_b32_e32 v15, 16, v9
	v_and_b32_e32 v17, 0xffff0000, v9
	v_mul_f32_e32 v2, 0xbfb8aa3b, v11
	v_mul_f32_e32 v8, 0xbfb8aa3b, v13
	v_mul_f32_e32 v9, 0xbfb8aa3b, v15
	v_mul_f32_e32 v23, 0xbfb8aa3b, v17
	v_exp_f32_e32 v2, v2
	v_exp_f32_e32 v8, v8
	v_exp_f32_e32 v9, v9
	v_exp_f32_e32 v23, v23
	v_add_f32_e32 v2, 1.0, v2
	v_add_f32_e32 v8, 1.0, v8
	v_add_f32_e32 v9, 1.0, v9
	v_add_f32_e32 v28, 1.0, v23
	v_rcp_f32_e32 v23, v2
	v_rcp_f32_e32 v25, v8
	v_rcp_f32_e32 v27, v9
	v_rcp_f32_e32 v31, v28
	v_pk_mul_f32 v[8:9], v[22:23], v[10:11]
	v_pk_mul_f32 v[10:11], v[24:25], v[12:13]
	v_pk_mul_f32 v[12:13], v[26:27], v[14:15]
	v_pk_mul_f32 v[14:15], v[30:31], v[16:17]
	v_mul_f32_e32 v2, v8, v9
	v_mul_f32_e32 v8, v10, v11
	v_mul_f32_e32 v9, v12, v13
	v_mul_f32_e32 v10, v14, v15
	v_cvt_pk_bf16_f32 v8, v2, v8
	v_cvt_pk_bf16_f32 v9, v9, v10
	global_store_dwordx2 v[0:1], v[8:9], off offset:1632
	v_mov_b64_e32 v[8:9], v[198:199]
	v_lshlrev_b32_e32 v10, 16, v116
	v_and_b32_e32 v12, 0xffff0000, v116
	v_lshlrev_b32_e32 v14, 16, v114
	v_and_b32_e32 v16, 0xffff0000, v114
	v_or_b32_e32 v18, 0x2a0, v32
	v_mov_b32_e32 v19, v33
	v_lshl_add_u64 v[18:19], v[4:5], 0, v[18:19]
	v_lshlrev_b32_e32 v11, 16, v8
	v_and_b32_e32 v13, 0xffff0000, v8
	v_lshlrev_b32_e32 v15, 16, v9
	v_and_b32_e32 v17, 0xffff0000, v9
	v_mul_f32_e32 v2, 0xbfb8aa3b, v11
	v_mul_f32_e32 v8, 0xbfb8aa3b, v13
	v_mul_f32_e32 v9, 0xbfb8aa3b, v15
	v_mul_f32_e32 v23, 0xbfb8aa3b, v17
	v_exp_f32_e32 v2, v2
	v_exp_f32_e32 v8, v8
	v_exp_f32_e32 v9, v9
	v_exp_f32_e32 v23, v23
	v_add_f32_e32 v2, 1.0, v2
	v_add_f32_e32 v8, 1.0, v8
	v_add_f32_e32 v9, 1.0, v9
	v_add_f32_e32 v28, 1.0, v23
	v_rcp_f32_e32 v23, v2
	v_rcp_f32_e32 v25, v8
	v_rcp_f32_e32 v27, v9
	v_rcp_f32_e32 v31, v28
	v_pk_mul_f32 v[8:9], v[22:23], v[10:11]
	v_pk_mul_f32 v[10:11], v[24:25], v[12:13]
	v_pk_mul_f32 v[12:13], v[26:27], v[14:15]
	v_pk_mul_f32 v[14:15], v[30:31], v[16:17]
	v_mul_f32_e32 v2, v8, v9
	v_mul_f32_e32 v8, v10, v11
	v_mul_f32_e32 v9, v12, v13
	v_mul_f32_e32 v10, v14, v15
	v_cvt_pk_bf16_f32 v8, v2, v8
	v_cvt_pk_bf16_f32 v9, v9, v10
	global_store_dwordx2 v[0:1], v[8:9], off offset:1664
	v_mov_b64_e32 v[8:9], v[200:201]
	v_lshlrev_b32_e32 v10, 16, v113
	v_and_b32_e32 v12, 0xffff0000, v113
	v_lshlrev_b32_e32 v14, 16, v112
	v_and_b32_e32 v16, 0xffff0000, v112
	v_or_b32_e32 v18, 0x2c0, v32
	v_mov_b32_e32 v19, v33
	v_lshl_add_u64 v[18:19], v[4:5], 0, v[18:19]
	v_lshlrev_b32_e32 v11, 16, v8
	v_and_b32_e32 v13, 0xffff0000, v8
	v_lshlrev_b32_e32 v15, 16, v9
	v_and_b32_e32 v17, 0xffff0000, v9
	v_mul_f32_e32 v2, 0xbfb8aa3b, v11
	v_mul_f32_e32 v8, 0xbfb8aa3b, v13
	v_mul_f32_e32 v9, 0xbfb8aa3b, v15
	v_mul_f32_e32 v23, 0xbfb8aa3b, v17
	v_exp_f32_e32 v2, v2
	v_exp_f32_e32 v8, v8
	v_exp_f32_e32 v9, v9
	v_exp_f32_e32 v23, v23
	v_add_f32_e32 v2, 1.0, v2
	v_add_f32_e32 v8, 1.0, v8
	v_add_f32_e32 v9, 1.0, v9
	v_add_f32_e32 v28, 1.0, v23
	v_rcp_f32_e32 v23, v2
	v_rcp_f32_e32 v25, v8
	v_rcp_f32_e32 v27, v9
	v_rcp_f32_e32 v31, v28
	v_pk_mul_f32 v[8:9], v[22:23], v[10:11]
	v_pk_mul_f32 v[10:11], v[24:25], v[12:13]
	v_pk_mul_f32 v[12:13], v[26:27], v[14:15]
	v_pk_mul_f32 v[14:15], v[30:31], v[16:17]
	v_mul_f32_e32 v2, v8, v9
	v_mul_f32_e32 v8, v10, v11
	v_mul_f32_e32 v9, v12, v13
	v_mul_f32_e32 v10, v14, v15
	v_cvt_pk_bf16_f32 v8, v2, v8
	v_cvt_pk_bf16_f32 v9, v9, v10
	global_store_dwordx2 v[0:1], v[8:9], off offset:1696
	v_mov_b64_e32 v[8:9], v[202:203]
	v_lshlrev_b32_e32 v10, 16, v111
	v_and_b32_e32 v12, 0xffff0000, v111
	v_lshlrev_b32_e32 v14, 16, v110
	v_and_b32_e32 v16, 0xffff0000, v110
	v_or_b32_e32 v18, 0x2e0, v32
	v_mov_b32_e32 v19, v33
	v_lshl_add_u64 v[18:19], v[4:5], 0, v[18:19]
	v_lshlrev_b32_e32 v11, 16, v8
	v_and_b32_e32 v13, 0xffff0000, v8
	v_lshlrev_b32_e32 v15, 16, v9
	v_and_b32_e32 v17, 0xffff0000, v9
	v_mul_f32_e32 v2, 0xbfb8aa3b, v11
	v_mul_f32_e32 v8, 0xbfb8aa3b, v13
	v_mul_f32_e32 v9, 0xbfb8aa3b, v15
	v_mul_f32_e32 v23, 0xbfb8aa3b, v17
	v_exp_f32_e32 v2, v2
	v_exp_f32_e32 v8, v8
	v_exp_f32_e32 v9, v9
	v_exp_f32_e32 v23, v23
	v_add_f32_e32 v2, 1.0, v2
	v_add_f32_e32 v8, 1.0, v8
	v_add_f32_e32 v9, 1.0, v9
	v_add_f32_e32 v28, 1.0, v23
	v_rcp_f32_e32 v23, v2
	v_rcp_f32_e32 v25, v8
	v_rcp_f32_e32 v27, v9
	v_rcp_f32_e32 v31, v28
	v_pk_mul_f32 v[8:9], v[22:23], v[10:11]
	v_pk_mul_f32 v[10:11], v[24:25], v[12:13]
	v_pk_mul_f32 v[12:13], v[26:27], v[14:15]
	v_pk_mul_f32 v[14:15], v[30:31], v[16:17]
	v_mul_f32_e32 v2, v8, v9
	v_mul_f32_e32 v8, v10, v11
	v_mul_f32_e32 v9, v12, v13
	v_mul_f32_e32 v10, v14, v15
	v_cvt_pk_bf16_f32 v8, v2, v8
	v_cvt_pk_bf16_f32 v9, v9, v10
	global_store_dwordx2 v[0:1], v[8:9], off offset:1728
	v_mov_b64_e32 v[8:9], v[204:205]
	v_lshlrev_b32_e32 v14, 16, v29
	v_and_b32_e32 v16, 0xffff0000, v29
	v_lshlrev_b32_e32 v10, 16, v106
	v_and_b32_e32 v12, 0xffff0000, v106
	v_mov_b32_e32 v28, v3
	v_or_b32_e32 v18, 0x300, v32
	v_mov_b32_e32 v19, v33
	v_lshl_add_u64 v[18:19], v[4:5], 0, v[18:19]
	v_lshlrev_b32_e32 v11, 16, v8
	v_and_b32_e32 v13, 0xffff0000, v8
	v_lshlrev_b32_e32 v15, 16, v9
	v_and_b32_e32 v17, 0xffff0000, v9
	v_mul_f32_e32 v2, 0xbfb8aa3b, v11
	v_mul_f32_e32 v8, 0xbfb8aa3b, v13
	v_mul_f32_e32 v9, 0xbfb8aa3b, v15
	v_mul_f32_e32 v23, 0xbfb8aa3b, v17
	v_exp_f32_e32 v2, v2
	v_exp_f32_e32 v8, v8
	v_exp_f32_e32 v9, v9
	v_exp_f32_e32 v23, v23
	v_add_f32_e32 v2, 1.0, v2
	v_add_f32_e32 v8, 1.0, v8
	v_add_f32_e32 v9, 1.0, v9
	v_add_f32_e32 v29, 1.0, v23
	v_rcp_f32_e32 v23, v2
	v_rcp_f32_e32 v25, v8
	v_rcp_f32_e32 v27, v9
	v_rcp_f32_e32 v29, v29
	v_pk_mul_f32 v[8:9], v[22:23], v[10:11]
	v_pk_mul_f32 v[10:11], v[24:25], v[12:13]
	v_pk_mul_f32 v[12:13], v[26:27], v[14:15]
	v_pk_mul_f32 v[14:15], v[28:29], v[16:17]
	v_mul_f32_e32 v2, v8, v9
	v_mul_f32_e32 v8, v10, v11
	v_mul_f32_e32 v9, v12, v13
	v_mul_f32_e32 v10, v14, v15
	v_cvt_pk_bf16_f32 v8, v2, v8
	v_cvt_pk_bf16_f32 v9, v9, v10
	global_store_dwordx2 v[0:1], v[8:9], off offset:1760
	v_mov_b64_e32 v[8:9], v[206:207]
	v_lshlrev_b32_e32 v10, 16, v77
	v_and_b32_e32 v12, 0xffff0000, v77
	v_lshlrev_b32_e32 v14, 16, v76
	v_and_b32_e32 v16, 0xffff0000, v76
	v_or_b32_e32 v18, 0x320, v32
	v_mov_b32_e32 v19, v33
	v_lshl_add_u64 v[18:19], v[4:5], 0, v[18:19]
	v_lshlrev_b32_e32 v11, 16, v8
	v_and_b32_e32 v13, 0xffff0000, v8
	v_lshlrev_b32_e32 v15, 16, v9
	v_and_b32_e32 v17, 0xffff0000, v9
	v_mul_f32_e32 v2, 0xbfb8aa3b, v11
	v_mul_f32_e32 v8, 0xbfb8aa3b, v13
	v_mul_f32_e32 v9, 0xbfb8aa3b, v15
	v_mul_f32_e32 v23, 0xbfb8aa3b, v17
	v_exp_f32_e32 v2, v2
	v_exp_f32_e32 v8, v8
	v_exp_f32_e32 v9, v9
	v_exp_f32_e32 v23, v23
	v_add_f32_e32 v2, 1.0, v2
	v_add_f32_e32 v8, 1.0, v8
	v_add_f32_e32 v9, 1.0, v9
	v_add_f32_e32 v29, 1.0, v23
	v_rcp_f32_e32 v23, v2
	v_rcp_f32_e32 v25, v8
	v_rcp_f32_e32 v27, v9
	v_rcp_f32_e32 v29, v29
	v_pk_mul_f32 v[8:9], v[22:23], v[10:11]
	v_pk_mul_f32 v[10:11], v[24:25], v[12:13]
	v_pk_mul_f32 v[12:13], v[26:27], v[14:15]
	v_pk_mul_f32 v[14:15], v[28:29], v[16:17]
	v_mul_f32_e32 v2, v8, v9
	v_mul_f32_e32 v8, v10, v11
	v_mul_f32_e32 v9, v12, v13
	v_mul_f32_e32 v10, v14, v15
	v_cvt_pk_bf16_f32 v8, v2, v8
	v_cvt_pk_bf16_f32 v9, v9, v10
	global_store_dwordx2 v[0:1], v[8:9], off offset:1792
	v_mov_b64_e32 v[8:9], v[208:209]
	v_lshlrev_b32_e32 v10, 16, v75
	v_and_b32_e32 v12, 0xffff0000, v75
	v_lshlrev_b32_e32 v14, 16, v74
	v_and_b32_e32 v16, 0xffff0000, v74
	v_or_b32_e32 v18, 0x340, v32
	v_mov_b32_e32 v19, v33
	v_lshl_add_u64 v[18:19], v[4:5], 0, v[18:19]
	v_lshlrev_b32_e32 v11, 16, v8
	v_and_b32_e32 v13, 0xffff0000, v8
	v_lshlrev_b32_e32 v15, 16, v9
	v_and_b32_e32 v17, 0xffff0000, v9
	v_mul_f32_e32 v2, 0xbfb8aa3b, v11
	v_mul_f32_e32 v8, 0xbfb8aa3b, v13
	v_mul_f32_e32 v9, 0xbfb8aa3b, v15
	v_mul_f32_e32 v23, 0xbfb8aa3b, v17
	v_exp_f32_e32 v2, v2
	v_exp_f32_e32 v8, v8
	v_exp_f32_e32 v9, v9
	v_exp_f32_e32 v23, v23
	v_add_f32_e32 v2, 1.0, v2
	v_add_f32_e32 v8, 1.0, v8
	v_add_f32_e32 v9, 1.0, v9
	v_add_f32_e32 v29, 1.0, v23
	v_rcp_f32_e32 v23, v2
	v_rcp_f32_e32 v25, v8
	v_rcp_f32_e32 v27, v9
	v_rcp_f32_e32 v29, v29
	v_pk_mul_f32 v[8:9], v[22:23], v[10:11]
	v_pk_mul_f32 v[10:11], v[24:25], v[12:13]
	v_pk_mul_f32 v[12:13], v[26:27], v[14:15]
	v_pk_mul_f32 v[14:15], v[28:29], v[16:17]
	v_mul_f32_e32 v2, v8, v9
	v_mul_f32_e32 v8, v10, v11
	v_mul_f32_e32 v9, v12, v13
	v_mul_f32_e32 v10, v14, v15
	v_cvt_pk_bf16_f32 v8, v2, v8
	v_cvt_pk_bf16_f32 v9, v9, v10
	global_store_dwordx2 v[0:1], v[8:9], off offset:1824
	v_mov_b64_e32 v[8:9], v[210:211]
	v_lshlrev_b32_e32 v10, 16, v73
	v_and_b32_e32 v12, 0xffff0000, v73
	v_lshlrev_b32_e32 v14, 16, v72
	v_and_b32_e32 v16, 0xffff0000, v72
	v_or_b32_e32 v18, 0x360, v32
	v_mov_b32_e32 v19, v33
	v_lshl_add_u64 v[18:19], v[4:5], 0, v[18:19]
	v_lshlrev_b32_e32 v11, 16, v8
	v_and_b32_e32 v13, 0xffff0000, v8
	v_lshlrev_b32_e32 v15, 16, v9
	v_and_b32_e32 v17, 0xffff0000, v9
	v_mul_f32_e32 v2, 0xbfb8aa3b, v11
	v_mul_f32_e32 v8, 0xbfb8aa3b, v13
	v_mul_f32_e32 v9, 0xbfb8aa3b, v15
	v_mul_f32_e32 v23, 0xbfb8aa3b, v17
	v_exp_f32_e32 v2, v2
	v_exp_f32_e32 v8, v8
	v_exp_f32_e32 v9, v9
	v_exp_f32_e32 v23, v23
	v_add_f32_e32 v2, 1.0, v2
	v_add_f32_e32 v8, 1.0, v8
	v_add_f32_e32 v9, 1.0, v9
	v_add_f32_e32 v29, 1.0, v23
	v_rcp_f32_e32 v23, v2
	v_rcp_f32_e32 v25, v8
	v_rcp_f32_e32 v27, v9
	v_rcp_f32_e32 v29, v29
	v_pk_mul_f32 v[8:9], v[22:23], v[10:11]
	v_pk_mul_f32 v[10:11], v[24:25], v[12:13]
	v_pk_mul_f32 v[12:13], v[26:27], v[14:15]
	v_pk_mul_f32 v[14:15], v[28:29], v[16:17]
	v_mul_f32_e32 v2, v8, v9
	v_mul_f32_e32 v8, v10, v11
	v_mul_f32_e32 v9, v12, v13
	v_mul_f32_e32 v10, v14, v15
	v_cvt_pk_bf16_f32 v8, v2, v8
	v_cvt_pk_bf16_f32 v9, v9, v10
	global_store_dwordx2 v[0:1], v[8:9], off offset:1856
	v_mov_b64_e32 v[8:9], v[212:213]
	v_lshlrev_b32_e32 v10, 16, v71
	v_and_b32_e32 v12, 0xffff0000, v71
	v_lshlrev_b32_e32 v14, 16, v69
	v_and_b32_e32 v16, 0xffff0000, v69
	v_or_b32_e32 v18, 0x380, v32
	v_mov_b32_e32 v19, v33
	v_lshl_add_u64 v[18:19], v[4:5], 0, v[18:19]
	v_lshlrev_b32_e32 v11, 16, v8
	v_and_b32_e32 v13, 0xffff0000, v8
	v_lshlrev_b32_e32 v15, 16, v9
	v_and_b32_e32 v17, 0xffff0000, v9
	v_mul_f32_e32 v2, 0xbfb8aa3b, v11
	v_mul_f32_e32 v8, 0xbfb8aa3b, v13
	v_mul_f32_e32 v9, 0xbfb8aa3b, v15
	v_mul_f32_e32 v23, 0xbfb8aa3b, v17
	v_exp_f32_e32 v2, v2
	v_exp_f32_e32 v8, v8
	v_exp_f32_e32 v9, v9
	v_exp_f32_e32 v23, v23
	v_add_f32_e32 v2, 1.0, v2
	v_add_f32_e32 v8, 1.0, v8
	v_add_f32_e32 v9, 1.0, v9
	v_add_f32_e32 v29, 1.0, v23
	v_rcp_f32_e32 v23, v2
	v_rcp_f32_e32 v25, v8
	v_rcp_f32_e32 v27, v9
	v_rcp_f32_e32 v29, v29
	v_pk_mul_f32 v[8:9], v[22:23], v[10:11]
	v_pk_mul_f32 v[10:11], v[24:25], v[12:13]
	v_pk_mul_f32 v[12:13], v[26:27], v[14:15]
	v_pk_mul_f32 v[14:15], v[28:29], v[16:17]
	v_mul_f32_e32 v2, v8, v9
	v_mul_f32_e32 v8, v10, v11
	v_mul_f32_e32 v9, v12, v13
	v_mul_f32_e32 v10, v14, v15
	v_cvt_pk_bf16_f32 v8, v2, v8
	v_cvt_pk_bf16_f32 v9, v9, v10
	global_store_dwordx2 v[0:1], v[8:9], off offset:1888
	v_mov_b64_e32 v[8:9], v[214:215]
	v_lshlrev_b32_e32 v10, 16, v70
	v_and_b32_e32 v12, 0xffff0000, v70
	v_lshlrev_b32_e32 v14, 16, v68
	v_and_b32_e32 v16, 0xffff0000, v68
	v_or_b32_e32 v18, 0x3a0, v32
	v_mov_b32_e32 v19, v33
	v_lshl_add_u64 v[18:19], v[4:5], 0, v[18:19]
	v_lshlrev_b32_e32 v11, 16, v8
	v_and_b32_e32 v13, 0xffff0000, v8
	v_lshlrev_b32_e32 v15, 16, v9
	v_and_b32_e32 v17, 0xffff0000, v9
	v_mul_f32_e32 v2, 0xbfb8aa3b, v11
	v_mul_f32_e32 v8, 0xbfb8aa3b, v13
	v_mul_f32_e32 v9, 0xbfb8aa3b, v15
	v_mul_f32_e32 v23, 0xbfb8aa3b, v17
	v_exp_f32_e32 v2, v2
	v_exp_f32_e32 v8, v8
	v_exp_f32_e32 v9, v9
	v_exp_f32_e32 v23, v23
	v_add_f32_e32 v2, 1.0, v2
	v_add_f32_e32 v8, 1.0, v8
	v_add_f32_e32 v9, 1.0, v9
	v_add_f32_e32 v29, 1.0, v23
	v_rcp_f32_e32 v23, v2
	v_rcp_f32_e32 v25, v8
	v_rcp_f32_e32 v27, v9
	v_rcp_f32_e32 v29, v29
	v_pk_mul_f32 v[8:9], v[22:23], v[10:11]
	v_pk_mul_f32 v[10:11], v[24:25], v[12:13]
	v_pk_mul_f32 v[12:13], v[26:27], v[14:15]
	v_pk_mul_f32 v[14:15], v[28:29], v[16:17]
	v_mul_f32_e32 v2, v8, v9
	v_mul_f32_e32 v8, v10, v11
	v_mul_f32_e32 v9, v12, v13
	v_mul_f32_e32 v10, v14, v15
	v_cvt_pk_bf16_f32 v8, v2, v8
	v_cvt_pk_bf16_f32 v9, v9, v10
	global_store_dwordx2 v[0:1], v[8:9], off offset:1920
	v_mov_b64_e32 v[8:9], v[216:217]
	v_lshlrev_b32_e32 v10, 16, v66
	v_and_b32_e32 v12, 0xffff0000, v66
	v_lshlrev_b32_e32 v14, 16, v64
	v_and_b32_e32 v16, 0xffff0000, v64
	v_or_b32_e32 v18, 0x3c0, v32
	v_mov_b32_e32 v19, v33
	v_lshl_add_u64 v[18:19], v[4:5], 0, v[18:19]
	v_or_b32_e32 v32, 0x3e0, v32
	v_lshl_add_u64 v[4:5], v[4:5], 0, v[32:33]
	v_lshlrev_b32_e32 v11, 16, v8
	v_and_b32_e32 v13, 0xffff0000, v8
	v_lshlrev_b32_e32 v15, 16, v9
	v_and_b32_e32 v17, 0xffff0000, v9
	v_mul_f32_e32 v2, 0xbfb8aa3b, v11
	v_mul_f32_e32 v8, 0xbfb8aa3b, v13
	v_mul_f32_e32 v9, 0xbfb8aa3b, v15
	v_mul_f32_e32 v23, 0xbfb8aa3b, v17
	v_exp_f32_e32 v2, v2
	v_exp_f32_e32 v8, v8
	v_exp_f32_e32 v9, v9
	v_exp_f32_e32 v23, v23
	v_add_f32_e32 v2, 1.0, v2
	v_add_f32_e32 v8, 1.0, v8
	v_add_f32_e32 v9, 1.0, v9
	v_add_f32_e32 v29, 1.0, v23
	v_rcp_f32_e32 v23, v2
	v_rcp_f32_e32 v25, v8
	v_rcp_f32_e32 v27, v9
	v_rcp_f32_e32 v29, v29
	v_pk_mul_f32 v[8:9], v[22:23], v[10:11]
	v_pk_mul_f32 v[10:11], v[24:25], v[12:13]
	v_pk_mul_f32 v[12:13], v[26:27], v[14:15]
	v_pk_mul_f32 v[14:15], v[28:29], v[16:17]
	v_mul_f32_e32 v2, v8, v9
	v_mul_f32_e32 v8, v10, v11
	v_mul_f32_e32 v9, v12, v13
	v_mul_f32_e32 v10, v14, v15
	v_cvt_pk_bf16_f32 v8, v2, v8
	v_cvt_pk_bf16_f32 v9, v9, v10
	global_store_dwordx2 v[0:1], v[8:9], off offset:1952
	v_mov_b64_e32 v[8:9], v[218:219]
	v_lshlrev_b32_e32 v10, 16, v21
	v_and_b32_e32 v12, 0xffff0000, v21
	v_lshlrev_b32_e32 v14, 16, v20
	v_and_b32_e32 v16, 0xffff0000, v20
	v_mov_b32_e32 v18, v3
	v_mov_b32_e32 v20, v3
	v_lshlrev_b32_e32 v11, 16, v8
	v_and_b32_e32 v13, 0xffff0000, v8
	v_lshlrev_b32_e32 v15, 16, v9
	v_and_b32_e32 v17, 0xffff0000, v9
	v_mul_f32_e32 v2, 0xbfb8aa3b, v11
	v_mul_f32_e32 v8, 0xbfb8aa3b, v13
	v_mul_f32_e32 v9, 0xbfb8aa3b, v15
	v_mul_f32_e32 v19, 0xbfb8aa3b, v17
	v_exp_f32_e32 v2, v2
	v_exp_f32_e32 v8, v8
	v_exp_f32_e32 v9, v9
	v_exp_f32_e32 v19, v19
	v_add_f32_e32 v2, 1.0, v2
	v_add_f32_e32 v8, 1.0, v8
	v_add_f32_e32 v9, 1.0, v9
	v_add_f32_e32 v25, 1.0, v19
	v_rcp_f32_e32 v19, v2
	v_rcp_f32_e32 v21, v8
	v_rcp_f32_e32 v23, v9
	v_rcp_f32_e32 v25, v25
	v_pk_mul_f32 v[8:9], v[18:19], v[10:11]
	v_pk_mul_f32 v[10:11], v[20:21], v[12:13]
	v_pk_mul_f32 v[12:13], v[22:23], v[14:15]
	v_pk_mul_f32 v[14:15], v[24:25], v[16:17]
	v_mul_f32_e32 v2, v8, v9
	v_mul_f32_e32 v8, v10, v11
	v_mul_f32_e32 v9, v12, v13
	v_mul_f32_e32 v10, v14, v15
	v_cvt_pk_bf16_f32 v8, v2, v8
	v_cvt_pk_bf16_f32 v9, v9, v10
	global_store_dwordx2 v[0:1], v[8:9], off offset:1984
	v_mov_b64_e32 v[4:5], v[220:221]
	v_mov_b32_e32 v12, v3
	v_mov_b32_e32 v14, v3
	v_mov_b32_e32 v16, v3
	v_lshlrev_b32_e32 v2, 16, v7
	v_and_b32_e32 v8, 0xffff0000, v7
	v_lshlrev_b32_e32 v10, 16, v6
	v_and_b32_e32 v6, 0xffff0000, v6
	v_lshlrev_b32_e32 v3, 16, v4
	v_and_b32_e32 v9, 0xffff0000, v4
	v_lshlrev_b32_e32 v11, 16, v5
	v_and_b32_e32 v7, 0xffff0000, v5
	v_mul_f32_e32 v4, 0xbfb8aa3b, v3
	v_mul_f32_e32 v5, 0xbfb8aa3b, v9
	v_mul_f32_e32 v13, 0xbfb8aa3b, v11
	v_mul_f32_e32 v15, 0xbfb8aa3b, v7
	v_exp_f32_e32 v4, v4
	v_exp_f32_e32 v5, v5
	v_exp_f32_e32 v13, v13
	v_exp_f32_e32 v15, v15
	v_add_f32_e32 v4, 1.0, v4
	v_add_f32_e32 v5, 1.0, v5
	v_add_f32_e32 v17, 1.0, v13
	v_add_f32_e32 v19, 1.0, v15
	v_rcp_f32_e32 v13, v4
	v_rcp_f32_e32 v15, v5
	v_rcp_f32_e32 v17, v17
	v_rcp_f32_e32 v19, v19
	v_pk_mul_f32 v[2:3], v[12:13], v[2:3]
	v_pk_mul_f32 v[4:5], v[14:15], v[8:9]
	v_pk_mul_f32 v[8:9], v[16:17], v[10:11]
	v_pk_mul_f32 v[6:7], v[18:19], v[6:7]
	v_mul_f32_e32 v2, v2, v3
	v_mul_f32_e32 v3, v4, v5
	v_mul_f32_e32 v4, v8, v9
	v_mul_f32_e32 v5, v6, v7
	v_cvt_pk_bf16_f32 v2, v2, v3
	v_cvt_pk_bf16_f32 v3, v4, v5
	global_store_dwordx2 v[0:1], v[2:3], off offset:2016
	s_cbranch_scc1 .LBB0_900
.LBB0_898:
	v_readlane_b32 s12, v254, 3
	v_mbcnt_lo_u32_b32 v0, -1, 0
	v_mbcnt_hi_u32_b32 v0, -1, v0
	s_nop 1
	v_or_b32_e32 v4, s12, v0
	v_bfe_u32 v230, v4, 2, 7
	v_mov_b32_e32 v231, 0
	v_lshl_add_u64 v[226:227], s[4:5], 0, v[230:231]
	v_mad_u64_u32 v[228:229], s[12:13], v226, s9, v[34:35]
	v_mov_b32_e32 v226, v229
	v_mad_u64_u32 v[226:227], s[12:13], v227, s9, v[226:227]
	v_mov_b32_e32 v229, v226
	v_lshlrev_b32_e32 v226, 3, v4
	v_and_b32_e32 v232, 24, v226
	v_lshlrev_b32_e32 v226, 1, v232
	v_mov_b32_e32 v227, v231
	v_lshl_add_u64 v[234:235], v[228:229], 0, v[226:227]
	global_load_dwordx4 v[242:245], v[234:235], off offset:2048
	global_load_dwordx4 v[246:249], v[234:235], off offset:2112
	global_load_dwordx4 v[250:253], v[234:235], off offset:2176
	global_load_dwordx4 v[238:241], v[234:235], off offset:2240
	s_nop 0
	v_cmp_gt_i32_e32 vcc, s2, v4
	s_barrier
	s_and_saveexec_b64 s[12:13], vcc
	s_cbranch_execz .LBB0_897
	v_ashrrev_i32_e32 v5, 31, v4
	v_lshl_add_u64 v[0:1], s[4:5], 0, v[4:5]
	v_lshlrev_b64 v[0:1], 6, v[0:1]
	v_lshl_add_u64 v[14:15], s[18:19], 0, v[0:1]
	global_load_dwordx4 v[0:3], v[14:15], off
	global_load_dwordx4 v[6:9], v[14:15], off offset:16
	global_load_dwordx4 v[10:13], v[14:15], off offset:32
	s_nop 0
	global_load_dwordx4 v[14:17], v[14:15], off offset:48
	s_waitcnt vmcnt(3)
	v_pk_add_f32 v[0:1], v[0:1], 0 op_sel_hi:[1,0]
	s_nop 0
	v_pk_add_f32 v[0:1], v[0:1], v[2:3]
	s_waitcnt vmcnt(2)
	v_pk_add_f32 v[0:1], v[0:1], v[6:7]
	s_nop 0
	v_pk_add_f32 v[0:1], v[0:1], v[8:9]
	s_waitcnt vmcnt(1)
	v_pk_add_f32 v[0:1], v[0:1], v[10:11]
	s_nop 0
	v_pk_add_f32 v[0:1], v[0:1], v[12:13]
	s_waitcnt vmcnt(0)
	v_pk_add_f32 v[0:1], v[0:1], v[14:15]
	s_nop 0
	v_pk_add_f32 v[0:1], v[0:1], v[16:17]
	s_nop 0
	v_pk_mul_f32 v[0:1], v[0:1], s[8:9] op_sel_hi:[1,0]
	s_nop 0
	v_fma_f32 v1, -v0, v0, v1
	v_max_f32_e32 v1, 0, v1
	v_add_f32_e32 v1, 0x358637bd, v1
	v_mul_f32_e32 v2, 0x4b800000, v1
	v_cmp_gt_f32_e32 vcc, s3, v1
	s_nop 1
	v_cndmask_b32_e32 v1, v1, v2, vcc
	v_rsq_f32_e32 v1, v1
	v_lshl_add_u32 v2, v4, 3, 0
	v_add_u32_e32 v2, 0x11000, v2
	v_mul_f32_e32 v3, 0x45800000, v1
	v_cndmask_b32_e32 v1, v1, v3, vcc
	ds_write_b64 v2, v[0:1]
	s_branch .LBB0_897
